# up/down projection GEMM mainloops: LDS-DMA staging with 3-buffer ring (2 stages in flight), double fragment sets
# speedup vs baseline: 1.0188x; 1.0056x over previous
.LBB0_1066:
	v_add_co_u32_e32 v182, vcc, 0x800, v152
	s_nop 1
	v_addc_co_u32_e32 v183, vcc, 0, v153, vcc
	v_add_co_u32_e32 v204, vcc, s34, v182
	s_nop 1
	v_addc_co_u32_e32 v205, vcc, 0, v183, vcc
	v_add_co_u32_e32 v206, vcc, s35, v182
	s_nop 1
	v_addc_co_u32_e32 v207, vcc, 0, v183, vcc
	v_add_co_u32_e32 v208, vcc, 0x14fe000, v154
	s_nop 1
	v_addc_co_u32_e32 v209, vcc, 0, v155, vcc
	v_add_co_u32_e32 v210, vcc, 0x1520000, v154
	s_nop 1
	v_addc_co_u32_e32 v211, vcc, 0, v155, vcc
	v_add_co_u32_e32 v212, vcc, 0x1542000, v154
	s_nop 1
	v_addc_co_u32_e32 v213, vcc, 0, v155, vcc
	v_add_co_u32_e32 v214, vcc, 0x1564000, v154
	s_nop 1
	v_addc_co_u32_e32 v215, vcc, 0, v155, vcc
	v_and_b32_e32 v216, 3, v156
	v_bfe_u32 v217, v156, 4, 2
	v_xor_b32_e32 v218, v216, v217
	v_sub_u32_e32 v218, v218, v216
	v_lshlrev_b32_e32 v218, 4, v218
	v_ashrrev_i32_e32 v219, 31, v218
	v_lshl_add_u64 v[204:205], v[218:219], 0, v[204:205]
	v_lshl_add_u64 v[206:207], v[218:219], 0, v[206:207]
	v_lshl_add_u64 v[208:209], v[218:219], 0, v[208:209]
	v_lshl_add_u64 v[210:211], v[218:219], 0, v[210:211]
	v_lshl_add_u64 v[212:213], v[218:219], 0, v[212:213]
	v_lshl_add_u64 v[214:215], v[218:219], 0, v[214:215]
	v_mov_b32_e32 v216, 64
	v_mov_b32_e32 v217, 0
	v_lshl_add_u64 v[204:205], v[216:217], 1, v[204:205]
	v_lshl_add_u64 v[206:207], v[216:217], 1, v[206:207]
	v_lshl_add_u64 v[208:209], v[216:217], 1, v[208:209]
	v_lshl_add_u64 v[210:211], v[216:217], 1, v[210:211]
	v_lshl_add_u64 v[212:213], v[216:217], 1, v[212:213]
	v_lshl_add_u64 v[214:215], v[216:217], 1, v[214:215]
	v_lshrrev_b32_e32 v246, 6, v156
	v_lshlrev_b32_e32 v246, 10, v246
	s_nop 0
	v_readfirstlane_b32 s14, v246
	ds_read_b128 v[162:165], v159 offset:8192
	ds_read_b128 v[178:181], v158
	ds_read_b128 v[166:169], v159 offset:10240
	ds_read_b128 v[200:203], v158 offset:2048
	ds_read_b128 v[170:173], v159 offset:12288
	ds_read_b128 v[174:177], v159 offset:14336
	s_waitcnt lgkmcnt(4)
	v_mfma_f32_32x32x16_bf16 v[112:127], v[162:165], v[178:181], v[112:127]
	s_waitcnt lgkmcnt(3)
	v_mfma_f32_32x32x16_bf16 v[96:111], v[166:169], v[178:181], v[96:111]
	s_waitcnt lgkmcnt(1)
	v_mfma_f32_32x32x16_bf16 v[80:95], v[170:173], v[178:181], v[80:95]
	s_waitcnt lgkmcnt(0)
	v_mfma_f32_32x32x16_bf16 v[64:79], v[174:177], v[178:181], v[64:79]
	v_mfma_f32_32x32x16_bf16 v[48:63], v[162:165], v[200:203], v[48:63]
	v_mfma_f32_32x32x16_bf16 v[32:47], v[166:169], v[200:203], v[32:47]
	v_mfma_f32_32x32x16_bf16 v[16:31], v[170:173], v[200:203], v[16:31]
	v_mfma_f32_32x32x16_bf16 v[0:15], v[174:177], v[200:203], v[0:15]
	ds_read_b128 v[162:165], v157 offset:8192
	ds_read_b128 v[178:181], v160
	ds_read_b128 v[166:169], v157 offset:10240
	ds_read_b128 v[200:203], v160 offset:2048
	ds_read_b128 v[170:173], v157 offset:12288
	ds_read_b128 v[174:177], v157 offset:14336
	s_waitcnt vmcnt(5)
	ds_write_b128 v161, v[144:147] offset:24576
	s_waitcnt vmcnt(3)
	ds_write_b128 v161, v[148:151] offset:28672
	ds_write_b128 v161, v[140:143] offset:32768
	s_waitcnt vmcnt(2)
	ds_write_b128 v161, v[132:135] offset:36864
	s_waitcnt vmcnt(1)
	ds_write_b128 v161, v[128:131] offset:40960
	s_waitcnt vmcnt(0)
	ds_write_b128 v161, v[136:139] offset:45056
	s_add_u32 m0, s14, 0xc000
	s_nop 0
	global_load_lds_dwordx4 v[204:205], off
	v_lshl_add_u64 v[204:205], v[216:217], 0, v[204:205]
	s_add_u32 m0, s14, 0xd000
	s_nop 0
	global_load_lds_dwordx4 v[206:207], off
	v_lshl_add_u64 v[206:207], v[216:217], 0, v[206:207]
	s_add_u32 m0, s14, 0xe000
	s_nop 0
	global_load_lds_dwordx4 v[208:209], off
	v_lshl_add_u64 v[208:209], v[216:217], 0, v[208:209]
	s_add_u32 m0, s14, 0xf000
	s_nop 0
	global_load_lds_dwordx4 v[210:211], off
	v_lshl_add_u64 v[210:211], v[216:217], 0, v[210:211]
	s_add_u32 m0, s14, 0x10000
	s_nop 0
	global_load_lds_dwordx4 v[212:213], off
	v_lshl_add_u64 v[212:213], v[216:217], 0, v[212:213]
	s_add_u32 m0, s14, 0x11000
	s_nop 0
	global_load_lds_dwordx4 v[214:215], off
	v_lshl_add_u64 v[214:215], v[216:217], 0, v[214:215]
	s_waitcnt lgkmcnt(10)
	v_mfma_f32_32x32x16_bf16 v[112:127], v[162:165], v[178:181], v[112:127]
	s_waitcnt lgkmcnt(9)
	v_mfma_f32_32x32x16_bf16 v[96:111], v[166:169], v[178:181], v[96:111]
	s_waitcnt lgkmcnt(7)
	v_mfma_f32_32x32x16_bf16 v[80:95], v[170:173], v[178:181], v[80:95]
	s_waitcnt lgkmcnt(6)
	v_mfma_f32_32x32x16_bf16 v[64:79], v[174:177], v[178:181], v[64:79]
	v_mfma_f32_32x32x16_bf16 v[48:63], v[162:165], v[200:203], v[48:63]
	v_mfma_f32_32x32x16_bf16 v[32:47], v[166:169], v[200:203], v[32:47]
	v_mfma_f32_32x32x16_bf16 v[16:31], v[170:173], v[200:203], v[16:31]
	v_mfma_f32_32x32x16_bf16 v[0:15], v[174:177], v[200:203], v[0:15]
	s_waitcnt lgkmcnt(0)
	s_barrier
	ds_read_b128 v[162:165], v159 offset:32768
	ds_read_b128 v[178:181], v158 offset:24576
	ds_read_b128 v[166:169], v159 offset:34816
	ds_read_b128 v[200:203], v158 offset:26624
	ds_read_b128 v[170:173], v159 offset:36864
	ds_read_b128 v[174:177], v159 offset:38912
	ds_read_b128 v[128:131], v157 offset:32768
	ds_read_b128 v[144:147], v160 offset:24576
	ds_read_b128 v[132:135], v157 offset:34816
	ds_read_b128 v[148:151], v160 offset:26624
	ds_read_b128 v[136:139], v157 offset:36864
	ds_read_b128 v[140:143], v157 offset:38912
	s_waitcnt lgkmcnt(10)
	v_mfma_f32_32x32x16_bf16 v[112:127], v[162:165], v[178:181], v[112:127]
	s_mov_b32 m0, s14
	s_nop 0
	global_load_lds_dwordx4 v[204:205], off
	v_lshl_add_u64 v[204:205], v[216:217], 0, v[204:205]
	s_waitcnt lgkmcnt(9)
	v_mfma_f32_32x32x16_bf16 v[96:111], v[166:169], v[178:181], v[96:111]
	s_add_u32 m0, s14, 0x1000
	s_nop 0
	global_load_lds_dwordx4 v[206:207], off
	v_lshl_add_u64 v[206:207], v[216:217], 0, v[206:207]
	s_waitcnt lgkmcnt(7)
	v_mfma_f32_32x32x16_bf16 v[80:95], v[170:173], v[178:181], v[80:95]
	s_add_u32 m0, s14, 0x2000
	s_nop 0
	global_load_lds_dwordx4 v[208:209], off
	v_lshl_add_u64 v[208:209], v[216:217], 0, v[208:209]
	s_waitcnt lgkmcnt(6)
	v_mfma_f32_32x32x16_bf16 v[64:79], v[174:177], v[178:181], v[64:79]
	s_add_u32 m0, s14, 0x3000
	s_nop 0
	global_load_lds_dwordx4 v[210:211], off
	v_lshl_add_u64 v[210:211], v[216:217], 0, v[210:211]
	v_mfma_f32_32x32x16_bf16 v[48:63], v[162:165], v[200:203], v[48:63]
	s_add_u32 m0, s14, 0x4000
	s_nop 0
	global_load_lds_dwordx4 v[212:213], off
	v_lshl_add_u64 v[212:213], v[216:217], 0, v[212:213]
	v_mfma_f32_32x32x16_bf16 v[32:47], v[166:169], v[200:203], v[32:47]
	s_add_u32 m0, s14, 0x5000
	s_nop 0
	global_load_lds_dwordx4 v[214:215], off
	v_lshl_add_u64 v[214:215], v[216:217], 0, v[214:215]
	v_mfma_f32_32x32x16_bf16 v[16:31], v[170:173], v[200:203], v[16:31]
	v_mfma_f32_32x32x16_bf16 v[0:15], v[174:177], v[200:203], v[0:15]
	s_waitcnt lgkmcnt(4)
	v_mfma_f32_32x32x16_bf16 v[112:127], v[128:131], v[144:147], v[112:127]
	s_waitcnt lgkmcnt(3)
	v_mfma_f32_32x32x16_bf16 v[96:111], v[132:135], v[144:147], v[96:111]
	s_waitcnt lgkmcnt(1)
	v_mfma_f32_32x32x16_bf16 v[80:95], v[136:139], v[144:147], v[80:95]
	s_waitcnt lgkmcnt(0)
	v_mfma_f32_32x32x16_bf16 v[64:79], v[140:143], v[144:147], v[64:79]
	v_mfma_f32_32x32x16_bf16 v[48:63], v[128:131], v[148:151], v[48:63]
	v_mfma_f32_32x32x16_bf16 v[32:47], v[132:135], v[148:151], v[32:47]
	v_mfma_f32_32x32x16_bf16 v[16:31], v[136:139], v[148:151], v[16:31]
	v_mfma_f32_32x32x16_bf16 v[0:15], v[140:143], v[148:151], v[0:15]
	s_waitcnt vmcnt(6)
	s_waitcnt lgkmcnt(0)
	s_barrier
	ds_read_b128 v[162:165], v159 offset:57344
	ds_read_b128 v[178:181], v158 offset:49152
	ds_read_b128 v[166:169], v159 offset:59392
	ds_read_b128 v[200:203], v158 offset:51200
	ds_read_b128 v[170:173], v159 offset:61440
	ds_read_b128 v[174:177], v159 offset:63488
	ds_read_b128 v[128:131], v157 offset:57344
	ds_read_b128 v[144:147], v160 offset:49152
	ds_read_b128 v[132:135], v157 offset:59392
	ds_read_b128 v[148:151], v160 offset:51200
	ds_read_b128 v[136:139], v157 offset:61440
	ds_read_b128 v[140:143], v157 offset:63488
	s_waitcnt lgkmcnt(10)
	v_mfma_f32_32x32x16_bf16 v[112:127], v[162:165], v[178:181], v[112:127]
	s_add_u32 m0, s14, 0x6000
	s_nop 0
	global_load_lds_dwordx4 v[204:205], off
	v_lshl_add_u64 v[204:205], v[216:217], 0, v[204:205]
	s_waitcnt lgkmcnt(9)
	v_mfma_f32_32x32x16_bf16 v[96:111], v[166:169], v[178:181], v[96:111]
	s_add_u32 m0, s14, 0x7000
	s_nop 0
	global_load_lds_dwordx4 v[206:207], off
	v_lshl_add_u64 v[206:207], v[216:217], 0, v[206:207]
	s_waitcnt lgkmcnt(7)
	v_mfma_f32_32x32x16_bf16 v[80:95], v[170:173], v[178:181], v[80:95]
	s_add_u32 m0, s14, 0x8000
	s_nop 0
	global_load_lds_dwordx4 v[208:209], off
	v_lshl_add_u64 v[208:209], v[216:217], 0, v[208:209]
	s_waitcnt lgkmcnt(6)
	v_mfma_f32_32x32x16_bf16 v[64:79], v[174:177], v[178:181], v[64:79]
	s_add_u32 m0, s14, 0x9000
	s_nop 0
	global_load_lds_dwordx4 v[210:211], off
	v_lshl_add_u64 v[210:211], v[216:217], 0, v[210:211]
	v_mfma_f32_32x32x16_bf16 v[48:63], v[162:165], v[200:203], v[48:63]
	s_add_u32 m0, s14, 0xa000
	s_nop 0
	global_load_lds_dwordx4 v[212:213], off
	v_lshl_add_u64 v[212:213], v[216:217], 0, v[212:213]
	v_mfma_f32_32x32x16_bf16 v[32:47], v[166:169], v[200:203], v[32:47]
	s_add_u32 m0, s14, 0xb000
	s_nop 0
	global_load_lds_dwordx4 v[214:215], off
	v_lshl_add_u64 v[214:215], v[216:217], 0, v[214:215]
	v_mfma_f32_32x32x16_bf16 v[16:31], v[170:173], v[200:203], v[16:31]
	v_mfma_f32_32x32x16_bf16 v[0:15], v[174:177], v[200:203], v[0:15]
	s_waitcnt lgkmcnt(4)
	v_mfma_f32_32x32x16_bf16 v[112:127], v[128:131], v[144:147], v[112:127]
	s_waitcnt lgkmcnt(3)
	v_mfma_f32_32x32x16_bf16 v[96:111], v[132:135], v[144:147], v[96:111]
	s_waitcnt lgkmcnt(1)
	v_mfma_f32_32x32x16_bf16 v[80:95], v[136:139], v[144:147], v[80:95]
	s_waitcnt lgkmcnt(0)
	v_mfma_f32_32x32x16_bf16 v[64:79], v[140:143], v[144:147], v[64:79]
	v_mfma_f32_32x32x16_bf16 v[48:63], v[128:131], v[148:151], v[48:63]
	v_mfma_f32_32x32x16_bf16 v[32:47], v[132:135], v[148:151], v[32:47]
	v_mfma_f32_32x32x16_bf16 v[16:31], v[136:139], v[148:151], v[16:31]
	v_mfma_f32_32x32x16_bf16 v[0:15], v[140:143], v[148:151], v[0:15]
	s_waitcnt vmcnt(6)
	s_waitcnt lgkmcnt(0)
	s_barrier
	ds_read_b128 v[162:165], v159 offset:8192
	ds_read_b128 v[178:181], v158
	ds_read_b128 v[166:169], v159 offset:10240
	ds_read_b128 v[200:203], v158 offset:2048
	ds_read_b128 v[170:173], v159 offset:12288
	ds_read_b128 v[174:177], v159 offset:14336
	ds_read_b128 v[128:131], v157 offset:8192
	ds_read_b128 v[144:147], v160
	ds_read_b128 v[132:135], v157 offset:10240
	ds_read_b128 v[148:151], v160 offset:2048
	ds_read_b128 v[136:139], v157 offset:12288
	ds_read_b128 v[140:143], v157 offset:14336
	s_waitcnt lgkmcnt(10)
	v_mfma_f32_32x32x16_bf16 v[112:127], v[162:165], v[178:181], v[112:127]
	s_add_u32 m0, s14, 0xc000
	s_nop 0
	global_load_lds_dwordx4 v[204:205], off
	v_lshl_add_u64 v[204:205], v[216:217], 0, v[204:205]
	s_waitcnt lgkmcnt(9)
	v_mfma_f32_32x32x16_bf16 v[96:111], v[166:169], v[178:181], v[96:111]
	s_add_u32 m0, s14, 0xd000
	s_nop 0
	global_load_lds_dwordx4 v[206:207], off
	v_lshl_add_u64 v[206:207], v[216:217], 0, v[206:207]
	s_waitcnt lgkmcnt(7)
	v_mfma_f32_32x32x16_bf16 v[80:95], v[170:173], v[178:181], v[80:95]
	s_add_u32 m0, s14, 0xe000
	s_nop 0
	global_load_lds_dwordx4 v[208:209], off
	v_lshl_add_u64 v[208:209], v[216:217], 0, v[208:209]
	s_waitcnt lgkmcnt(6)
	v_mfma_f32_32x32x16_bf16 v[64:79], v[174:177], v[178:181], v[64:79]
	s_add_u32 m0, s14, 0xf000
	s_nop 0
	global_load_lds_dwordx4 v[210:211], off
	v_lshl_add_u64 v[210:211], v[216:217], 0, v[210:211]
	v_mfma_f32_32x32x16_bf16 v[48:63], v[162:165], v[200:203], v[48:63]
	s_add_u32 m0, s14, 0x10000
	s_nop 0
	global_load_lds_dwordx4 v[212:213], off
	v_lshl_add_u64 v[212:213], v[216:217], 0, v[212:213]
	v_mfma_f32_32x32x16_bf16 v[32:47], v[166:169], v[200:203], v[32:47]
	s_add_u32 m0, s14, 0x11000
	s_nop 0
	global_load_lds_dwordx4 v[214:215], off
	v_lshl_add_u64 v[214:215], v[216:217], 0, v[214:215]
	v_mfma_f32_32x32x16_bf16 v[16:31], v[170:173], v[200:203], v[16:31]
	v_mfma_f32_32x32x16_bf16 v[0:15], v[174:177], v[200:203], v[0:15]
	s_waitcnt lgkmcnt(4)
	v_mfma_f32_32x32x16_bf16 v[112:127], v[128:131], v[144:147], v[112:127]
	s_waitcnt lgkmcnt(3)
	v_mfma_f32_32x32x16_bf16 v[96:111], v[132:135], v[144:147], v[96:111]
	s_waitcnt lgkmcnt(1)
	v_mfma_f32_32x32x16_bf16 v[80:95], v[136:139], v[144:147], v[80:95]
	s_waitcnt lgkmcnt(0)
	v_mfma_f32_32x32x16_bf16 v[64:79], v[140:143], v[144:147], v[64:79]
	v_mfma_f32_32x32x16_bf16 v[48:63], v[128:131], v[148:151], v[48:63]
	v_mfma_f32_32x32x16_bf16 v[32:47], v[132:135], v[148:151], v[32:47]
	v_mfma_f32_32x32x16_bf16 v[16:31], v[136:139], v[148:151], v[16:31]
	v_mfma_f32_32x32x16_bf16 v[0:15], v[140:143], v[148:151], v[0:15]
	s_waitcnt vmcnt(6)
	s_waitcnt lgkmcnt(0)
	s_barrier
	ds_read_b128 v[162:165], v159 offset:32768
	ds_read_b128 v[178:181], v158 offset:24576
	ds_read_b128 v[166:169], v159 offset:34816
	ds_read_b128 v[200:203], v158 offset:26624
	ds_read_b128 v[170:173], v159 offset:36864
	ds_read_b128 v[174:177], v159 offset:38912
	ds_read_b128 v[128:131], v157 offset:32768
	ds_read_b128 v[144:147], v160 offset:24576
	ds_read_b128 v[132:135], v157 offset:34816
	ds_read_b128 v[148:151], v160 offset:26624
	ds_read_b128 v[136:139], v157 offset:36864
	ds_read_b128 v[140:143], v157 offset:38912
	s_waitcnt lgkmcnt(10)
	v_mfma_f32_32x32x16_bf16 v[112:127], v[162:165], v[178:181], v[112:127]
	s_mov_b32 m0, s14
	s_nop 0
	global_load_lds_dwordx4 v[204:205], off
	v_lshl_add_u64 v[204:205], v[216:217], 0, v[204:205]
	s_waitcnt lgkmcnt(9)
	v_mfma_f32_32x32x16_bf16 v[96:111], v[166:169], v[178:181], v[96:111]
	s_add_u32 m0, s14, 0x1000
	s_nop 0
	global_load_lds_dwordx4 v[206:207], off
	v_lshl_add_u64 v[206:207], v[216:217], 0, v[206:207]
	s_waitcnt lgkmcnt(7)
	v_mfma_f32_32x32x16_bf16 v[80:95], v[170:173], v[178:181], v[80:95]
	s_add_u32 m0, s14, 0x2000
	s_nop 0
	global_load_lds_dwordx4 v[208:209], off
	v_lshl_add_u64 v[208:209], v[216:217], 0, v[208:209]
	s_waitcnt lgkmcnt(6)
	v_mfma_f32_32x32x16_bf16 v[64:79], v[174:177], v[178:181], v[64:79]
	s_add_u32 m0, s14, 0x3000
	s_nop 0
	global_load_lds_dwordx4 v[210:211], off
	v_lshl_add_u64 v[210:211], v[216:217], 0, v[210:211]
	v_mfma_f32_32x32x16_bf16 v[48:63], v[162:165], v[200:203], v[48:63]
	s_add_u32 m0, s14, 0x4000
	s_nop 0
	global_load_lds_dwordx4 v[212:213], off
	v_lshl_add_u64 v[212:213], v[216:217], 0, v[212:213]
	v_mfma_f32_32x32x16_bf16 v[32:47], v[166:169], v[200:203], v[32:47]
	s_add_u32 m0, s14, 0x5000
	s_nop 0
	global_load_lds_dwordx4 v[214:215], off
	v_lshl_add_u64 v[214:215], v[216:217], 0, v[214:215]
	v_mfma_f32_32x32x16_bf16 v[16:31], v[170:173], v[200:203], v[16:31]
	v_mfma_f32_32x32x16_bf16 v[0:15], v[174:177], v[200:203], v[0:15]
	s_waitcnt lgkmcnt(4)
	v_mfma_f32_32x32x16_bf16 v[112:127], v[128:131], v[144:147], v[112:127]
	s_waitcnt lgkmcnt(3)
	v_mfma_f32_32x32x16_bf16 v[96:111], v[132:135], v[144:147], v[96:111]
	s_waitcnt lgkmcnt(1)
	v_mfma_f32_32x32x16_bf16 v[80:95], v[136:139], v[144:147], v[80:95]
	s_waitcnt lgkmcnt(0)
	v_mfma_f32_32x32x16_bf16 v[64:79], v[140:143], v[144:147], v[64:79]
	v_mfma_f32_32x32x16_bf16 v[48:63], v[128:131], v[148:151], v[48:63]
	v_mfma_f32_32x32x16_bf16 v[32:47], v[132:135], v[148:151], v[32:47]
	v_mfma_f32_32x32x16_bf16 v[16:31], v[136:139], v[148:151], v[16:31]
	v_mfma_f32_32x32x16_bf16 v[0:15], v[140:143], v[148:151], v[0:15]
	s_waitcnt vmcnt(6)
	s_waitcnt lgkmcnt(0)
	s_barrier
	ds_read_b128 v[162:165], v159 offset:57344
	ds_read_b128 v[178:181], v158 offset:49152
	ds_read_b128 v[166:169], v159 offset:59392
	ds_read_b128 v[200:203], v158 offset:51200
	ds_read_b128 v[170:173], v159 offset:61440
	ds_read_b128 v[174:177], v159 offset:63488
	ds_read_b128 v[128:131], v157 offset:57344
	ds_read_b128 v[144:147], v160 offset:49152
	ds_read_b128 v[132:135], v157 offset:59392
	ds_read_b128 v[148:151], v160 offset:51200
	ds_read_b128 v[136:139], v157 offset:61440
	ds_read_b128 v[140:143], v157 offset:63488
	s_waitcnt lgkmcnt(10)
	v_mfma_f32_32x32x16_bf16 v[112:127], v[162:165], v[178:181], v[112:127]
	s_add_u32 m0, s14, 0x6000
	s_nop 0
	global_load_lds_dwordx4 v[204:205], off
	v_lshl_add_u64 v[204:205], v[216:217], 0, v[204:205]
	s_waitcnt lgkmcnt(9)
	v_mfma_f32_32x32x16_bf16 v[96:111], v[166:169], v[178:181], v[96:111]
	s_add_u32 m0, s14, 0x7000
	s_nop 0
	global_load_lds_dwordx4 v[206:207], off
	v_lshl_add_u64 v[206:207], v[216:217], 0, v[206:207]
	s_waitcnt lgkmcnt(7)
	v_mfma_f32_32x32x16_bf16 v[80:95], v[170:173], v[178:181], v[80:95]
	s_add_u32 m0, s14, 0x8000
	s_nop 0
	global_load_lds_dwordx4 v[208:209], off
	v_lshl_add_u64 v[208:209], v[216:217], 0, v[208:209]
	s_waitcnt lgkmcnt(6)
	v_mfma_f32_32x32x16_bf16 v[64:79], v[174:177], v[178:181], v[64:79]
	s_add_u32 m0, s14, 0x9000
	s_nop 0
	global_load_lds_dwordx4 v[210:211], off
	v_lshl_add_u64 v[210:211], v[216:217], 0, v[210:211]
	v_mfma_f32_32x32x16_bf16 v[48:63], v[162:165], v[200:203], v[48:63]
	s_add_u32 m0, s14, 0xa000
	s_nop 0
	global_load_lds_dwordx4 v[212:213], off
	v_lshl_add_u64 v[212:213], v[216:217], 0, v[212:213]
	v_mfma_f32_32x32x16_bf16 v[32:47], v[166:169], v[200:203], v[32:47]
	s_add_u32 m0, s14, 0xb000
	s_nop 0
	global_load_lds_dwordx4 v[214:215], off
	v_lshl_add_u64 v[214:215], v[216:217], 0, v[214:215]
	v_mfma_f32_32x32x16_bf16 v[16:31], v[170:173], v[200:203], v[16:31]
	v_mfma_f32_32x32x16_bf16 v[0:15], v[174:177], v[200:203], v[0:15]
	s_waitcnt lgkmcnt(4)
	v_mfma_f32_32x32x16_bf16 v[112:127], v[128:131], v[144:147], v[112:127]
	s_waitcnt lgkmcnt(3)
	v_mfma_f32_32x32x16_bf16 v[96:111], v[132:135], v[144:147], v[96:111]
	s_waitcnt lgkmcnt(1)
	v_mfma_f32_32x32x16_bf16 v[80:95], v[136:139], v[144:147], v[80:95]
	s_waitcnt lgkmcnt(0)
	v_mfma_f32_32x32x16_bf16 v[64:79], v[140:143], v[144:147], v[64:79]
	v_mfma_f32_32x32x16_bf16 v[48:63], v[128:131], v[148:151], v[48:63]
	v_mfma_f32_32x32x16_bf16 v[32:47], v[132:135], v[148:151], v[32:47]
	v_mfma_f32_32x32x16_bf16 v[16:31], v[136:139], v[148:151], v[16:31]
	v_mfma_f32_32x32x16_bf16 v[0:15], v[140:143], v[148:151], v[0:15]
	s_waitcnt vmcnt(6)
	s_waitcnt lgkmcnt(0)
	s_barrier
	ds_read_b128 v[162:165], v159 offset:8192
	ds_read_b128 v[178:181], v158
	ds_read_b128 v[166:169], v159 offset:10240
	ds_read_b128 v[200:203], v158 offset:2048
	ds_read_b128 v[170:173], v159 offset:12288
	ds_read_b128 v[174:177], v159 offset:14336
	ds_read_b128 v[128:131], v157 offset:8192
	ds_read_b128 v[144:147], v160
	ds_read_b128 v[132:135], v157 offset:10240
	ds_read_b128 v[148:151], v160 offset:2048
	ds_read_b128 v[136:139], v157 offset:12288
	ds_read_b128 v[140:143], v157 offset:14336
	s_waitcnt lgkmcnt(10)
	v_mfma_f32_32x32x16_bf16 v[112:127], v[162:165], v[178:181], v[112:127]
	s_add_u32 m0, s14, 0xc000
	s_nop 0
	global_load_lds_dwordx4 v[204:205], off
	v_lshl_add_u64 v[204:205], v[216:217], 0, v[204:205]
	s_waitcnt lgkmcnt(9)
	v_mfma_f32_32x32x16_bf16 v[96:111], v[166:169], v[178:181], v[96:111]
	s_add_u32 m0, s14, 0xd000
	s_nop 0
	global_load_lds_dwordx4 v[206:207], off
	v_lshl_add_u64 v[206:207], v[216:217], 0, v[206:207]
	s_waitcnt lgkmcnt(7)
	v_mfma_f32_32x32x16_bf16 v[80:95], v[170:173], v[178:181], v[80:95]
	s_add_u32 m0, s14, 0xe000
	s_nop 0
	global_load_lds_dwordx4 v[208:209], off
	v_lshl_add_u64 v[208:209], v[216:217], 0, v[208:209]
	s_waitcnt lgkmcnt(6)
	v_mfma_f32_32x32x16_bf16 v[64:79], v[174:177], v[178:181], v[64:79]
	s_add_u32 m0, s14, 0xf000
	s_nop 0
	global_load_lds_dwordx4 v[210:211], off
	v_lshl_add_u64 v[210:211], v[216:217], 0, v[210:211]
	v_mfma_f32_32x32x16_bf16 v[48:63], v[162:165], v[200:203], v[48:63]
	s_add_u32 m0, s14, 0x10000
	s_nop 0
	global_load_lds_dwordx4 v[212:213], off
	v_lshl_add_u64 v[212:213], v[216:217], 0, v[212:213]
	v_mfma_f32_32x32x16_bf16 v[32:47], v[166:169], v[200:203], v[32:47]
	s_add_u32 m0, s14, 0x11000
	s_nop 0
	global_load_lds_dwordx4 v[214:215], off
	v_lshl_add_u64 v[214:215], v[216:217], 0, v[214:215]
	v_mfma_f32_32x32x16_bf16 v[16:31], v[170:173], v[200:203], v[16:31]
	v_mfma_f32_32x32x16_bf16 v[0:15], v[174:177], v[200:203], v[0:15]
	s_waitcnt lgkmcnt(4)
	v_mfma_f32_32x32x16_bf16 v[112:127], v[128:131], v[144:147], v[112:127]
	s_waitcnt lgkmcnt(3)
	v_mfma_f32_32x32x16_bf16 v[96:111], v[132:135], v[144:147], v[96:111]
	s_waitcnt lgkmcnt(1)
	v_mfma_f32_32x32x16_bf16 v[80:95], v[136:139], v[144:147], v[80:95]
	s_waitcnt lgkmcnt(0)
	v_mfma_f32_32x32x16_bf16 v[64:79], v[140:143], v[144:147], v[64:79]
	v_mfma_f32_32x32x16_bf16 v[48:63], v[128:131], v[148:151], v[48:63]
	v_mfma_f32_32x32x16_bf16 v[32:47], v[132:135], v[148:151], v[32:47]
	v_mfma_f32_32x32x16_bf16 v[16:31], v[136:139], v[148:151], v[16:31]
	v_mfma_f32_32x32x16_bf16 v[0:15], v[140:143], v[148:151], v[0:15]
	s_waitcnt vmcnt(6)
	s_waitcnt lgkmcnt(0)
	s_barrier
	ds_read_b128 v[162:165], v159 offset:32768
	ds_read_b128 v[178:181], v158 offset:24576
	ds_read_b128 v[166:169], v159 offset:34816
	ds_read_b128 v[200:203], v158 offset:26624
	ds_read_b128 v[170:173], v159 offset:36864
	ds_read_b128 v[174:177], v159 offset:38912
	ds_read_b128 v[128:131], v157 offset:32768
	ds_read_b128 v[144:147], v160 offset:24576
	ds_read_b128 v[132:135], v157 offset:34816
	ds_read_b128 v[148:151], v160 offset:26624
	ds_read_b128 v[136:139], v157 offset:36864
	ds_read_b128 v[140:143], v157 offset:38912
	s_waitcnt lgkmcnt(10)
	v_mfma_f32_32x32x16_bf16 v[112:127], v[162:165], v[178:181], v[112:127]
	s_mov_b32 m0, s14
	s_nop 0
	global_load_lds_dwordx4 v[204:205], off
	v_lshl_add_u64 v[204:205], v[216:217], 0, v[204:205]
	s_waitcnt lgkmcnt(9)
	v_mfma_f32_32x32x16_bf16 v[96:111], v[166:169], v[178:181], v[96:111]
	s_add_u32 m0, s14, 0x1000
	s_nop 0
	global_load_lds_dwordx4 v[206:207], off
	v_lshl_add_u64 v[206:207], v[216:217], 0, v[206:207]
	s_waitcnt lgkmcnt(7)
	v_mfma_f32_32x32x16_bf16 v[80:95], v[170:173], v[178:181], v[80:95]
	s_add_u32 m0, s14, 0x2000
	s_nop 0
	global_load_lds_dwordx4 v[208:209], off
	v_lshl_add_u64 v[208:209], v[216:217], 0, v[208:209]
	s_waitcnt lgkmcnt(6)
	v_mfma_f32_32x32x16_bf16 v[64:79], v[174:177], v[178:181], v[64:79]
	s_add_u32 m0, s14, 0x3000
	s_nop 0
	global_load_lds_dwordx4 v[210:211], off
	v_lshl_add_u64 v[210:211], v[216:217], 0, v[210:211]
	v_mfma_f32_32x32x16_bf16 v[48:63], v[162:165], v[200:203], v[48:63]
	s_add_u32 m0, s14, 0x4000
	s_nop 0
	global_load_lds_dwordx4 v[212:213], off
	v_lshl_add_u64 v[212:213], v[216:217], 0, v[212:213]
	v_mfma_f32_32x32x16_bf16 v[32:47], v[166:169], v[200:203], v[32:47]
	s_add_u32 m0, s14, 0x5000
	s_nop 0
	global_load_lds_dwordx4 v[214:215], off
	v_lshl_add_u64 v[214:215], v[216:217], 0, v[214:215]
	v_mfma_f32_32x32x16_bf16 v[16:31], v[170:173], v[200:203], v[16:31]
	v_mfma_f32_32x32x16_bf16 v[0:15], v[174:177], v[200:203], v[0:15]
	s_waitcnt lgkmcnt(4)
	v_mfma_f32_32x32x16_bf16 v[112:127], v[128:131], v[144:147], v[112:127]
	s_waitcnt lgkmcnt(3)
	v_mfma_f32_32x32x16_bf16 v[96:111], v[132:135], v[144:147], v[96:111]
	s_waitcnt lgkmcnt(1)
	v_mfma_f32_32x32x16_bf16 v[80:95], v[136:139], v[144:147], v[80:95]
	s_waitcnt lgkmcnt(0)
	v_mfma_f32_32x32x16_bf16 v[64:79], v[140:143], v[144:147], v[64:79]
	v_mfma_f32_32x32x16_bf16 v[48:63], v[128:131], v[148:151], v[48:63]
	v_mfma_f32_32x32x16_bf16 v[32:47], v[132:135], v[148:151], v[32:47]
	v_mfma_f32_32x32x16_bf16 v[16:31], v[136:139], v[148:151], v[16:31]
	v_mfma_f32_32x32x16_bf16 v[0:15], v[140:143], v[148:151], v[0:15]
	s_waitcnt vmcnt(6)
	s_waitcnt lgkmcnt(0)
	s_barrier
	ds_read_b128 v[162:165], v159 offset:57344
	ds_read_b128 v[178:181], v158 offset:49152
	ds_read_b128 v[166:169], v159 offset:59392
	ds_read_b128 v[200:203], v158 offset:51200
	ds_read_b128 v[170:173], v159 offset:61440
	ds_read_b128 v[174:177], v159 offset:63488
	ds_read_b128 v[128:131], v157 offset:57344
	ds_read_b128 v[144:147], v160 offset:49152
	ds_read_b128 v[132:135], v157 offset:59392
	ds_read_b128 v[148:151], v160 offset:51200
	ds_read_b128 v[136:139], v157 offset:61440
	ds_read_b128 v[140:143], v157 offset:63488
	s_waitcnt lgkmcnt(10)
	v_mfma_f32_32x32x16_bf16 v[112:127], v[162:165], v[178:181], v[112:127]
	s_add_u32 m0, s14, 0x6000
	s_nop 0
	global_load_lds_dwordx4 v[204:205], off
	v_lshl_add_u64 v[204:205], v[216:217], 0, v[204:205]
	s_waitcnt lgkmcnt(9)
	v_mfma_f32_32x32x16_bf16 v[96:111], v[166:169], v[178:181], v[96:111]
	s_add_u32 m0, s14, 0x7000
	s_nop 0
	global_load_lds_dwordx4 v[206:207], off
	v_lshl_add_u64 v[206:207], v[216:217], 0, v[206:207]
	s_waitcnt lgkmcnt(7)
	v_mfma_f32_32x32x16_bf16 v[80:95], v[170:173], v[178:181], v[80:95]
	s_add_u32 m0, s14, 0x8000
	s_nop 0
	global_load_lds_dwordx4 v[208:209], off
	v_lshl_add_u64 v[208:209], v[216:217], 0, v[208:209]
	s_waitcnt lgkmcnt(6)
	v_mfma_f32_32x32x16_bf16 v[64:79], v[174:177], v[178:181], v[64:79]
	s_add_u32 m0, s14, 0x9000
	s_nop 0
	global_load_lds_dwordx4 v[210:211], off
	v_lshl_add_u64 v[210:211], v[216:217], 0, v[210:211]
	v_mfma_f32_32x32x16_bf16 v[48:63], v[162:165], v[200:203], v[48:63]
	s_add_u32 m0, s14, 0xa000
	s_nop 0
	global_load_lds_dwordx4 v[212:213], off
	v_lshl_add_u64 v[212:213], v[216:217], 0, v[212:213]
	v_mfma_f32_32x32x16_bf16 v[32:47], v[166:169], v[200:203], v[32:47]
	s_add_u32 m0, s14, 0xb000
	s_nop 0
	global_load_lds_dwordx4 v[214:215], off
	v_lshl_add_u64 v[214:215], v[216:217], 0, v[214:215]
	v_mfma_f32_32x32x16_bf16 v[16:31], v[170:173], v[200:203], v[16:31]
	v_mfma_f32_32x32x16_bf16 v[0:15], v[174:177], v[200:203], v[0:15]
	s_waitcnt lgkmcnt(4)
	v_mfma_f32_32x32x16_bf16 v[112:127], v[128:131], v[144:147], v[112:127]
	s_waitcnt lgkmcnt(3)
	v_mfma_f32_32x32x16_bf16 v[96:111], v[132:135], v[144:147], v[96:111]
	s_waitcnt lgkmcnt(1)
	v_mfma_f32_32x32x16_bf16 v[80:95], v[136:139], v[144:147], v[80:95]
	s_waitcnt lgkmcnt(0)
	v_mfma_f32_32x32x16_bf16 v[64:79], v[140:143], v[144:147], v[64:79]
	v_mfma_f32_32x32x16_bf16 v[48:63], v[128:131], v[148:151], v[48:63]
	v_mfma_f32_32x32x16_bf16 v[32:47], v[132:135], v[148:151], v[32:47]
	v_mfma_f32_32x32x16_bf16 v[16:31], v[136:139], v[148:151], v[16:31]
	v_mfma_f32_32x32x16_bf16 v[0:15], v[140:143], v[148:151], v[0:15]
	s_waitcnt vmcnt(6)
	s_waitcnt lgkmcnt(0)
	s_barrier
	ds_read_b128 v[162:165], v159 offset:8192
	ds_read_b128 v[178:181], v158
	ds_read_b128 v[166:169], v159 offset:10240
	ds_read_b128 v[200:203], v158 offset:2048
	ds_read_b128 v[170:173], v159 offset:12288
	ds_read_b128 v[174:177], v159 offset:14336
	ds_read_b128 v[128:131], v157 offset:8192
	ds_read_b128 v[144:147], v160
	ds_read_b128 v[132:135], v157 offset:10240
	ds_read_b128 v[148:151], v160 offset:2048
	ds_read_b128 v[136:139], v157 offset:12288
	ds_read_b128 v[140:143], v157 offset:14336
	s_waitcnt lgkmcnt(10)
	v_mfma_f32_32x32x16_bf16 v[112:127], v[162:165], v[178:181], v[112:127]
	s_add_u32 m0, s14, 0xc000
	s_nop 0
	global_load_lds_dwordx4 v[204:205], off
	v_lshl_add_u64 v[204:205], v[216:217], 0, v[204:205]
	s_waitcnt lgkmcnt(9)
	v_mfma_f32_32x32x16_bf16 v[96:111], v[166:169], v[178:181], v[96:111]
	s_add_u32 m0, s14, 0xd000
	s_nop 0
	global_load_lds_dwordx4 v[206:207], off
	v_lshl_add_u64 v[206:207], v[216:217], 0, v[206:207]
	s_waitcnt lgkmcnt(7)
	v_mfma_f32_32x32x16_bf16 v[80:95], v[170:173], v[178:181], v[80:95]
	s_add_u32 m0, s14, 0xe000
	s_nop 0
	global_load_lds_dwordx4 v[208:209], off
	v_lshl_add_u64 v[208:209], v[216:217], 0, v[208:209]
	s_waitcnt lgkmcnt(6)
	v_mfma_f32_32x32x16_bf16 v[64:79], v[174:177], v[178:181], v[64:79]
	s_add_u32 m0, s14, 0xf000
	s_nop 0
	global_load_lds_dwordx4 v[210:211], off
	v_lshl_add_u64 v[210:211], v[216:217], 0, v[210:211]
	v_mfma_f32_32x32x16_bf16 v[48:63], v[162:165], v[200:203], v[48:63]
	s_add_u32 m0, s14, 0x10000
	s_nop 0
	global_load_lds_dwordx4 v[212:213], off
	v_lshl_add_u64 v[212:213], v[216:217], 0, v[212:213]
	v_mfma_f32_32x32x16_bf16 v[32:47], v[166:169], v[200:203], v[32:47]
	s_add_u32 m0, s14, 0x11000
	s_nop 0
	global_load_lds_dwordx4 v[214:215], off
	v_lshl_add_u64 v[214:215], v[216:217], 0, v[214:215]
	v_mfma_f32_32x32x16_bf16 v[16:31], v[170:173], v[200:203], v[16:31]
	v_mfma_f32_32x32x16_bf16 v[0:15], v[174:177], v[200:203], v[0:15]
	s_waitcnt lgkmcnt(4)
	v_mfma_f32_32x32x16_bf16 v[112:127], v[128:131], v[144:147], v[112:127]
	s_waitcnt lgkmcnt(3)
	v_mfma_f32_32x32x16_bf16 v[96:111], v[132:135], v[144:147], v[96:111]
	s_waitcnt lgkmcnt(1)
	v_mfma_f32_32x32x16_bf16 v[80:95], v[136:139], v[144:147], v[80:95]
	s_waitcnt lgkmcnt(0)
	v_mfma_f32_32x32x16_bf16 v[64:79], v[140:143], v[144:147], v[64:79]
	v_mfma_f32_32x32x16_bf16 v[48:63], v[128:131], v[148:151], v[48:63]
	v_mfma_f32_32x32x16_bf16 v[32:47], v[132:135], v[148:151], v[32:47]
	v_mfma_f32_32x32x16_bf16 v[16:31], v[136:139], v[148:151], v[16:31]
	v_mfma_f32_32x32x16_bf16 v[0:15], v[140:143], v[148:151], v[0:15]
	s_waitcnt vmcnt(6)
	s_waitcnt lgkmcnt(0)
	s_barrier
	ds_read_b128 v[162:165], v159 offset:32768
	ds_read_b128 v[178:181], v158 offset:24576
	ds_read_b128 v[166:169], v159 offset:34816
	ds_read_b128 v[200:203], v158 offset:26624
	ds_read_b128 v[170:173], v159 offset:36864
	ds_read_b128 v[174:177], v159 offset:38912
	ds_read_b128 v[128:131], v157 offset:32768
	ds_read_b128 v[144:147], v160 offset:24576
	ds_read_b128 v[132:135], v157 offset:34816
	ds_read_b128 v[148:151], v160 offset:26624
	ds_read_b128 v[136:139], v157 offset:36864
	ds_read_b128 v[140:143], v157 offset:38912
	s_waitcnt lgkmcnt(10)
	v_mfma_f32_32x32x16_bf16 v[112:127], v[162:165], v[178:181], v[112:127]
	s_mov_b32 m0, s14
	s_nop 0
	global_load_lds_dwordx4 v[204:205], off
	v_lshl_add_u64 v[204:205], v[216:217], 0, v[204:205]
	s_waitcnt lgkmcnt(9)
	v_mfma_f32_32x32x16_bf16 v[96:111], v[166:169], v[178:181], v[96:111]
	s_add_u32 m0, s14, 0x1000
	s_nop 0
	global_load_lds_dwordx4 v[206:207], off
	v_lshl_add_u64 v[206:207], v[216:217], 0, v[206:207]
	s_waitcnt lgkmcnt(7)
	v_mfma_f32_32x32x16_bf16 v[80:95], v[170:173], v[178:181], v[80:95]
	s_add_u32 m0, s14, 0x2000
	s_nop 0
	global_load_lds_dwordx4 v[208:209], off
	v_lshl_add_u64 v[208:209], v[216:217], 0, v[208:209]
	s_waitcnt lgkmcnt(6)
	v_mfma_f32_32x32x16_bf16 v[64:79], v[174:177], v[178:181], v[64:79]
	s_add_u32 m0, s14, 0x3000
	s_nop 0
	global_load_lds_dwordx4 v[210:211], off
	v_lshl_add_u64 v[210:211], v[216:217], 0, v[210:211]
	v_mfma_f32_32x32x16_bf16 v[48:63], v[162:165], v[200:203], v[48:63]
	s_add_u32 m0, s14, 0x4000
	s_nop 0
	global_load_lds_dwordx4 v[212:213], off
	v_lshl_add_u64 v[212:213], v[216:217], 0, v[212:213]
	v_mfma_f32_32x32x16_bf16 v[32:47], v[166:169], v[200:203], v[32:47]
	s_add_u32 m0, s14, 0x5000
	s_nop 0
	global_load_lds_dwordx4 v[214:215], off
	v_lshl_add_u64 v[214:215], v[216:217], 0, v[214:215]
	v_mfma_f32_32x32x16_bf16 v[16:31], v[170:173], v[200:203], v[16:31]
	v_mfma_f32_32x32x16_bf16 v[0:15], v[174:177], v[200:203], v[0:15]
	s_waitcnt lgkmcnt(4)
	v_mfma_f32_32x32x16_bf16 v[112:127], v[128:131], v[144:147], v[112:127]
	s_waitcnt lgkmcnt(3)
	v_mfma_f32_32x32x16_bf16 v[96:111], v[132:135], v[144:147], v[96:111]
	s_waitcnt lgkmcnt(1)
	v_mfma_f32_32x32x16_bf16 v[80:95], v[136:139], v[144:147], v[80:95]
	s_waitcnt lgkmcnt(0)
	v_mfma_f32_32x32x16_bf16 v[64:79], v[140:143], v[144:147], v[64:79]
	v_mfma_f32_32x32x16_bf16 v[48:63], v[128:131], v[148:151], v[48:63]
	v_mfma_f32_32x32x16_bf16 v[32:47], v[132:135], v[148:151], v[32:47]
	v_mfma_f32_32x32x16_bf16 v[16:31], v[136:139], v[148:151], v[16:31]
	v_mfma_f32_32x32x16_bf16 v[0:15], v[140:143], v[148:151], v[0:15]
	s_waitcnt vmcnt(6)
	s_waitcnt lgkmcnt(0)
	s_barrier
	ds_read_b128 v[162:165], v159 offset:57344
	ds_read_b128 v[178:181], v158 offset:49152
	ds_read_b128 v[166:169], v159 offset:59392
	ds_read_b128 v[200:203], v158 offset:51200
	ds_read_b128 v[170:173], v159 offset:61440
	ds_read_b128 v[174:177], v159 offset:63488
	ds_read_b128 v[128:131], v157 offset:57344
	ds_read_b128 v[144:147], v160 offset:49152
	ds_read_b128 v[132:135], v157 offset:59392
	ds_read_b128 v[148:151], v160 offset:51200
	ds_read_b128 v[136:139], v157 offset:61440
	ds_read_b128 v[140:143], v157 offset:63488
	s_waitcnt lgkmcnt(10)
	v_mfma_f32_32x32x16_bf16 v[112:127], v[162:165], v[178:181], v[112:127]
	s_add_u32 m0, s14, 0x6000
	s_nop 0
	global_load_lds_dwordx4 v[204:205], off
	v_lshl_add_u64 v[204:205], v[216:217], 0, v[204:205]
	s_waitcnt lgkmcnt(9)
	v_mfma_f32_32x32x16_bf16 v[96:111], v[166:169], v[178:181], v[96:111]
	s_add_u32 m0, s14, 0x7000
	s_nop 0
	global_load_lds_dwordx4 v[206:207], off
	v_lshl_add_u64 v[206:207], v[216:217], 0, v[206:207]
	s_waitcnt lgkmcnt(7)
	v_mfma_f32_32x32x16_bf16 v[80:95], v[170:173], v[178:181], v[80:95]
	s_add_u32 m0, s14, 0x8000
	s_nop 0
	global_load_lds_dwordx4 v[208:209], off
	v_lshl_add_u64 v[208:209], v[216:217], 0, v[208:209]
	s_waitcnt lgkmcnt(6)
	v_mfma_f32_32x32x16_bf16 v[64:79], v[174:177], v[178:181], v[64:79]
	s_add_u32 m0, s14, 0x9000
	s_nop 0
	global_load_lds_dwordx4 v[210:211], off
	v_lshl_add_u64 v[210:211], v[216:217], 0, v[210:211]
	v_mfma_f32_32x32x16_bf16 v[48:63], v[162:165], v[200:203], v[48:63]
	s_add_u32 m0, s14, 0xa000
	s_nop 0
	global_load_lds_dwordx4 v[212:213], off
	v_lshl_add_u64 v[212:213], v[216:217], 0, v[212:213]
	v_mfma_f32_32x32x16_bf16 v[32:47], v[166:169], v[200:203], v[32:47]
	s_add_u32 m0, s14, 0xb000
	s_nop 0
	global_load_lds_dwordx4 v[214:215], off
	v_lshl_add_u64 v[214:215], v[216:217], 0, v[214:215]
	v_mfma_f32_32x32x16_bf16 v[16:31], v[170:173], v[200:203], v[16:31]
	v_mfma_f32_32x32x16_bf16 v[0:15], v[174:177], v[200:203], v[0:15]
	s_waitcnt lgkmcnt(4)
	v_mfma_f32_32x32x16_bf16 v[112:127], v[128:131], v[144:147], v[112:127]
	s_waitcnt lgkmcnt(3)
	v_mfma_f32_32x32x16_bf16 v[96:111], v[132:135], v[144:147], v[96:111]
	s_waitcnt lgkmcnt(1)
	v_mfma_f32_32x32x16_bf16 v[80:95], v[136:139], v[144:147], v[80:95]
	s_waitcnt lgkmcnt(0)
	v_mfma_f32_32x32x16_bf16 v[64:79], v[140:143], v[144:147], v[64:79]
	v_mfma_f32_32x32x16_bf16 v[48:63], v[128:131], v[148:151], v[48:63]
	v_mfma_f32_32x32x16_bf16 v[32:47], v[132:135], v[148:151], v[32:47]
	v_mfma_f32_32x32x16_bf16 v[16:31], v[136:139], v[148:151], v[16:31]
	v_mfma_f32_32x32x16_bf16 v[0:15], v[140:143], v[148:151], v[0:15]
	s_waitcnt vmcnt(6)
	s_waitcnt lgkmcnt(0)
	s_barrier
	ds_read_b128 v[162:165], v159 offset:8192
	ds_read_b128 v[178:181], v158
	ds_read_b128 v[166:169], v159 offset:10240
	ds_read_b128 v[200:203], v158 offset:2048
	ds_read_b128 v[170:173], v159 offset:12288
	ds_read_b128 v[174:177], v159 offset:14336
	ds_read_b128 v[128:131], v157 offset:8192
	ds_read_b128 v[144:147], v160
	ds_read_b128 v[132:135], v157 offset:10240
	ds_read_b128 v[148:151], v160 offset:2048
	ds_read_b128 v[136:139], v157 offset:12288
	ds_read_b128 v[140:143], v157 offset:14336
	s_waitcnt lgkmcnt(10)
	v_mfma_f32_32x32x16_bf16 v[112:127], v[162:165], v[178:181], v[112:127]
	s_add_u32 m0, s14, 0xc000
	s_nop 0
	global_load_lds_dwordx4 v[204:205], off
	v_lshl_add_u64 v[204:205], v[216:217], 0, v[204:205]
	s_waitcnt lgkmcnt(9)
	v_mfma_f32_32x32x16_bf16 v[96:111], v[166:169], v[178:181], v[96:111]
	s_add_u32 m0, s14, 0xd000
	s_nop 0
	global_load_lds_dwordx4 v[206:207], off
	v_lshl_add_u64 v[206:207], v[216:217], 0, v[206:207]
	s_waitcnt lgkmcnt(7)
	v_mfma_f32_32x32x16_bf16 v[80:95], v[170:173], v[178:181], v[80:95]
	s_add_u32 m0, s14, 0xe000
	s_nop 0
	global_load_lds_dwordx4 v[208:209], off
	v_lshl_add_u64 v[208:209], v[216:217], 0, v[208:209]
	s_waitcnt lgkmcnt(6)
	v_mfma_f32_32x32x16_bf16 v[64:79], v[174:177], v[178:181], v[64:79]
	s_add_u32 m0, s14, 0xf000
	s_nop 0
	global_load_lds_dwordx4 v[210:211], off
	v_lshl_add_u64 v[210:211], v[216:217], 0, v[210:211]
	v_mfma_f32_32x32x16_bf16 v[48:63], v[162:165], v[200:203], v[48:63]
	s_add_u32 m0, s14, 0x10000
	s_nop 0
	global_load_lds_dwordx4 v[212:213], off
	v_lshl_add_u64 v[212:213], v[216:217], 0, v[212:213]
	v_mfma_f32_32x32x16_bf16 v[32:47], v[166:169], v[200:203], v[32:47]
	s_add_u32 m0, s14, 0x11000
	s_nop 0
	global_load_lds_dwordx4 v[214:215], off
	v_lshl_add_u64 v[214:215], v[216:217], 0, v[214:215]
	v_mfma_f32_32x32x16_bf16 v[16:31], v[170:173], v[200:203], v[16:31]
	v_mfma_f32_32x32x16_bf16 v[0:15], v[174:177], v[200:203], v[0:15]
	s_waitcnt lgkmcnt(4)
	v_mfma_f32_32x32x16_bf16 v[112:127], v[128:131], v[144:147], v[112:127]
	s_waitcnt lgkmcnt(3)
	v_mfma_f32_32x32x16_bf16 v[96:111], v[132:135], v[144:147], v[96:111]
	s_waitcnt lgkmcnt(1)
	v_mfma_f32_32x32x16_bf16 v[80:95], v[136:139], v[144:147], v[80:95]
	s_waitcnt lgkmcnt(0)
	v_mfma_f32_32x32x16_bf16 v[64:79], v[140:143], v[144:147], v[64:79]
	v_mfma_f32_32x32x16_bf16 v[48:63], v[128:131], v[148:151], v[48:63]
	v_mfma_f32_32x32x16_bf16 v[32:47], v[132:135], v[148:151], v[32:47]
	v_mfma_f32_32x32x16_bf16 v[16:31], v[136:139], v[148:151], v[16:31]
	v_mfma_f32_32x32x16_bf16 v[0:15], v[140:143], v[148:151], v[0:15]
	s_waitcnt vmcnt(6)
	s_waitcnt lgkmcnt(0)
	s_barrier
	ds_read_b128 v[162:165], v159 offset:32768
	ds_read_b128 v[178:181], v158 offset:24576
	ds_read_b128 v[166:169], v159 offset:34816
	ds_read_b128 v[200:203], v158 offset:26624
	ds_read_b128 v[170:173], v159 offset:36864
	ds_read_b128 v[174:177], v159 offset:38912
	ds_read_b128 v[128:131], v157 offset:32768
	ds_read_b128 v[144:147], v160 offset:24576
	ds_read_b128 v[132:135], v157 offset:34816
	ds_read_b128 v[148:151], v160 offset:26624
	ds_read_b128 v[136:139], v157 offset:36864
	ds_read_b128 v[140:143], v157 offset:38912
	s_waitcnt lgkmcnt(10)
	v_mfma_f32_32x32x16_bf16 v[112:127], v[162:165], v[178:181], v[112:127]
	s_mov_b32 m0, s14
	s_nop 0
	global_load_lds_dwordx4 v[204:205], off
	v_lshl_add_u64 v[204:205], v[216:217], 0, v[204:205]
	s_waitcnt lgkmcnt(9)
	v_mfma_f32_32x32x16_bf16 v[96:111], v[166:169], v[178:181], v[96:111]
	s_add_u32 m0, s14, 0x1000
	s_nop 0
	global_load_lds_dwordx4 v[206:207], off
	v_lshl_add_u64 v[206:207], v[216:217], 0, v[206:207]
	s_waitcnt lgkmcnt(7)
	v_mfma_f32_32x32x16_bf16 v[80:95], v[170:173], v[178:181], v[80:95]
	s_add_u32 m0, s14, 0x2000
	s_nop 0
	global_load_lds_dwordx4 v[208:209], off
	v_lshl_add_u64 v[208:209], v[216:217], 0, v[208:209]
	s_waitcnt lgkmcnt(6)
	v_mfma_f32_32x32x16_bf16 v[64:79], v[174:177], v[178:181], v[64:79]
	s_add_u32 m0, s14, 0x3000
	s_nop 0
	global_load_lds_dwordx4 v[210:211], off
	v_lshl_add_u64 v[210:211], v[216:217], 0, v[210:211]
	v_mfma_f32_32x32x16_bf16 v[48:63], v[162:165], v[200:203], v[48:63]
	s_add_u32 m0, s14, 0x4000
	s_nop 0
	global_load_lds_dwordx4 v[212:213], off
	v_lshl_add_u64 v[212:213], v[216:217], 0, v[212:213]
	v_mfma_f32_32x32x16_bf16 v[32:47], v[166:169], v[200:203], v[32:47]
	s_add_u32 m0, s14, 0x5000
	s_nop 0
	global_load_lds_dwordx4 v[214:215], off
	v_lshl_add_u64 v[214:215], v[216:217], 0, v[214:215]
	v_mfma_f32_32x32x16_bf16 v[16:31], v[170:173], v[200:203], v[16:31]
	v_mfma_f32_32x32x16_bf16 v[0:15], v[174:177], v[200:203], v[0:15]
	s_waitcnt lgkmcnt(4)
	v_mfma_f32_32x32x16_bf16 v[112:127], v[128:131], v[144:147], v[112:127]
	s_waitcnt lgkmcnt(3)
	v_mfma_f32_32x32x16_bf16 v[96:111], v[132:135], v[144:147], v[96:111]
	s_waitcnt lgkmcnt(1)
	v_mfma_f32_32x32x16_bf16 v[80:95], v[136:139], v[144:147], v[80:95]
	s_waitcnt lgkmcnt(0)
	v_mfma_f32_32x32x16_bf16 v[64:79], v[140:143], v[144:147], v[64:79]
	v_mfma_f32_32x32x16_bf16 v[48:63], v[128:131], v[148:151], v[48:63]
	v_mfma_f32_32x32x16_bf16 v[32:47], v[132:135], v[148:151], v[32:47]
	v_mfma_f32_32x32x16_bf16 v[16:31], v[136:139], v[148:151], v[16:31]
	v_mfma_f32_32x32x16_bf16 v[0:15], v[140:143], v[148:151], v[0:15]
	s_waitcnt vmcnt(6)
	s_waitcnt lgkmcnt(0)
	s_barrier
	ds_read_b128 v[162:165], v159 offset:57344
	ds_read_b128 v[178:181], v158 offset:49152
	ds_read_b128 v[166:169], v159 offset:59392
	ds_read_b128 v[200:203], v158 offset:51200
	ds_read_b128 v[170:173], v159 offset:61440
	ds_read_b128 v[174:177], v159 offset:63488
	ds_read_b128 v[128:131], v157 offset:57344
	ds_read_b128 v[144:147], v160 offset:49152
	ds_read_b128 v[132:135], v157 offset:59392
	ds_read_b128 v[148:151], v160 offset:51200
	ds_read_b128 v[136:139], v157 offset:61440
	ds_read_b128 v[140:143], v157 offset:63488
	s_waitcnt lgkmcnt(10)
	v_mfma_f32_32x32x16_bf16 v[112:127], v[162:165], v[178:181], v[112:127]
	s_add_u32 m0, s14, 0x6000
	s_nop 0
	global_load_lds_dwordx4 v[204:205], off
	v_lshl_add_u64 v[204:205], v[216:217], 0, v[204:205]
	s_waitcnt lgkmcnt(9)
	v_mfma_f32_32x32x16_bf16 v[96:111], v[166:169], v[178:181], v[96:111]
	s_add_u32 m0, s14, 0x7000
	s_nop 0
	global_load_lds_dwordx4 v[206:207], off
	v_lshl_add_u64 v[206:207], v[216:217], 0, v[206:207]
	s_waitcnt lgkmcnt(7)
	v_mfma_f32_32x32x16_bf16 v[80:95], v[170:173], v[178:181], v[80:95]
	s_add_u32 m0, s14, 0x8000
	s_nop 0
	global_load_lds_dwordx4 v[208:209], off
	v_lshl_add_u64 v[208:209], v[216:217], 0, v[208:209]
	s_waitcnt lgkmcnt(6)
	v_mfma_f32_32x32x16_bf16 v[64:79], v[174:177], v[178:181], v[64:79]
	s_add_u32 m0, s14, 0x9000
	s_nop 0
	global_load_lds_dwordx4 v[210:211], off
	v_lshl_add_u64 v[210:211], v[216:217], 0, v[210:211]
	v_mfma_f32_32x32x16_bf16 v[48:63], v[162:165], v[200:203], v[48:63]
	s_add_u32 m0, s14, 0xa000
	s_nop 0
	global_load_lds_dwordx4 v[212:213], off
	v_lshl_add_u64 v[212:213], v[216:217], 0, v[212:213]
	v_mfma_f32_32x32x16_bf16 v[32:47], v[166:169], v[200:203], v[32:47]
	s_add_u32 m0, s14, 0xb000
	s_nop 0
	global_load_lds_dwordx4 v[214:215], off
	v_lshl_add_u64 v[214:215], v[216:217], 0, v[214:215]
	v_mfma_f32_32x32x16_bf16 v[16:31], v[170:173], v[200:203], v[16:31]
	v_mfma_f32_32x32x16_bf16 v[0:15], v[174:177], v[200:203], v[0:15]
	s_waitcnt lgkmcnt(4)
	v_mfma_f32_32x32x16_bf16 v[112:127], v[128:131], v[144:147], v[112:127]
	s_waitcnt lgkmcnt(3)
	v_mfma_f32_32x32x16_bf16 v[96:111], v[132:135], v[144:147], v[96:111]
	s_waitcnt lgkmcnt(1)
	v_mfma_f32_32x32x16_bf16 v[80:95], v[136:139], v[144:147], v[80:95]
	s_waitcnt lgkmcnt(0)
	v_mfma_f32_32x32x16_bf16 v[64:79], v[140:143], v[144:147], v[64:79]
	v_mfma_f32_32x32x16_bf16 v[48:63], v[128:131], v[148:151], v[48:63]
	v_mfma_f32_32x32x16_bf16 v[32:47], v[132:135], v[148:151], v[32:47]
	v_mfma_f32_32x32x16_bf16 v[16:31], v[136:139], v[148:151], v[16:31]
	v_mfma_f32_32x32x16_bf16 v[0:15], v[140:143], v[148:151], v[0:15]
	s_waitcnt vmcnt(6)
	s_waitcnt lgkmcnt(0)
	s_barrier
	ds_read_b128 v[162:165], v159 offset:8192
	ds_read_b128 v[178:181], v158
	ds_read_b128 v[166:169], v159 offset:10240
	ds_read_b128 v[200:203], v158 offset:2048
	ds_read_b128 v[170:173], v159 offset:12288
	ds_read_b128 v[174:177], v159 offset:14336
	ds_read_b128 v[128:131], v157 offset:8192
	ds_read_b128 v[144:147], v160
	ds_read_b128 v[132:135], v157 offset:10240
	ds_read_b128 v[148:151], v160 offset:2048
	ds_read_b128 v[136:139], v157 offset:12288
	ds_read_b128 v[140:143], v157 offset:14336
	s_waitcnt lgkmcnt(10)
	v_mfma_f32_32x32x16_bf16 v[112:127], v[162:165], v[178:181], v[112:127]
	s_add_u32 m0, s14, 0xc000
	s_nop 0
	global_load_lds_dwordx4 v[204:205], off
	v_lshl_add_u64 v[204:205], v[216:217], 0, v[204:205]
	s_waitcnt lgkmcnt(9)
	v_mfma_f32_32x32x16_bf16 v[96:111], v[166:169], v[178:181], v[96:111]
	s_add_u32 m0, s14, 0xd000
	s_nop 0
	global_load_lds_dwordx4 v[206:207], off
	v_lshl_add_u64 v[206:207], v[216:217], 0, v[206:207]
	s_waitcnt lgkmcnt(7)
	v_mfma_f32_32x32x16_bf16 v[80:95], v[170:173], v[178:181], v[80:95]
	s_add_u32 m0, s14, 0xe000
	s_nop 0
	global_load_lds_dwordx4 v[208:209], off
	v_lshl_add_u64 v[208:209], v[216:217], 0, v[208:209]
	s_waitcnt lgkmcnt(6)
	v_mfma_f32_32x32x16_bf16 v[64:79], v[174:177], v[178:181], v[64:79]
	s_add_u32 m0, s14, 0xf000
	s_nop 0
	global_load_lds_dwordx4 v[210:211], off
	v_lshl_add_u64 v[210:211], v[216:217], 0, v[210:211]
	v_mfma_f32_32x32x16_bf16 v[48:63], v[162:165], v[200:203], v[48:63]
	s_add_u32 m0, s14, 0x10000
	s_nop 0
	global_load_lds_dwordx4 v[212:213], off
	v_lshl_add_u64 v[212:213], v[216:217], 0, v[212:213]
	v_mfma_f32_32x32x16_bf16 v[32:47], v[166:169], v[200:203], v[32:47]
	s_add_u32 m0, s14, 0x11000
	s_nop 0
	global_load_lds_dwordx4 v[214:215], off
	v_lshl_add_u64 v[214:215], v[216:217], 0, v[214:215]
	v_mfma_f32_32x32x16_bf16 v[16:31], v[170:173], v[200:203], v[16:31]
	v_mfma_f32_32x32x16_bf16 v[0:15], v[174:177], v[200:203], v[0:15]
	s_waitcnt lgkmcnt(4)
	v_mfma_f32_32x32x16_bf16 v[112:127], v[128:131], v[144:147], v[112:127]
	s_waitcnt lgkmcnt(3)
	v_mfma_f32_32x32x16_bf16 v[96:111], v[132:135], v[144:147], v[96:111]
	s_waitcnt lgkmcnt(1)
	v_mfma_f32_32x32x16_bf16 v[80:95], v[136:139], v[144:147], v[80:95]
	s_waitcnt lgkmcnt(0)
	v_mfma_f32_32x32x16_bf16 v[64:79], v[140:143], v[144:147], v[64:79]
	v_mfma_f32_32x32x16_bf16 v[48:63], v[128:131], v[148:151], v[48:63]
	v_mfma_f32_32x32x16_bf16 v[32:47], v[132:135], v[148:151], v[32:47]
	v_mfma_f32_32x32x16_bf16 v[16:31], v[136:139], v[148:151], v[16:31]
	v_mfma_f32_32x32x16_bf16 v[0:15], v[140:143], v[148:151], v[0:15]
	s_waitcnt vmcnt(6)
	s_waitcnt lgkmcnt(0)
	s_barrier
	ds_read_b128 v[162:165], v159 offset:32768
	ds_read_b128 v[178:181], v158 offset:24576
	ds_read_b128 v[166:169], v159 offset:34816
	ds_read_b128 v[200:203], v158 offset:26624
	ds_read_b128 v[170:173], v159 offset:36864
	ds_read_b128 v[174:177], v159 offset:38912
	ds_read_b128 v[128:131], v157 offset:32768
	ds_read_b128 v[144:147], v160 offset:24576
	ds_read_b128 v[132:135], v157 offset:34816
	ds_read_b128 v[148:151], v160 offset:26624
	ds_read_b128 v[136:139], v157 offset:36864
	ds_read_b128 v[140:143], v157 offset:38912
	s_waitcnt lgkmcnt(10)
	v_mfma_f32_32x32x16_bf16 v[112:127], v[162:165], v[178:181], v[112:127]
	s_mov_b32 m0, s14
	s_nop 0
	global_load_lds_dwordx4 v[204:205], off
	v_lshl_add_u64 v[204:205], v[216:217], 0, v[204:205]
	s_waitcnt lgkmcnt(9)
	v_mfma_f32_32x32x16_bf16 v[96:111], v[166:169], v[178:181], v[96:111]
	s_add_u32 m0, s14, 0x1000
	s_nop 0
	global_load_lds_dwordx4 v[206:207], off
	v_lshl_add_u64 v[206:207], v[216:217], 0, v[206:207]
	s_waitcnt lgkmcnt(7)
	v_mfma_f32_32x32x16_bf16 v[80:95], v[170:173], v[178:181], v[80:95]
	s_add_u32 m0, s14, 0x2000
	s_nop 0
	global_load_lds_dwordx4 v[208:209], off
	v_lshl_add_u64 v[208:209], v[216:217], 0, v[208:209]
	s_waitcnt lgkmcnt(6)
	v_mfma_f32_32x32x16_bf16 v[64:79], v[174:177], v[178:181], v[64:79]
	s_add_u32 m0, s14, 0x3000
	s_nop 0
	global_load_lds_dwordx4 v[210:211], off
	v_lshl_add_u64 v[210:211], v[216:217], 0, v[210:211]
	v_mfma_f32_32x32x16_bf16 v[48:63], v[162:165], v[200:203], v[48:63]
	s_add_u32 m0, s14, 0x4000
	s_nop 0
	global_load_lds_dwordx4 v[212:213], off
	v_lshl_add_u64 v[212:213], v[216:217], 0, v[212:213]
	v_mfma_f32_32x32x16_bf16 v[32:47], v[166:169], v[200:203], v[32:47]
	s_add_u32 m0, s14, 0x5000
	s_nop 0
	global_load_lds_dwordx4 v[214:215], off
	v_lshl_add_u64 v[214:215], v[216:217], 0, v[214:215]
	v_mfma_f32_32x32x16_bf16 v[16:31], v[170:173], v[200:203], v[16:31]
	v_mfma_f32_32x32x16_bf16 v[0:15], v[174:177], v[200:203], v[0:15]
	s_waitcnt lgkmcnt(4)
	v_mfma_f32_32x32x16_bf16 v[112:127], v[128:131], v[144:147], v[112:127]
	s_waitcnt lgkmcnt(3)
	v_mfma_f32_32x32x16_bf16 v[96:111], v[132:135], v[144:147], v[96:111]
	s_waitcnt lgkmcnt(1)
	v_mfma_f32_32x32x16_bf16 v[80:95], v[136:139], v[144:147], v[80:95]
	s_waitcnt lgkmcnt(0)
	v_mfma_f32_32x32x16_bf16 v[64:79], v[140:143], v[144:147], v[64:79]
	v_mfma_f32_32x32x16_bf16 v[48:63], v[128:131], v[148:151], v[48:63]
	v_mfma_f32_32x32x16_bf16 v[32:47], v[132:135], v[148:151], v[32:47]
	v_mfma_f32_32x32x16_bf16 v[16:31], v[136:139], v[148:151], v[16:31]
	v_mfma_f32_32x32x16_bf16 v[0:15], v[140:143], v[148:151], v[0:15]
	s_waitcnt vmcnt(6)
	s_waitcnt lgkmcnt(0)
	s_barrier
	ds_read_b128 v[162:165], v159 offset:57344
	ds_read_b128 v[178:181], v158 offset:49152
	ds_read_b128 v[166:169], v159 offset:59392
	ds_read_b128 v[200:203], v158 offset:51200
	ds_read_b128 v[170:173], v159 offset:61440
	ds_read_b128 v[174:177], v159 offset:63488
	ds_read_b128 v[128:131], v157 offset:57344
	ds_read_b128 v[144:147], v160 offset:49152
	ds_read_b128 v[132:135], v157 offset:59392
	ds_read_b128 v[148:151], v160 offset:51200
	ds_read_b128 v[136:139], v157 offset:61440
	ds_read_b128 v[140:143], v157 offset:63488
	s_waitcnt lgkmcnt(10)
	v_mfma_f32_32x32x16_bf16 v[112:127], v[162:165], v[178:181], v[112:127]
	s_add_u32 m0, s14, 0x6000
	s_nop 0
	global_load_lds_dwordx4 v[204:205], off
	v_lshl_add_u64 v[204:205], v[216:217], 0, v[204:205]
	s_waitcnt lgkmcnt(9)
	v_mfma_f32_32x32x16_bf16 v[96:111], v[166:169], v[178:181], v[96:111]
	s_add_u32 m0, s14, 0x7000
	s_nop 0
	global_load_lds_dwordx4 v[206:207], off
	v_lshl_add_u64 v[206:207], v[216:217], 0, v[206:207]
	s_waitcnt lgkmcnt(7)
	v_mfma_f32_32x32x16_bf16 v[80:95], v[170:173], v[178:181], v[80:95]
	s_add_u32 m0, s14, 0x8000
	s_nop 0
	global_load_lds_dwordx4 v[208:209], off
	v_lshl_add_u64 v[208:209], v[216:217], 0, v[208:209]
	s_waitcnt lgkmcnt(6)
	v_mfma_f32_32x32x16_bf16 v[64:79], v[174:177], v[178:181], v[64:79]
	s_add_u32 m0, s14, 0x9000
	s_nop 0
	global_load_lds_dwordx4 v[210:211], off
	v_lshl_add_u64 v[210:211], v[216:217], 0, v[210:211]
	v_mfma_f32_32x32x16_bf16 v[48:63], v[162:165], v[200:203], v[48:63]
	s_add_u32 m0, s14, 0xa000
	s_nop 0
	global_load_lds_dwordx4 v[212:213], off
	v_lshl_add_u64 v[212:213], v[216:217], 0, v[212:213]
	v_mfma_f32_32x32x16_bf16 v[32:47], v[166:169], v[200:203], v[32:47]
	s_add_u32 m0, s14, 0xb000
	s_nop 0
	global_load_lds_dwordx4 v[214:215], off
	v_lshl_add_u64 v[214:215], v[216:217], 0, v[214:215]
	v_mfma_f32_32x32x16_bf16 v[16:31], v[170:173], v[200:203], v[16:31]
	v_mfma_f32_32x32x16_bf16 v[0:15], v[174:177], v[200:203], v[0:15]
	s_waitcnt lgkmcnt(4)
	v_mfma_f32_32x32x16_bf16 v[112:127], v[128:131], v[144:147], v[112:127]
	s_waitcnt lgkmcnt(3)
	v_mfma_f32_32x32x16_bf16 v[96:111], v[132:135], v[144:147], v[96:111]
	s_waitcnt lgkmcnt(1)
	v_mfma_f32_32x32x16_bf16 v[80:95], v[136:139], v[144:147], v[80:95]
	s_waitcnt lgkmcnt(0)
	v_mfma_f32_32x32x16_bf16 v[64:79], v[140:143], v[144:147], v[64:79]
	v_mfma_f32_32x32x16_bf16 v[48:63], v[128:131], v[148:151], v[48:63]
	v_mfma_f32_32x32x16_bf16 v[32:47], v[132:135], v[148:151], v[32:47]
	v_mfma_f32_32x32x16_bf16 v[16:31], v[136:139], v[148:151], v[16:31]
	v_mfma_f32_32x32x16_bf16 v[0:15], v[140:143], v[148:151], v[0:15]
	s_waitcnt vmcnt(6)
	s_waitcnt lgkmcnt(0)
	s_barrier
	ds_read_b128 v[162:165], v159 offset:8192
	ds_read_b128 v[178:181], v158
	ds_read_b128 v[166:169], v159 offset:10240
	ds_read_b128 v[200:203], v158 offset:2048
	ds_read_b128 v[170:173], v159 offset:12288
	ds_read_b128 v[174:177], v159 offset:14336
	ds_read_b128 v[128:131], v157 offset:8192
	ds_read_b128 v[144:147], v160
	ds_read_b128 v[132:135], v157 offset:10240
	ds_read_b128 v[148:151], v160 offset:2048
	ds_read_b128 v[136:139], v157 offset:12288
	ds_read_b128 v[140:143], v157 offset:14336
	s_waitcnt lgkmcnt(10)
	v_mfma_f32_32x32x16_bf16 v[112:127], v[162:165], v[178:181], v[112:127]
	s_add_u32 m0, s14, 0xc000
	s_nop 0
	global_load_lds_dwordx4 v[204:205], off
	v_lshl_add_u64 v[204:205], v[216:217], 0, v[204:205]
	s_waitcnt lgkmcnt(9)
	v_mfma_f32_32x32x16_bf16 v[96:111], v[166:169], v[178:181], v[96:111]
	s_add_u32 m0, s14, 0xd000
	s_nop 0
	global_load_lds_dwordx4 v[206:207], off
	v_lshl_add_u64 v[206:207], v[216:217], 0, v[206:207]
	s_waitcnt lgkmcnt(7)
	v_mfma_f32_32x32x16_bf16 v[80:95], v[170:173], v[178:181], v[80:95]
	s_add_u32 m0, s14, 0xe000
	s_nop 0
	global_load_lds_dwordx4 v[208:209], off
	v_lshl_add_u64 v[208:209], v[216:217], 0, v[208:209]
	s_waitcnt lgkmcnt(6)
	v_mfma_f32_32x32x16_bf16 v[64:79], v[174:177], v[178:181], v[64:79]
	s_add_u32 m0, s14, 0xf000
	s_nop 0
	global_load_lds_dwordx4 v[210:211], off
	v_lshl_add_u64 v[210:211], v[216:217], 0, v[210:211]
	v_mfma_f32_32x32x16_bf16 v[48:63], v[162:165], v[200:203], v[48:63]
	s_add_u32 m0, s14, 0x10000
	s_nop 0
	global_load_lds_dwordx4 v[212:213], off
	v_lshl_add_u64 v[212:213], v[216:217], 0, v[212:213]
	v_mfma_f32_32x32x16_bf16 v[32:47], v[166:169], v[200:203], v[32:47]
	s_add_u32 m0, s14, 0x11000
	s_nop 0
	global_load_lds_dwordx4 v[214:215], off
	v_lshl_add_u64 v[214:215], v[216:217], 0, v[214:215]
	v_mfma_f32_32x32x16_bf16 v[16:31], v[170:173], v[200:203], v[16:31]
	v_mfma_f32_32x32x16_bf16 v[0:15], v[174:177], v[200:203], v[0:15]
	s_waitcnt lgkmcnt(4)
	v_mfma_f32_32x32x16_bf16 v[112:127], v[128:131], v[144:147], v[112:127]
	s_waitcnt lgkmcnt(3)
	v_mfma_f32_32x32x16_bf16 v[96:111], v[132:135], v[144:147], v[96:111]
	s_waitcnt lgkmcnt(1)
	v_mfma_f32_32x32x16_bf16 v[80:95], v[136:139], v[144:147], v[80:95]
	s_waitcnt lgkmcnt(0)
	v_mfma_f32_32x32x16_bf16 v[64:79], v[140:143], v[144:147], v[64:79]
	v_mfma_f32_32x32x16_bf16 v[48:63], v[128:131], v[148:151], v[48:63]
	v_mfma_f32_32x32x16_bf16 v[32:47], v[132:135], v[148:151], v[32:47]
	v_mfma_f32_32x32x16_bf16 v[16:31], v[136:139], v[148:151], v[16:31]
	v_mfma_f32_32x32x16_bf16 v[0:15], v[140:143], v[148:151], v[0:15]
	s_waitcnt vmcnt(6)
	s_waitcnt lgkmcnt(0)
	s_barrier
	ds_read_b128 v[162:165], v159 offset:32768
	ds_read_b128 v[178:181], v158 offset:24576
	ds_read_b128 v[166:169], v159 offset:34816
	ds_read_b128 v[200:203], v158 offset:26624
	ds_read_b128 v[170:173], v159 offset:36864
	ds_read_b128 v[174:177], v159 offset:38912
	ds_read_b128 v[128:131], v157 offset:32768
	ds_read_b128 v[144:147], v160 offset:24576
	ds_read_b128 v[132:135], v157 offset:34816
	ds_read_b128 v[148:151], v160 offset:26624
	ds_read_b128 v[136:139], v157 offset:36864
	ds_read_b128 v[140:143], v157 offset:38912
	s_waitcnt lgkmcnt(10)
	v_mfma_f32_32x32x16_bf16 v[112:127], v[162:165], v[178:181], v[112:127]
	s_mov_b32 m0, s14
	s_nop 0
	global_load_lds_dwordx4 v[204:205], off
	v_lshl_add_u64 v[204:205], v[216:217], 0, v[204:205]
	s_waitcnt lgkmcnt(9)
	v_mfma_f32_32x32x16_bf16 v[96:111], v[166:169], v[178:181], v[96:111]
	s_add_u32 m0, s14, 0x1000
	s_nop 0
	global_load_lds_dwordx4 v[206:207], off
	v_lshl_add_u64 v[206:207], v[216:217], 0, v[206:207]
	s_waitcnt lgkmcnt(7)
	v_mfma_f32_32x32x16_bf16 v[80:95], v[170:173], v[178:181], v[80:95]
	s_add_u32 m0, s14, 0x2000
	s_nop 0
	global_load_lds_dwordx4 v[208:209], off
	v_lshl_add_u64 v[208:209], v[216:217], 0, v[208:209]
	s_waitcnt lgkmcnt(6)
	v_mfma_f32_32x32x16_bf16 v[64:79], v[174:177], v[178:181], v[64:79]
	s_add_u32 m0, s14, 0x3000
	s_nop 0
	global_load_lds_dwordx4 v[210:211], off
	v_lshl_add_u64 v[210:211], v[216:217], 0, v[210:211]
	v_mfma_f32_32x32x16_bf16 v[48:63], v[162:165], v[200:203], v[48:63]
	s_add_u32 m0, s14, 0x4000
	s_nop 0
	global_load_lds_dwordx4 v[212:213], off
	v_lshl_add_u64 v[212:213], v[216:217], 0, v[212:213]
	v_mfma_f32_32x32x16_bf16 v[32:47], v[166:169], v[200:203], v[32:47]
	s_add_u32 m0, s14, 0x5000
	s_nop 0
	global_load_lds_dwordx4 v[214:215], off
	v_lshl_add_u64 v[214:215], v[216:217], 0, v[214:215]
	v_mfma_f32_32x32x16_bf16 v[16:31], v[170:173], v[200:203], v[16:31]
	v_mfma_f32_32x32x16_bf16 v[0:15], v[174:177], v[200:203], v[0:15]
	s_waitcnt lgkmcnt(4)
	v_mfma_f32_32x32x16_bf16 v[112:127], v[128:131], v[144:147], v[112:127]
	s_waitcnt lgkmcnt(3)
	v_mfma_f32_32x32x16_bf16 v[96:111], v[132:135], v[144:147], v[96:111]
	s_waitcnt lgkmcnt(1)
	v_mfma_f32_32x32x16_bf16 v[80:95], v[136:139], v[144:147], v[80:95]
	s_waitcnt lgkmcnt(0)
	v_mfma_f32_32x32x16_bf16 v[64:79], v[140:143], v[144:147], v[64:79]
	v_mfma_f32_32x32x16_bf16 v[48:63], v[128:131], v[148:151], v[48:63]
	v_mfma_f32_32x32x16_bf16 v[32:47], v[132:135], v[148:151], v[32:47]
	v_mfma_f32_32x32x16_bf16 v[16:31], v[136:139], v[148:151], v[16:31]
	v_mfma_f32_32x32x16_bf16 v[0:15], v[140:143], v[148:151], v[0:15]
	s_waitcnt vmcnt(6)
	s_waitcnt lgkmcnt(0)
	s_barrier
	ds_read_b128 v[162:165], v159 offset:57344
	ds_read_b128 v[178:181], v158 offset:49152
	ds_read_b128 v[166:169], v159 offset:59392
	ds_read_b128 v[200:203], v158 offset:51200
	ds_read_b128 v[170:173], v159 offset:61440
	ds_read_b128 v[174:177], v159 offset:63488
	ds_read_b128 v[128:131], v157 offset:57344
	ds_read_b128 v[144:147], v160 offset:49152
	ds_read_b128 v[132:135], v157 offset:59392
	ds_read_b128 v[148:151], v160 offset:51200
	ds_read_b128 v[136:139], v157 offset:61440
	ds_read_b128 v[140:143], v157 offset:63488
	s_waitcnt lgkmcnt(10)
	v_mfma_f32_32x32x16_bf16 v[112:127], v[162:165], v[178:181], v[112:127]
	s_add_u32 m0, s14, 0x6000
	s_nop 0
	global_load_lds_dwordx4 v[204:205], off
	v_lshl_add_u64 v[204:205], v[216:217], 0, v[204:205]
	s_waitcnt lgkmcnt(9)
	v_mfma_f32_32x32x16_bf16 v[96:111], v[166:169], v[178:181], v[96:111]
	s_add_u32 m0, s14, 0x7000
	s_nop 0
	global_load_lds_dwordx4 v[206:207], off
	v_lshl_add_u64 v[206:207], v[216:217], 0, v[206:207]
	s_waitcnt lgkmcnt(7)
	v_mfma_f32_32x32x16_bf16 v[80:95], v[170:173], v[178:181], v[80:95]
	s_add_u32 m0, s14, 0x8000
	s_nop 0
	global_load_lds_dwordx4 v[208:209], off
	v_lshl_add_u64 v[208:209], v[216:217], 0, v[208:209]
	s_waitcnt lgkmcnt(6)
	v_mfma_f32_32x32x16_bf16 v[64:79], v[174:177], v[178:181], v[64:79]
	s_add_u32 m0, s14, 0x9000
	s_nop 0
	global_load_lds_dwordx4 v[210:211], off
	v_lshl_add_u64 v[210:211], v[216:217], 0, v[210:211]
	v_mfma_f32_32x32x16_bf16 v[48:63], v[162:165], v[200:203], v[48:63]
	s_add_u32 m0, s14, 0xa000
	s_nop 0
	global_load_lds_dwordx4 v[212:213], off
	v_lshl_add_u64 v[212:213], v[216:217], 0, v[212:213]
	v_mfma_f32_32x32x16_bf16 v[32:47], v[166:169], v[200:203], v[32:47]
	s_add_u32 m0, s14, 0xb000
	s_nop 0
	global_load_lds_dwordx4 v[214:215], off
	v_lshl_add_u64 v[214:215], v[216:217], 0, v[214:215]
	v_mfma_f32_32x32x16_bf16 v[16:31], v[170:173], v[200:203], v[16:31]
	v_mfma_f32_32x32x16_bf16 v[0:15], v[174:177], v[200:203], v[0:15]
	s_waitcnt lgkmcnt(4)
	v_mfma_f32_32x32x16_bf16 v[112:127], v[128:131], v[144:147], v[112:127]
	s_waitcnt lgkmcnt(3)
	v_mfma_f32_32x32x16_bf16 v[96:111], v[132:135], v[144:147], v[96:111]
	s_waitcnt lgkmcnt(1)
	v_mfma_f32_32x32x16_bf16 v[80:95], v[136:139], v[144:147], v[80:95]
	s_waitcnt lgkmcnt(0)
	v_mfma_f32_32x32x16_bf16 v[64:79], v[140:143], v[144:147], v[64:79]
	v_mfma_f32_32x32x16_bf16 v[48:63], v[128:131], v[148:151], v[48:63]
	v_mfma_f32_32x32x16_bf16 v[32:47], v[132:135], v[148:151], v[32:47]
	v_mfma_f32_32x32x16_bf16 v[16:31], v[136:139], v[148:151], v[16:31]
	v_mfma_f32_32x32x16_bf16 v[0:15], v[140:143], v[148:151], v[0:15]
	s_waitcnt vmcnt(6)
	s_waitcnt lgkmcnt(0)
	s_barrier
	ds_read_b128 v[162:165], v159 offset:8192
	ds_read_b128 v[178:181], v158
	ds_read_b128 v[166:169], v159 offset:10240
	ds_read_b128 v[200:203], v158 offset:2048
	ds_read_b128 v[170:173], v159 offset:12288
	ds_read_b128 v[174:177], v159 offset:14336
	ds_read_b128 v[128:131], v157 offset:8192
	ds_read_b128 v[144:147], v160
	ds_read_b128 v[132:135], v157 offset:10240
	ds_read_b128 v[148:151], v160 offset:2048
	ds_read_b128 v[136:139], v157 offset:12288
	ds_read_b128 v[140:143], v157 offset:14336
	s_waitcnt lgkmcnt(10)
	v_mfma_f32_32x32x16_bf16 v[112:127], v[162:165], v[178:181], v[112:127]
	s_add_u32 m0, s14, 0xc000
	s_nop 0
	global_load_lds_dwordx4 v[204:205], off
	v_lshl_add_u64 v[204:205], v[216:217], 0, v[204:205]
	s_waitcnt lgkmcnt(9)
	v_mfma_f32_32x32x16_bf16 v[96:111], v[166:169], v[178:181], v[96:111]
	s_add_u32 m0, s14, 0xd000
	s_nop 0
	global_load_lds_dwordx4 v[206:207], off
	v_lshl_add_u64 v[206:207], v[216:217], 0, v[206:207]
	s_waitcnt lgkmcnt(7)
	v_mfma_f32_32x32x16_bf16 v[80:95], v[170:173], v[178:181], v[80:95]
	s_add_u32 m0, s14, 0xe000
	s_nop 0
	global_load_lds_dwordx4 v[208:209], off
	v_lshl_add_u64 v[208:209], v[216:217], 0, v[208:209]
	s_waitcnt lgkmcnt(6)
	v_mfma_f32_32x32x16_bf16 v[64:79], v[174:177], v[178:181], v[64:79]
	s_add_u32 m0, s14, 0xf000
	s_nop 0
	global_load_lds_dwordx4 v[210:211], off
	v_lshl_add_u64 v[210:211], v[216:217], 0, v[210:211]
	v_mfma_f32_32x32x16_bf16 v[48:63], v[162:165], v[200:203], v[48:63]
	s_add_u32 m0, s14, 0x10000
	s_nop 0
	global_load_lds_dwordx4 v[212:213], off
	v_lshl_add_u64 v[212:213], v[216:217], 0, v[212:213]
	v_mfma_f32_32x32x16_bf16 v[32:47], v[166:169], v[200:203], v[32:47]
	s_add_u32 m0, s14, 0x11000
	s_nop 0
	global_load_lds_dwordx4 v[214:215], off
	v_lshl_add_u64 v[214:215], v[216:217], 0, v[214:215]
	v_mfma_f32_32x32x16_bf16 v[16:31], v[170:173], v[200:203], v[16:31]
	v_mfma_f32_32x32x16_bf16 v[0:15], v[174:177], v[200:203], v[0:15]
	s_waitcnt lgkmcnt(4)
	v_mfma_f32_32x32x16_bf16 v[112:127], v[128:131], v[144:147], v[112:127]
	s_waitcnt lgkmcnt(3)
	v_mfma_f32_32x32x16_bf16 v[96:111], v[132:135], v[144:147], v[96:111]
	s_waitcnt lgkmcnt(1)
	v_mfma_f32_32x32x16_bf16 v[80:95], v[136:139], v[144:147], v[80:95]
	s_waitcnt lgkmcnt(0)
	v_mfma_f32_32x32x16_bf16 v[64:79], v[140:143], v[144:147], v[64:79]
	v_mfma_f32_32x32x16_bf16 v[48:63], v[128:131], v[148:151], v[48:63]
	v_mfma_f32_32x32x16_bf16 v[32:47], v[132:135], v[148:151], v[32:47]
	v_mfma_f32_32x32x16_bf16 v[16:31], v[136:139], v[148:151], v[16:31]
	v_mfma_f32_32x32x16_bf16 v[0:15], v[140:143], v[148:151], v[0:15]
	s_waitcnt vmcnt(6)
	s_waitcnt lgkmcnt(0)
	s_barrier
	ds_read_b128 v[162:165], v159 offset:32768
	ds_read_b128 v[178:181], v158 offset:24576
	ds_read_b128 v[166:169], v159 offset:34816
	ds_read_b128 v[200:203], v158 offset:26624
	ds_read_b128 v[170:173], v159 offset:36864
	ds_read_b128 v[174:177], v159 offset:38912
	ds_read_b128 v[128:131], v157 offset:32768
	ds_read_b128 v[144:147], v160 offset:24576
	ds_read_b128 v[132:135], v157 offset:34816
	ds_read_b128 v[148:151], v160 offset:26624
	ds_read_b128 v[136:139], v157 offset:36864
	ds_read_b128 v[140:143], v157 offset:38912
	s_waitcnt lgkmcnt(10)
	v_mfma_f32_32x32x16_bf16 v[112:127], v[162:165], v[178:181], v[112:127]
	s_mov_b32 m0, s14
	s_nop 0
	global_load_lds_dwordx4 v[204:205], off
	v_lshl_add_u64 v[204:205], v[216:217], 0, v[204:205]
	s_waitcnt lgkmcnt(9)
	v_mfma_f32_32x32x16_bf16 v[96:111], v[166:169], v[178:181], v[96:111]
	s_add_u32 m0, s14, 0x1000
	s_nop 0
	global_load_lds_dwordx4 v[206:207], off
	v_lshl_add_u64 v[206:207], v[216:217], 0, v[206:207]
	s_waitcnt lgkmcnt(7)
	v_mfma_f32_32x32x16_bf16 v[80:95], v[170:173], v[178:181], v[80:95]
	s_add_u32 m0, s14, 0x2000
	s_nop 0
	global_load_lds_dwordx4 v[208:209], off
	v_lshl_add_u64 v[208:209], v[216:217], 0, v[208:209]
	s_waitcnt lgkmcnt(6)
	v_mfma_f32_32x32x16_bf16 v[64:79], v[174:177], v[178:181], v[64:79]
	s_add_u32 m0, s14, 0x3000
	s_nop 0
	global_load_lds_dwordx4 v[210:211], off
	v_lshl_add_u64 v[210:211], v[216:217], 0, v[210:211]
	v_mfma_f32_32x32x16_bf16 v[48:63], v[162:165], v[200:203], v[48:63]
	s_add_u32 m0, s14, 0x4000
	s_nop 0
	global_load_lds_dwordx4 v[212:213], off
	v_lshl_add_u64 v[212:213], v[216:217], 0, v[212:213]
	v_mfma_f32_32x32x16_bf16 v[32:47], v[166:169], v[200:203], v[32:47]
	s_add_u32 m0, s14, 0x5000
	s_nop 0
	global_load_lds_dwordx4 v[214:215], off
	v_lshl_add_u64 v[214:215], v[216:217], 0, v[214:215]
	v_mfma_f32_32x32x16_bf16 v[16:31], v[170:173], v[200:203], v[16:31]
	v_mfma_f32_32x32x16_bf16 v[0:15], v[174:177], v[200:203], v[0:15]
	s_waitcnt lgkmcnt(4)
	v_mfma_f32_32x32x16_bf16 v[112:127], v[128:131], v[144:147], v[112:127]
	s_waitcnt lgkmcnt(3)
	v_mfma_f32_32x32x16_bf16 v[96:111], v[132:135], v[144:147], v[96:111]
	s_waitcnt lgkmcnt(1)
	v_mfma_f32_32x32x16_bf16 v[80:95], v[136:139], v[144:147], v[80:95]
	s_waitcnt lgkmcnt(0)
	v_mfma_f32_32x32x16_bf16 v[64:79], v[140:143], v[144:147], v[64:79]
	v_mfma_f32_32x32x16_bf16 v[48:63], v[128:131], v[148:151], v[48:63]
	v_mfma_f32_32x32x16_bf16 v[32:47], v[132:135], v[148:151], v[32:47]
	v_mfma_f32_32x32x16_bf16 v[16:31], v[136:139], v[148:151], v[16:31]
	v_mfma_f32_32x32x16_bf16 v[0:15], v[140:143], v[148:151], v[0:15]
	s_waitcnt vmcnt(6)
	s_waitcnt lgkmcnt(0)
	s_barrier
	ds_read_b128 v[162:165], v159 offset:57344
	ds_read_b128 v[178:181], v158 offset:49152
	ds_read_b128 v[166:169], v159 offset:59392
	ds_read_b128 v[200:203], v158 offset:51200
	ds_read_b128 v[170:173], v159 offset:61440
	ds_read_b128 v[174:177], v159 offset:63488
	ds_read_b128 v[128:131], v157 offset:57344
	ds_read_b128 v[144:147], v160 offset:49152
	ds_read_b128 v[132:135], v157 offset:59392
	ds_read_b128 v[148:151], v160 offset:51200
	ds_read_b128 v[136:139], v157 offset:61440
	ds_read_b128 v[140:143], v157 offset:63488
	s_waitcnt lgkmcnt(10)
	v_mfma_f32_32x32x16_bf16 v[112:127], v[162:165], v[178:181], v[112:127]
	s_add_u32 m0, s14, 0x6000
	s_nop 0
	global_load_lds_dwordx4 v[204:205], off
	v_lshl_add_u64 v[204:205], v[216:217], 0, v[204:205]
	s_waitcnt lgkmcnt(9)
	v_mfma_f32_32x32x16_bf16 v[96:111], v[166:169], v[178:181], v[96:111]
	s_add_u32 m0, s14, 0x7000
	s_nop 0
	global_load_lds_dwordx4 v[206:207], off
	v_lshl_add_u64 v[206:207], v[216:217], 0, v[206:207]
	s_waitcnt lgkmcnt(7)
	v_mfma_f32_32x32x16_bf16 v[80:95], v[170:173], v[178:181], v[80:95]
	s_add_u32 m0, s14, 0x8000
	s_nop 0
	global_load_lds_dwordx4 v[208:209], off
	v_lshl_add_u64 v[208:209], v[216:217], 0, v[208:209]
	s_waitcnt lgkmcnt(6)
	v_mfma_f32_32x32x16_bf16 v[64:79], v[174:177], v[178:181], v[64:79]
	s_add_u32 m0, s14, 0x9000
	s_nop 0
	global_load_lds_dwordx4 v[210:211], off
	v_lshl_add_u64 v[210:211], v[216:217], 0, v[210:211]
	v_mfma_f32_32x32x16_bf16 v[48:63], v[162:165], v[200:203], v[48:63]
	s_add_u32 m0, s14, 0xa000
	s_nop 0
	global_load_lds_dwordx4 v[212:213], off
	v_lshl_add_u64 v[212:213], v[216:217], 0, v[212:213]
	v_mfma_f32_32x32x16_bf16 v[32:47], v[166:169], v[200:203], v[32:47]
	s_add_u32 m0, s14, 0xb000
	s_nop 0
	global_load_lds_dwordx4 v[214:215], off
	v_lshl_add_u64 v[214:215], v[216:217], 0, v[214:215]
	v_mfma_f32_32x32x16_bf16 v[16:31], v[170:173], v[200:203], v[16:31]
	v_mfma_f32_32x32x16_bf16 v[0:15], v[174:177], v[200:203], v[0:15]
	s_waitcnt lgkmcnt(4)
	v_mfma_f32_32x32x16_bf16 v[112:127], v[128:131], v[144:147], v[112:127]
	s_waitcnt lgkmcnt(3)
	v_mfma_f32_32x32x16_bf16 v[96:111], v[132:135], v[144:147], v[96:111]
	s_waitcnt lgkmcnt(1)
	v_mfma_f32_32x32x16_bf16 v[80:95], v[136:139], v[144:147], v[80:95]
	s_waitcnt lgkmcnt(0)
	v_mfma_f32_32x32x16_bf16 v[64:79], v[140:143], v[144:147], v[64:79]
	v_mfma_f32_32x32x16_bf16 v[48:63], v[128:131], v[148:151], v[48:63]
	v_mfma_f32_32x32x16_bf16 v[32:47], v[132:135], v[148:151], v[32:47]
	v_mfma_f32_32x32x16_bf16 v[16:31], v[136:139], v[148:151], v[16:31]
	v_mfma_f32_32x32x16_bf16 v[0:15], v[140:143], v[148:151], v[0:15]
	s_waitcnt vmcnt(6)
	s_waitcnt lgkmcnt(0)
	s_barrier
	ds_read_b128 v[162:165], v159 offset:8192
	ds_read_b128 v[178:181], v158
	ds_read_b128 v[166:169], v159 offset:10240
	ds_read_b128 v[200:203], v158 offset:2048
	ds_read_b128 v[170:173], v159 offset:12288
	ds_read_b128 v[174:177], v159 offset:14336
	ds_read_b128 v[128:131], v157 offset:8192
	ds_read_b128 v[144:147], v160
	ds_read_b128 v[132:135], v157 offset:10240
	ds_read_b128 v[148:151], v160 offset:2048
	ds_read_b128 v[136:139], v157 offset:12288
	ds_read_b128 v[140:143], v157 offset:14336
	s_waitcnt lgkmcnt(10)
	v_mfma_f32_32x32x16_bf16 v[112:127], v[162:165], v[178:181], v[112:127]
	s_add_u32 m0, s14, 0xc000
	s_nop 0
	global_load_lds_dwordx4 v[204:205], off
	v_lshl_add_u64 v[204:205], v[216:217], 0, v[204:205]
	s_waitcnt lgkmcnt(9)
	v_mfma_f32_32x32x16_bf16 v[96:111], v[166:169], v[178:181], v[96:111]
	s_add_u32 m0, s14, 0xd000
	s_nop 0
	global_load_lds_dwordx4 v[206:207], off
	v_lshl_add_u64 v[206:207], v[216:217], 0, v[206:207]
	s_waitcnt lgkmcnt(7)
	v_mfma_f32_32x32x16_bf16 v[80:95], v[170:173], v[178:181], v[80:95]
	s_add_u32 m0, s14, 0xe000
	s_nop 0
	global_load_lds_dwordx4 v[208:209], off
	v_lshl_add_u64 v[208:209], v[216:217], 0, v[208:209]
	s_waitcnt lgkmcnt(6)
	v_mfma_f32_32x32x16_bf16 v[64:79], v[174:177], v[178:181], v[64:79]
	s_add_u32 m0, s14, 0xf000
	s_nop 0
	global_load_lds_dwordx4 v[210:211], off
	v_lshl_add_u64 v[210:211], v[216:217], 0, v[210:211]
	v_mfma_f32_32x32x16_bf16 v[48:63], v[162:165], v[200:203], v[48:63]
	s_add_u32 m0, s14, 0x10000
	s_nop 0
	global_load_lds_dwordx4 v[212:213], off
	v_lshl_add_u64 v[212:213], v[216:217], 0, v[212:213]
	v_mfma_f32_32x32x16_bf16 v[32:47], v[166:169], v[200:203], v[32:47]
	s_add_u32 m0, s14, 0x11000
	s_nop 0
	global_load_lds_dwordx4 v[214:215], off
	v_lshl_add_u64 v[214:215], v[216:217], 0, v[214:215]
	v_mfma_f32_32x32x16_bf16 v[16:31], v[170:173], v[200:203], v[16:31]
	v_mfma_f32_32x32x16_bf16 v[0:15], v[174:177], v[200:203], v[0:15]
	s_waitcnt lgkmcnt(4)
	v_mfma_f32_32x32x16_bf16 v[112:127], v[128:131], v[144:147], v[112:127]
	s_waitcnt lgkmcnt(3)
	v_mfma_f32_32x32x16_bf16 v[96:111], v[132:135], v[144:147], v[96:111]
	s_waitcnt lgkmcnt(1)
	v_mfma_f32_32x32x16_bf16 v[80:95], v[136:139], v[144:147], v[80:95]
	s_waitcnt lgkmcnt(0)
	v_mfma_f32_32x32x16_bf16 v[64:79], v[140:143], v[144:147], v[64:79]
	v_mfma_f32_32x32x16_bf16 v[48:63], v[128:131], v[148:151], v[48:63]
	v_mfma_f32_32x32x16_bf16 v[32:47], v[132:135], v[148:151], v[32:47]
	v_mfma_f32_32x32x16_bf16 v[16:31], v[136:139], v[148:151], v[16:31]
	v_mfma_f32_32x32x16_bf16 v[0:15], v[140:143], v[148:151], v[0:15]
	s_waitcnt vmcnt(6)
	s_waitcnt lgkmcnt(0)
	s_barrier
	ds_read_b128 v[162:165], v159 offset:32768
	ds_read_b128 v[178:181], v158 offset:24576
	ds_read_b128 v[166:169], v159 offset:34816
	ds_read_b128 v[200:203], v158 offset:26624
	ds_read_b128 v[170:173], v159 offset:36864
	ds_read_b128 v[174:177], v159 offset:38912
	ds_read_b128 v[128:131], v157 offset:32768
	ds_read_b128 v[144:147], v160 offset:24576
	ds_read_b128 v[132:135], v157 offset:34816
	ds_read_b128 v[148:151], v160 offset:26624
	ds_read_b128 v[136:139], v157 offset:36864
	ds_read_b128 v[140:143], v157 offset:38912
	s_waitcnt lgkmcnt(10)
	v_mfma_f32_32x32x16_bf16 v[112:127], v[162:165], v[178:181], v[112:127]
	s_mov_b32 m0, s14
	s_nop 0
	global_load_lds_dwordx4 v[204:205], off
	v_lshl_add_u64 v[204:205], v[216:217], 0, v[204:205]
	s_waitcnt lgkmcnt(9)
	v_mfma_f32_32x32x16_bf16 v[96:111], v[166:169], v[178:181], v[96:111]
	s_add_u32 m0, s14, 0x1000
	s_nop 0
	global_load_lds_dwordx4 v[206:207], off
	v_lshl_add_u64 v[206:207], v[216:217], 0, v[206:207]
	s_waitcnt lgkmcnt(7)
	v_mfma_f32_32x32x16_bf16 v[80:95], v[170:173], v[178:181], v[80:95]
	s_add_u32 m0, s14, 0x2000
	s_nop 0
	global_load_lds_dwordx4 v[208:209], off
	v_lshl_add_u64 v[208:209], v[216:217], 0, v[208:209]
	s_waitcnt lgkmcnt(6)
	v_mfma_f32_32x32x16_bf16 v[64:79], v[174:177], v[178:181], v[64:79]
	s_add_u32 m0, s14, 0x3000
	s_nop 0
	global_load_lds_dwordx4 v[210:211], off
	v_lshl_add_u64 v[210:211], v[216:217], 0, v[210:211]
	v_mfma_f32_32x32x16_bf16 v[48:63], v[162:165], v[200:203], v[48:63]
	s_add_u32 m0, s14, 0x4000
	s_nop 0
	global_load_lds_dwordx4 v[212:213], off
	v_lshl_add_u64 v[212:213], v[216:217], 0, v[212:213]
	v_mfma_f32_32x32x16_bf16 v[32:47], v[166:169], v[200:203], v[32:47]
	s_add_u32 m0, s14, 0x5000
	s_nop 0
	global_load_lds_dwordx4 v[214:215], off
	v_lshl_add_u64 v[214:215], v[216:217], 0, v[214:215]
	v_mfma_f32_32x32x16_bf16 v[16:31], v[170:173], v[200:203], v[16:31]
	v_mfma_f32_32x32x16_bf16 v[0:15], v[174:177], v[200:203], v[0:15]
	s_waitcnt lgkmcnt(4)
	v_mfma_f32_32x32x16_bf16 v[112:127], v[128:131], v[144:147], v[112:127]
	s_waitcnt lgkmcnt(3)
	v_mfma_f32_32x32x16_bf16 v[96:111], v[132:135], v[144:147], v[96:111]
	s_waitcnt lgkmcnt(1)
	v_mfma_f32_32x32x16_bf16 v[80:95], v[136:139], v[144:147], v[80:95]
	s_waitcnt lgkmcnt(0)
	v_mfma_f32_32x32x16_bf16 v[64:79], v[140:143], v[144:147], v[64:79]
	v_mfma_f32_32x32x16_bf16 v[48:63], v[128:131], v[148:151], v[48:63]
	v_mfma_f32_32x32x16_bf16 v[32:47], v[132:135], v[148:151], v[32:47]
	v_mfma_f32_32x32x16_bf16 v[16:31], v[136:139], v[148:151], v[16:31]
	v_mfma_f32_32x32x16_bf16 v[0:15], v[140:143], v[148:151], v[0:15]
	s_waitcnt vmcnt(6)
	s_waitcnt lgkmcnt(0)
	s_barrier
	ds_read_b128 v[162:165], v159 offset:57344
	ds_read_b128 v[178:181], v158 offset:49152
	ds_read_b128 v[166:169], v159 offset:59392
	ds_read_b128 v[200:203], v158 offset:51200
	ds_read_b128 v[170:173], v159 offset:61440
	ds_read_b128 v[174:177], v159 offset:63488
	ds_read_b128 v[128:131], v157 offset:57344
	ds_read_b128 v[144:147], v160 offset:49152
	ds_read_b128 v[132:135], v157 offset:59392
	ds_read_b128 v[148:151], v160 offset:51200
	ds_read_b128 v[136:139], v157 offset:61440
	ds_read_b128 v[140:143], v157 offset:63488
	s_waitcnt lgkmcnt(10)
	v_mfma_f32_32x32x16_bf16 v[112:127], v[162:165], v[178:181], v[112:127]
	s_add_u32 m0, s14, 0x6000
	s_nop 0
	global_load_lds_dwordx4 v[204:205], off
	v_lshl_add_u64 v[204:205], v[216:217], 0, v[204:205]
	s_waitcnt lgkmcnt(9)
	v_mfma_f32_32x32x16_bf16 v[96:111], v[166:169], v[178:181], v[96:111]
	s_add_u32 m0, s14, 0x7000
	s_nop 0
	global_load_lds_dwordx4 v[206:207], off
	v_lshl_add_u64 v[206:207], v[216:217], 0, v[206:207]
	s_waitcnt lgkmcnt(7)
	v_mfma_f32_32x32x16_bf16 v[80:95], v[170:173], v[178:181], v[80:95]
	s_add_u32 m0, s14, 0x8000
	s_nop 0
	global_load_lds_dwordx4 v[208:209], off
	v_lshl_add_u64 v[208:209], v[216:217], 0, v[208:209]
	s_waitcnt lgkmcnt(6)
	v_mfma_f32_32x32x16_bf16 v[64:79], v[174:177], v[178:181], v[64:79]
	s_add_u32 m0, s14, 0x9000
	s_nop 0
	global_load_lds_dwordx4 v[210:211], off
	v_lshl_add_u64 v[210:211], v[216:217], 0, v[210:211]
	v_mfma_f32_32x32x16_bf16 v[48:63], v[162:165], v[200:203], v[48:63]
	s_add_u32 m0, s14, 0xa000
	s_nop 0
	global_load_lds_dwordx4 v[212:213], off
	v_lshl_add_u64 v[212:213], v[216:217], 0, v[212:213]
	v_mfma_f32_32x32x16_bf16 v[32:47], v[166:169], v[200:203], v[32:47]
	s_add_u32 m0, s14, 0xb000
	s_nop 0
	global_load_lds_dwordx4 v[214:215], off
	v_lshl_add_u64 v[214:215], v[216:217], 0, v[214:215]
	v_mfma_f32_32x32x16_bf16 v[16:31], v[170:173], v[200:203], v[16:31]
	v_mfma_f32_32x32x16_bf16 v[0:15], v[174:177], v[200:203], v[0:15]
	s_waitcnt lgkmcnt(4)
	v_mfma_f32_32x32x16_bf16 v[112:127], v[128:131], v[144:147], v[112:127]
	s_waitcnt lgkmcnt(3)
	v_mfma_f32_32x32x16_bf16 v[96:111], v[132:135], v[144:147], v[96:111]
	s_waitcnt lgkmcnt(1)
	v_mfma_f32_32x32x16_bf16 v[80:95], v[136:139], v[144:147], v[80:95]
	s_waitcnt lgkmcnt(0)
	v_mfma_f32_32x32x16_bf16 v[64:79], v[140:143], v[144:147], v[64:79]
	v_mfma_f32_32x32x16_bf16 v[48:63], v[128:131], v[148:151], v[48:63]
	v_mfma_f32_32x32x16_bf16 v[32:47], v[132:135], v[148:151], v[32:47]
	v_mfma_f32_32x32x16_bf16 v[16:31], v[136:139], v[148:151], v[16:31]
	v_mfma_f32_32x32x16_bf16 v[0:15], v[140:143], v[148:151], v[0:15]
	s_waitcnt vmcnt(6)
	s_waitcnt lgkmcnt(0)
	s_barrier
	ds_read_b128 v[162:165], v159 offset:8192
	ds_read_b128 v[178:181], v158
	ds_read_b128 v[166:169], v159 offset:10240
	ds_read_b128 v[200:203], v158 offset:2048
	ds_read_b128 v[170:173], v159 offset:12288
	ds_read_b128 v[174:177], v159 offset:14336
	ds_read_b128 v[128:131], v157 offset:8192
	ds_read_b128 v[144:147], v160
	ds_read_b128 v[132:135], v157 offset:10240
	ds_read_b128 v[148:151], v160 offset:2048
	ds_read_b128 v[136:139], v157 offset:12288
	ds_read_b128 v[140:143], v157 offset:14336
	s_waitcnt lgkmcnt(10)
	v_mfma_f32_32x32x16_bf16 v[112:127], v[162:165], v[178:181], v[112:127]
	s_add_u32 m0, s14, 0xc000
	s_nop 0
	global_load_lds_dwordx4 v[204:205], off
	v_lshl_add_u64 v[204:205], v[216:217], 0, v[204:205]
	s_waitcnt lgkmcnt(9)
	v_mfma_f32_32x32x16_bf16 v[96:111], v[166:169], v[178:181], v[96:111]
	s_add_u32 m0, s14, 0xd000
	s_nop 0
	global_load_lds_dwordx4 v[206:207], off
	v_lshl_add_u64 v[206:207], v[216:217], 0, v[206:207]
	s_waitcnt lgkmcnt(7)
	v_mfma_f32_32x32x16_bf16 v[80:95], v[170:173], v[178:181], v[80:95]
	s_add_u32 m0, s14, 0xe000
	s_nop 0
	global_load_lds_dwordx4 v[208:209], off
	v_lshl_add_u64 v[208:209], v[216:217], 0, v[208:209]
	s_waitcnt lgkmcnt(6)
	v_mfma_f32_32x32x16_bf16 v[64:79], v[174:177], v[178:181], v[64:79]
	s_add_u32 m0, s14, 0xf000
	s_nop 0
	global_load_lds_dwordx4 v[210:211], off
	v_lshl_add_u64 v[210:211], v[216:217], 0, v[210:211]
	v_mfma_f32_32x32x16_bf16 v[48:63], v[162:165], v[200:203], v[48:63]
	s_add_u32 m0, s14, 0x10000
	s_nop 0
	global_load_lds_dwordx4 v[212:213], off
	v_lshl_add_u64 v[212:213], v[216:217], 0, v[212:213]
	v_mfma_f32_32x32x16_bf16 v[32:47], v[166:169], v[200:203], v[32:47]
	s_add_u32 m0, s14, 0x11000
	s_nop 0
	global_load_lds_dwordx4 v[214:215], off
	v_lshl_add_u64 v[214:215], v[216:217], 0, v[214:215]
	v_mfma_f32_32x32x16_bf16 v[16:31], v[170:173], v[200:203], v[16:31]
	v_mfma_f32_32x32x16_bf16 v[0:15], v[174:177], v[200:203], v[0:15]
	s_waitcnt lgkmcnt(4)
	v_mfma_f32_32x32x16_bf16 v[112:127], v[128:131], v[144:147], v[112:127]
	s_waitcnt lgkmcnt(3)
	v_mfma_f32_32x32x16_bf16 v[96:111], v[132:135], v[144:147], v[96:111]
	s_waitcnt lgkmcnt(1)
	v_mfma_f32_32x32x16_bf16 v[80:95], v[136:139], v[144:147], v[80:95]
	s_waitcnt lgkmcnt(0)
	v_mfma_f32_32x32x16_bf16 v[64:79], v[140:143], v[144:147], v[64:79]
	v_mfma_f32_32x32x16_bf16 v[48:63], v[128:131], v[148:151], v[48:63]
	v_mfma_f32_32x32x16_bf16 v[32:47], v[132:135], v[148:151], v[32:47]
	v_mfma_f32_32x32x16_bf16 v[16:31], v[136:139], v[148:151], v[16:31]
	v_mfma_f32_32x32x16_bf16 v[0:15], v[140:143], v[148:151], v[0:15]
	s_waitcnt vmcnt(6)
	s_waitcnt lgkmcnt(0)
	s_barrier
	ds_read_b128 v[162:165], v159 offset:32768
	ds_read_b128 v[178:181], v158 offset:24576
	ds_read_b128 v[166:169], v159 offset:34816
	ds_read_b128 v[200:203], v158 offset:26624
	ds_read_b128 v[170:173], v159 offset:36864
	ds_read_b128 v[174:177], v159 offset:38912
	ds_read_b128 v[128:131], v157 offset:32768
	ds_read_b128 v[144:147], v160 offset:24576
	ds_read_b128 v[132:135], v157 offset:34816
	ds_read_b128 v[148:151], v160 offset:26624
	ds_read_b128 v[136:139], v157 offset:36864
	ds_read_b128 v[140:143], v157 offset:38912
	s_waitcnt lgkmcnt(10)
	v_mfma_f32_32x32x16_bf16 v[112:127], v[162:165], v[178:181], v[112:127]
	s_mov_b32 m0, s14
	s_nop 0
	global_load_lds_dwordx4 v[204:205], off
	v_lshl_add_u64 v[204:205], v[216:217], 0, v[204:205]
	s_waitcnt lgkmcnt(9)
	v_mfma_f32_32x32x16_bf16 v[96:111], v[166:169], v[178:181], v[96:111]
	s_add_u32 m0, s14, 0x1000
	s_nop 0
	global_load_lds_dwordx4 v[206:207], off
	v_lshl_add_u64 v[206:207], v[216:217], 0, v[206:207]
	s_waitcnt lgkmcnt(7)
	v_mfma_f32_32x32x16_bf16 v[80:95], v[170:173], v[178:181], v[80:95]
	s_add_u32 m0, s14, 0x2000
	s_nop 0
	global_load_lds_dwordx4 v[208:209], off
	v_lshl_add_u64 v[208:209], v[216:217], 0, v[208:209]
	s_waitcnt lgkmcnt(6)
	v_mfma_f32_32x32x16_bf16 v[64:79], v[174:177], v[178:181], v[64:79]
	s_add_u32 m0, s14, 0x3000
	s_nop 0
	global_load_lds_dwordx4 v[210:211], off
	v_lshl_add_u64 v[210:211], v[216:217], 0, v[210:211]
	v_mfma_f32_32x32x16_bf16 v[48:63], v[162:165], v[200:203], v[48:63]
	s_add_u32 m0, s14, 0x4000
	s_nop 0
	global_load_lds_dwordx4 v[212:213], off
	v_lshl_add_u64 v[212:213], v[216:217], 0, v[212:213]
	v_mfma_f32_32x32x16_bf16 v[32:47], v[166:169], v[200:203], v[32:47]
	s_add_u32 m0, s14, 0x5000
	s_nop 0
	global_load_lds_dwordx4 v[214:215], off
	v_lshl_add_u64 v[214:215], v[216:217], 0, v[214:215]
	v_mfma_f32_32x32x16_bf16 v[16:31], v[170:173], v[200:203], v[16:31]
	v_mfma_f32_32x32x16_bf16 v[0:15], v[174:177], v[200:203], v[0:15]
	s_waitcnt lgkmcnt(4)
	v_mfma_f32_32x32x16_bf16 v[112:127], v[128:131], v[144:147], v[112:127]
	s_waitcnt lgkmcnt(3)
	v_mfma_f32_32x32x16_bf16 v[96:111], v[132:135], v[144:147], v[96:111]
	s_waitcnt lgkmcnt(1)
	v_mfma_f32_32x32x16_bf16 v[80:95], v[136:139], v[144:147], v[80:95]
	s_waitcnt lgkmcnt(0)
	v_mfma_f32_32x32x16_bf16 v[64:79], v[140:143], v[144:147], v[64:79]
	v_mfma_f32_32x32x16_bf16 v[48:63], v[128:131], v[148:151], v[48:63]
	v_mfma_f32_32x32x16_bf16 v[32:47], v[132:135], v[148:151], v[32:47]
	v_mfma_f32_32x32x16_bf16 v[16:31], v[136:139], v[148:151], v[16:31]
	v_mfma_f32_32x32x16_bf16 v[0:15], v[140:143], v[148:151], v[0:15]
	s_waitcnt vmcnt(6)
	s_waitcnt lgkmcnt(0)
	s_barrier
	ds_read_b128 v[162:165], v159 offset:57344
	ds_read_b128 v[178:181], v158 offset:49152
	ds_read_b128 v[166:169], v159 offset:59392
	ds_read_b128 v[200:203], v158 offset:51200
	ds_read_b128 v[170:173], v159 offset:61440
	ds_read_b128 v[174:177], v159 offset:63488
	ds_read_b128 v[128:131], v157 offset:57344
	ds_read_b128 v[144:147], v160 offset:49152
	ds_read_b128 v[132:135], v157 offset:59392
	ds_read_b128 v[148:151], v160 offset:51200
	ds_read_b128 v[136:139], v157 offset:61440
	ds_read_b128 v[140:143], v157 offset:63488
	s_waitcnt lgkmcnt(10)
	v_mfma_f32_32x32x16_bf16 v[112:127], v[162:165], v[178:181], v[112:127]
	s_add_u32 m0, s14, 0x6000
	s_nop 0
	global_load_lds_dwordx4 v[204:205], off
	v_lshl_add_u64 v[204:205], v[216:217], 0, v[204:205]
	s_waitcnt lgkmcnt(9)
	v_mfma_f32_32x32x16_bf16 v[96:111], v[166:169], v[178:181], v[96:111]
	s_add_u32 m0, s14, 0x7000
	s_nop 0
	global_load_lds_dwordx4 v[206:207], off
	v_lshl_add_u64 v[206:207], v[216:217], 0, v[206:207]
	s_waitcnt lgkmcnt(7)
	v_mfma_f32_32x32x16_bf16 v[80:95], v[170:173], v[178:181], v[80:95]
	s_add_u32 m0, s14, 0x8000
	s_nop 0
	global_load_lds_dwordx4 v[208:209], off
	v_lshl_add_u64 v[208:209], v[216:217], 0, v[208:209]
	s_waitcnt lgkmcnt(6)
	v_mfma_f32_32x32x16_bf16 v[64:79], v[174:177], v[178:181], v[64:79]
	s_add_u32 m0, s14, 0x9000
	s_nop 0
	global_load_lds_dwordx4 v[210:211], off
	v_lshl_add_u64 v[210:211], v[216:217], 0, v[210:211]
	v_mfma_f32_32x32x16_bf16 v[48:63], v[162:165], v[200:203], v[48:63]
	s_add_u32 m0, s14, 0xa000
	s_nop 0
	global_load_lds_dwordx4 v[212:213], off
	v_lshl_add_u64 v[212:213], v[216:217], 0, v[212:213]
	v_mfma_f32_32x32x16_bf16 v[32:47], v[166:169], v[200:203], v[32:47]
	s_add_u32 m0, s14, 0xb000
	s_nop 0
	global_load_lds_dwordx4 v[214:215], off
	v_lshl_add_u64 v[214:215], v[216:217], 0, v[214:215]
	v_mfma_f32_32x32x16_bf16 v[16:31], v[170:173], v[200:203], v[16:31]
	v_mfma_f32_32x32x16_bf16 v[0:15], v[174:177], v[200:203], v[0:15]
	s_waitcnt lgkmcnt(4)
	v_mfma_f32_32x32x16_bf16 v[112:127], v[128:131], v[144:147], v[112:127]
	s_waitcnt lgkmcnt(3)
	v_mfma_f32_32x32x16_bf16 v[96:111], v[132:135], v[144:147], v[96:111]
	s_waitcnt lgkmcnt(1)
	v_mfma_f32_32x32x16_bf16 v[80:95], v[136:139], v[144:147], v[80:95]
	s_waitcnt lgkmcnt(0)
	v_mfma_f32_32x32x16_bf16 v[64:79], v[140:143], v[144:147], v[64:79]
	v_mfma_f32_32x32x16_bf16 v[48:63], v[128:131], v[148:151], v[48:63]
	v_mfma_f32_32x32x16_bf16 v[32:47], v[132:135], v[148:151], v[32:47]
	v_mfma_f32_32x32x16_bf16 v[16:31], v[136:139], v[148:151], v[16:31]
	v_mfma_f32_32x32x16_bf16 v[0:15], v[140:143], v[148:151], v[0:15]
	s_waitcnt vmcnt(6)
	s_waitcnt lgkmcnt(0)
	s_barrier
	ds_read_b128 v[162:165], v159 offset:8192
	ds_read_b128 v[178:181], v158
	ds_read_b128 v[166:169], v159 offset:10240
	ds_read_b128 v[200:203], v158 offset:2048
	ds_read_b128 v[170:173], v159 offset:12288
	ds_read_b128 v[174:177], v159 offset:14336
	ds_read_b128 v[128:131], v157 offset:8192
	ds_read_b128 v[144:147], v160
	ds_read_b128 v[132:135], v157 offset:10240
	ds_read_b128 v[148:151], v160 offset:2048
	ds_read_b128 v[136:139], v157 offset:12288
	ds_read_b128 v[140:143], v157 offset:14336
	s_waitcnt lgkmcnt(10)
	v_mfma_f32_32x32x16_bf16 v[112:127], v[162:165], v[178:181], v[112:127]
	s_waitcnt lgkmcnt(9)
	v_mfma_f32_32x32x16_bf16 v[96:111], v[166:169], v[178:181], v[96:111]
	s_waitcnt lgkmcnt(7)
	v_mfma_f32_32x32x16_bf16 v[80:95], v[170:173], v[178:181], v[80:95]
	s_waitcnt lgkmcnt(6)
	v_mfma_f32_32x32x16_bf16 v[64:79], v[174:177], v[178:181], v[64:79]
	v_mfma_f32_32x32x16_bf16 v[48:63], v[162:165], v[200:203], v[48:63]
	v_mfma_f32_32x32x16_bf16 v[32:47], v[166:169], v[200:203], v[32:47]
	v_mfma_f32_32x32x16_bf16 v[16:31], v[170:173], v[200:203], v[16:31]
	v_mfma_f32_32x32x16_bf16 v[0:15], v[174:177], v[200:203], v[0:15]
	s_waitcnt lgkmcnt(4)
	v_mfma_f32_32x32x16_bf16 v[112:127], v[128:131], v[144:147], v[112:127]
	s_waitcnt lgkmcnt(3)
	v_mfma_f32_32x32x16_bf16 v[96:111], v[132:135], v[144:147], v[96:111]
	s_waitcnt lgkmcnt(1)
	v_mfma_f32_32x32x16_bf16 v[80:95], v[136:139], v[144:147], v[80:95]
	s_waitcnt lgkmcnt(0)
	v_mfma_f32_32x32x16_bf16 v[64:79], v[140:143], v[144:147], v[64:79]
	v_mfma_f32_32x32x16_bf16 v[48:63], v[128:131], v[148:151], v[48:63]
	v_mfma_f32_32x32x16_bf16 v[32:47], v[132:135], v[148:151], v[32:47]
	v_mfma_f32_32x32x16_bf16 v[16:31], v[136:139], v[148:151], v[16:31]
	v_mfma_f32_32x32x16_bf16 v[0:15], v[140:143], v[148:151], v[0:15]
	s_waitcnt vmcnt(0)
	s_waitcnt lgkmcnt(0)
	s_barrier
	ds_read_b128 v[162:165], v159 offset:32768
	ds_read_b128 v[178:181], v158 offset:24576
	ds_read_b128 v[166:169], v159 offset:34816
	ds_read_b128 v[200:203], v158 offset:26624
	ds_read_b128 v[170:173], v159 offset:36864
	ds_read_b128 v[174:177], v159 offset:38912
	ds_read_b128 v[128:131], v157 offset:32768
	ds_read_b128 v[144:147], v160 offset:24576
	ds_read_b128 v[132:135], v157 offset:34816
	ds_read_b128 v[148:151], v160 offset:26624
	ds_read_b128 v[136:139], v157 offset:36864
	ds_read_b128 v[140:143], v157 offset:38912
	s_waitcnt lgkmcnt(10)
	v_mfma_f32_32x32x16_bf16 v[112:127], v[162:165], v[178:181], v[112:127]
	s_waitcnt lgkmcnt(9)
	v_mfma_f32_32x32x16_bf16 v[96:111], v[166:169], v[178:181], v[96:111]
	s_waitcnt lgkmcnt(7)
	v_mfma_f32_32x32x16_bf16 v[80:95], v[170:173], v[178:181], v[80:95]
	s_waitcnt lgkmcnt(6)
	v_mfma_f32_32x32x16_bf16 v[64:79], v[174:177], v[178:181], v[64:79]
	v_mfma_f32_32x32x16_bf16 v[48:63], v[162:165], v[200:203], v[48:63]
	v_mfma_f32_32x32x16_bf16 v[32:47], v[166:169], v[200:203], v[32:47]
	v_mfma_f32_32x32x16_bf16 v[16:31], v[170:173], v[200:203], v[16:31]
	v_mfma_f32_32x32x16_bf16 v[0:15], v[174:177], v[200:203], v[0:15]
	s_mov_b32 s14, 0xfffffc0
	s_movk_i32 s18, 0x210
	s_lshl_b64 s[4:5], s[4:5], 1
	s_mov_b32 s15, 0
	v_and_b32_e32 v152, 31, v156
	s_waitcnt lgkmcnt(0)
	s_barrier
	v_mfma_f32_32x32x16_bf16 v[48:63], v[128:131], v[148:151], v[48:63]
	v_mfma_f32_32x32x16_bf16 v[0:15], v[140:143], v[148:151], v[0:15]
	s_nop 10
	v_max_f32_e32 v48, v48, v48
	v_max_f32_e32 v49, v49, v49
	v_max_f32_e32 v50, v50, v50
	v_max_f32_e32 v51, v51, v51
	v_max_f32_e32 v52, v52, v52
	v_max_f32_e32 v53, v53, v53
	v_max_f32_e32 v48, 0, v48
	v_mfma_f32_32x32x16_bf16 v[112:127], v[128:131], v[144:147], v[112:127]
	v_lshrrev_b32_e32 v128, 1, v156
	v_lshrrev_b32_e32 v130, 2, v156
	v_and_or_b32 v129, v128, s14, v152
	v_lshlrev_b32_e32 v128, 2, v156
	v_and_b32_e32 v130, 8, v130
	s_movk_i32 s14, 0x100
	v_max_f32_e32 v0, v0, v0
	v_mfma_f32_32x32x16_bf16 v[96:111], v[132:135], v[144:147], v[96:111]
	v_max_f32_e32 v1, v1, v1
	v_max_f32_e32 v2, v2, v2
	v_max_f32_e32 v3, v3, v3
	v_max_f32_e32 v4, v4, v4
	v_max_f32_e32 v5, v5, v5
	v_max_f32_e32 v6, v6, v6
	v_max_f32_e32 v7, v7, v7
	v_mfma_f32_32x32x16_bf16 v[80:95], v[136:139], v[144:147], v[80:95]
	v_and_or_b32 v128, v128, s14, v130
	v_max_f32_e32 v49, 0, v49
	v_max_f32_e32 v50, 0, v50
	v_max_f32_e32 v51, 0, v51
	v_max_f32_e32 v52, 0, v52
	v_max_f32_e32 v53, 0, v53
	v_max_f32_e32 v0, 0, v0
	v_mfma_f32_32x32x16_bf16 v[64:79], v[140:143], v[144:147], v[64:79]
	v_max_f32_e32 v1, 0, v1
	v_max_f32_e32 v2, 0, v2
	v_max_f32_e32 v3, 0, v3
	v_max_f32_e32 v4, 0, v4
	v_max_f32_e32 v5, 0, v5
	v_max_f32_e32 v6, 0, v6
	v_max_f32_e32 v7, 0, v7
	v_mfma_f32_32x32x16_bf16 v[32:47], v[132:135], v[148:151], v[32:47]
	v_max_f32_e32 v8, v8, v8
	v_max_f32_e32 v9, v9, v9
	v_max_f32_e32 v10, v10, v10
	v_max_f32_e32 v11, v11, v11
	v_max_f32_e32 v12, v12, v12
	v_max_f32_e32 v13, v13, v13
	v_max_f32_e32 v14, v14, v14
	v_mfma_f32_32x32x16_bf16 v[16:31], v[136:139], v[148:151], v[16:31]
	v_max_f32_e32 v15, v15, v15
	v_mad_u64_u32 v[128:129], s[14:15], v129, s18, v[128:129]
	v_mul_f32_e64 v48, v48, v48
	v_mul_f32_e64 v49, v49, v49
	v_mul_f32_e64 v50, v50, v50
	v_mul_f32_e64 v51, v51, v51
	v_pk_mul_f32 v[52:53], v[52:53], v[52:53]
	v_pk_mul_f32 v[0:1], v[0:1], v[0:1]
	v_pk_mul_f32 v[2:3], v[2:3], v[2:3]
	v_pk_mul_f32 v[4:5], v[4:5], v[4:5]
	v_pk_mul_f32 v[6:7], v[6:7], v[6:7]
	v_max_f32_e32 v8, 0, v8
	v_max_f32_e32 v9, 0, v9
	v_max_f32_e32 v10, 0, v10
	v_max_f32_e32 v11, 0, v11
	v_max_f32_e32 v12, 0, v12
	v_max_f32_e32 v13, 0, v13
	v_max_f32_e32 v14, 0, v14
	v_max_f32_e32 v15, 0, v15
	v_cvt_pk_bf16_f32 v48, v48, v49
	v_cvt_pk_bf16_f32 v49, v50, v51
	v_cvt_pk_bf16_f32 v50, v52, v53
	v_add_u32_e32 v52, 0x4000, v128
	v_pk_mul_f32 v[8:9], v[8:9], v[8:9]
	v_pk_mul_f32 v[10:11], v[10:11], v[10:11]
	v_pk_mul_f32 v[12:13], v[12:13], v[12:13]
	v_pk_mul_f32 v[14:15], v[14:15], v[14:15]
	v_cvt_pk_bf16_f32 v0, v0, v1
	v_cvt_pk_bf16_f32 v1, v2, v3
	v_cvt_pk_bf16_f32 v2, v4, v5
	v_cvt_pk_bf16_f32 v3, v6, v7
	v_max_f32_e32 v112, v112, v112
	v_max_f32_e32 v113, v113, v113
	v_max_f32_e32 v114, v114, v114
	v_max_f32_e32 v115, v115, v115
	v_max_f32_e32 v116, v116, v116
	v_max_f32_e32 v117, v117, v117
	v_max_f32_e32 v118, v118, v118
	v_max_f32_e32 v119, v119, v119
	v_max_f32_e32 v96, v96, v96
	v_max_f32_e32 v97, v97, v97
	v_max_f32_e32 v98, v98, v98
	v_max_f32_e32 v99, v99, v99
	v_max_f32_e32 v100, v100, v100
	v_max_f32_e32 v101, v101, v101
	v_max_f32_e32 v102, v102, v102
	v_max_f32_e32 v103, v103, v103
	v_max_f32_e32 v80, v80, v80
	v_max_f32_e32 v81, v81, v81
	v_max_f32_e32 v82, v82, v82
	v_max_f32_e32 v83, v83, v83
	v_max_f32_e32 v84, v84, v84
	v_max_f32_e32 v85, v85, v85
	v_max_f32_e32 v86, v86, v86
	v_max_f32_e32 v87, v87, v87
	v_max_f32_e32 v64, v64, v64
	v_max_f32_e32 v65, v65, v65
	v_max_f32_e32 v66, v66, v66
	v_max_f32_e32 v67, v67, v67
	v_max_f32_e32 v68, v68, v68
	v_max_f32_e32 v69, v69, v69
	v_max_f32_e32 v70, v70, v70
	v_max_f32_e32 v71, v71, v71
	v_max_f32_e32 v54, v54, v54
	v_max_f32_e32 v55, v55, v55
	v_max_f32_e32 v32, v32, v32
	v_max_f32_e32 v33, v33, v33
	v_max_f32_e32 v34, v34, v34
	v_max_f32_e32 v35, v35, v35
	v_max_f32_e32 v36, v36, v36
	v_max_f32_e32 v37, v37, v37
	v_max_f32_e32 v38, v38, v38
	v_max_f32_e32 v39, v39, v39
	v_max_f32_e32 v16, v16, v16
	v_max_f32_e32 v17, v17, v17
	v_max_f32_e32 v18, v18, v18
	v_max_f32_e32 v19, v19, v19
	v_max_f32_e32 v20, v20, v20
	v_max_f32_e32 v21, v21, v21
	v_max_f32_e32 v22, v22, v22
	v_max_f32_e32 v23, v23, v23
	ds_write2_b64 v52, v[0:1], v[2:3] offset0:88 offset1:90
	v_cvt_pk_bf16_f32 v0, v8, v9
	v_cvt_pk_bf16_f32 v1, v10, v11
	v_cvt_pk_bf16_f32 v2, v12, v13
	v_cvt_pk_bf16_f32 v3, v14, v15
	v_readlane_b32 s14, v254, 54
	v_max_f32_e32 v112, 0, v112
	v_max_f32_e32 v113, 0, v113
	v_max_f32_e32 v114, 0, v114
	v_max_f32_e32 v115, 0, v115
	v_max_f32_e32 v116, 0, v116
	v_max_f32_e32 v117, 0, v117
	v_max_f32_e32 v118, 0, v118
	v_max_f32_e32 v119, 0, v119
	v_max_f32_e32 v120, v120, v120
	v_max_f32_e32 v121, v121, v121
	v_max_f32_e32 v122, v122, v122
	v_max_f32_e32 v123, v123, v123
	v_max_f32_e32 v124, v124, v124
	v_max_f32_e32 v125, v125, v125
	v_max_f32_e32 v126, v126, v126
	v_max_f32_e32 v127, v127, v127
	v_max_f32_e32 v96, 0, v96
	v_max_f32_e32 v97, 0, v97
	v_max_f32_e32 v98, 0, v98
	v_max_f32_e32 v99, 0, v99
	v_max_f32_e32 v100, 0, v100
	v_max_f32_e32 v101, 0, v101
	v_max_f32_e32 v102, 0, v102
	v_max_f32_e32 v103, 0, v103
	v_max_f32_e32 v104, v104, v104
	v_max_f32_e32 v105, v105, v105
	v_max_f32_e32 v106, v106, v106
	v_max_f32_e32 v107, v107, v107
	v_max_f32_e32 v108, v108, v108
	v_max_f32_e32 v109, v109, v109
	v_max_f32_e32 v110, v110, v110
	v_max_f32_e32 v111, v111, v111
	v_max_f32_e32 v80, 0, v80
	v_max_f32_e32 v81, 0, v81
	v_max_f32_e32 v82, 0, v82
	v_max_f32_e32 v83, 0, v83
	v_max_f32_e32 v84, 0, v84
	v_max_f32_e32 v85, 0, v85
	v_max_f32_e32 v86, 0, v86
	v_max_f32_e32 v87, 0, v87
	v_max_f32_e32 v88, v88, v88
	v_max_f32_e32 v89, v89, v89
	v_max_f32_e32 v90, v90, v90
	v_max_f32_e32 v91, v91, v91
	v_max_f32_e32 v92, v92, v92
	v_max_f32_e32 v93, v93, v93
	v_max_f32_e32 v94, v94, v94
	v_max_f32_e32 v95, v95, v95
	v_max_f32_e32 v64, 0, v64
	v_max_f32_e32 v65, 0, v65
	v_max_f32_e32 v66, 0, v66
	v_max_f32_e32 v67, 0, v67
	v_max_f32_e32 v68, 0, v68
	v_max_f32_e32 v69, 0, v69
	v_max_f32_e32 v70, 0, v70
	v_max_f32_e32 v71, 0, v71
	v_max_f32_e32 v72, v72, v72
	v_max_f32_e32 v73, v73, v73
	v_max_f32_e32 v74, v74, v74
	v_max_f32_e32 v75, v75, v75
	v_max_f32_e32 v76, v76, v76
	v_max_f32_e32 v77, v77, v77
	v_max_f32_e32 v78, v78, v78
	v_max_f32_e32 v79, v79, v79
	v_max_f32_e32 v54, 0, v54
	v_max_f32_e32 v55, 0, v55
	v_max_f32_e32 v56, v56, v56
	v_max_f32_e32 v57, v57, v57
	v_max_f32_e32 v58, v58, v58
	v_max_f32_e32 v59, v59, v59
	v_max_f32_e32 v60, v60, v60
	v_max_f32_e32 v61, v61, v61
	v_max_f32_e32 v62, v62, v62
	v_max_f32_e32 v63, v63, v63
	v_max_f32_e32 v32, 0, v32
	v_max_f32_e32 v33, 0, v33
	v_max_f32_e32 v34, 0, v34
	v_max_f32_e32 v35, 0, v35
	v_max_f32_e32 v36, 0, v36
	v_max_f32_e32 v37, 0, v37
	v_max_f32_e32 v38, 0, v38
	v_max_f32_e32 v39, 0, v39
	v_max_f32_e32 v40, v40, v40
	v_max_f32_e32 v41, v41, v41
	v_max_f32_e32 v42, v42, v42
	v_max_f32_e32 v43, v43, v43
	v_max_f32_e32 v44, v44, v44
	v_max_f32_e32 v45, v45, v45
	v_max_f32_e32 v46, v46, v46
	v_max_f32_e32 v47, v47, v47
	v_max_f32_e32 v16, 0, v16
	v_max_f32_e32 v17, 0, v17
	v_max_f32_e32 v18, 0, v18
	v_max_f32_e32 v19, 0, v19
	v_max_f32_e32 v20, 0, v20
	v_max_f32_e32 v21, 0, v21
	v_max_f32_e32 v22, 0, v22
	v_max_f32_e32 v23, 0, v23
	v_max_f32_e32 v24, v24, v24
	v_max_f32_e32 v25, v25, v25
	v_max_f32_e32 v26, v26, v26
	v_max_f32_e32 v27, v27, v27
	v_max_f32_e32 v28, v28, v28
	v_max_f32_e32 v29, v29, v29
	v_max_f32_e32 v30, v30, v30
	v_max_f32_e32 v31, v31, v31
	ds_write2_b64 v52, v[0:1], v[2:3] offset0:92 offset1:94
	v_lshlrev_b32_e32 v0, 4, v156
	v_readlane_b32 s15, v254, 55
	s_add_u32 s4, s14, s4
	v_pk_mul_f32 v[112:113], v[112:113], v[112:113]
	v_pk_mul_f32 v[114:115], v[114:115], v[114:115]
	v_pk_mul_f32 v[116:117], v[116:117], v[116:117]
	v_pk_mul_f32 v[118:119], v[118:119], v[118:119]
	v_max_f32_e32 v120, 0, v120
	v_max_f32_e32 v121, 0, v121
	v_max_f32_e32 v122, 0, v122
	v_max_f32_e32 v123, 0, v123
	v_max_f32_e32 v124, 0, v124
	v_max_f32_e32 v125, 0, v125
	v_max_f32_e32 v126, 0, v126
	v_max_f32_e32 v127, 0, v127
	v_pk_mul_f32 v[96:97], v[96:97], v[96:97]
	v_pk_mul_f32 v[98:99], v[98:99], v[98:99]
	v_pk_mul_f32 v[100:101], v[100:101], v[100:101]
	v_pk_mul_f32 v[102:103], v[102:103], v[102:103]
	v_max_f32_e32 v104, 0, v104
	v_max_f32_e32 v105, 0, v105
	v_max_f32_e32 v106, 0, v106
	v_max_f32_e32 v107, 0, v107
	v_max_f32_e32 v108, 0, v108
	v_max_f32_e32 v109, 0, v109
	v_max_f32_e32 v110, 0, v110
	v_max_f32_e32 v111, 0, v111
	v_pk_mul_f32 v[80:81], v[80:81], v[80:81]
	v_pk_mul_f32 v[82:83], v[82:83], v[82:83]
	v_pk_mul_f32 v[84:85], v[84:85], v[84:85]
	v_pk_mul_f32 v[86:87], v[86:87], v[86:87]
	v_max_f32_e32 v88, 0, v88
	v_max_f32_e32 v89, 0, v89
	v_max_f32_e32 v90, 0, v90
	v_max_f32_e32 v91, 0, v91
	v_max_f32_e32 v92, 0, v92
	v_max_f32_e32 v93, 0, v93
	v_max_f32_e32 v94, 0, v94
	v_max_f32_e32 v95, 0, v95
	v_pk_mul_f32 v[64:65], v[64:65], v[64:65]
	v_pk_mul_f32 v[66:67], v[66:67], v[66:67]
	v_pk_mul_f32 v[68:69], v[68:69], v[68:69]
	v_pk_mul_f32 v[70:71], v[70:71], v[70:71]
	v_max_f32_e32 v72, 0, v72
	v_max_f32_e32 v73, 0, v73
	v_max_f32_e32 v74, 0, v74
	v_max_f32_e32 v75, 0, v75
	v_max_f32_e32 v76, 0, v76
	v_max_f32_e32 v77, 0, v77
	v_max_f32_e32 v78, 0, v78
	v_max_f32_e32 v79, 0, v79
	v_pk_mul_f32 v[54:55], v[54:55], v[54:55]
	v_max_f32_e32 v56, 0, v56
	v_max_f32_e32 v57, 0, v57
	v_max_f32_e32 v58, 0, v58
	v_max_f32_e32 v59, 0, v59
	v_max_f32_e32 v60, 0, v60
	v_max_f32_e32 v61, 0, v61
	v_max_f32_e32 v62, 0, v62
	v_max_f32_e32 v63, 0, v63
	v_pk_mul_f32 v[32:33], v[32:33], v[32:33]
	v_pk_mul_f32 v[34:35], v[34:35], v[34:35]
	v_pk_mul_f32 v[36:37], v[36:37], v[36:37]
	v_pk_mul_f32 v[38:39], v[38:39], v[38:39]
	v_max_f32_e32 v40, 0, v40
	v_max_f32_e32 v41, 0, v41
	v_max_f32_e32 v42, 0, v42
	v_max_f32_e32 v43, 0, v43
	v_max_f32_e32 v44, 0, v44
	v_max_f32_e32 v45, 0, v45
	v_max_f32_e32 v46, 0, v46
	v_max_f32_e32 v47, 0, v47
	v_pk_mul_f32 v[16:17], v[16:17], v[16:17]
	v_pk_mul_f32 v[18:19], v[18:19], v[18:19]
	v_pk_mul_f32 v[20:21], v[20:21], v[20:21]
	v_pk_mul_f32 v[22:23], v[22:23], v[22:23]
	v_max_f32_e32 v24, 0, v24
	v_max_f32_e32 v25, 0, v25
	v_max_f32_e32 v26, 0, v26
	v_max_f32_e32 v27, 0, v27
	v_max_f32_e32 v28, 0, v28
	v_max_f32_e32 v29, 0, v29
	v_max_f32_e32 v30, 0, v30
	v_max_f32_e32 v31, 0, v31
	v_and_b32_e32 v190, 0x1f0, v0
	s_addc_u32 s5, s15, s5
	v_ashrrev_i32_e32 v2, 5, v156
	v_pk_mul_f32 v[120:121], v[120:121], v[120:121]
	v_pk_mul_f32 v[122:123], v[122:123], v[122:123]
	v_pk_mul_f32 v[124:125], v[124:125], v[124:125]
	v_pk_mul_f32 v[126:127], v[126:127], v[126:127]
	v_cvt_pk_bf16_f32 v112, v112, v113
	v_cvt_pk_bf16_f32 v113, v114, v115
	v_cvt_pk_bf16_f32 v114, v116, v117
	v_cvt_pk_bf16_f32 v115, v118, v119
	v_pk_mul_f32 v[104:105], v[104:105], v[104:105]
	v_pk_mul_f32 v[106:107], v[106:107], v[106:107]
	v_pk_mul_f32 v[108:109], v[108:109], v[108:109]
	v_pk_mul_f32 v[110:111], v[110:111], v[110:111]
	v_cvt_pk_bf16_f32 v96, v96, v97
	v_cvt_pk_bf16_f32 v97, v98, v99
	v_cvt_pk_bf16_f32 v98, v100, v101
	v_cvt_pk_bf16_f32 v99, v102, v103
	v_pk_mul_f32 v[88:89], v[88:89], v[88:89]
	v_pk_mul_f32 v[90:91], v[90:91], v[90:91]
	v_pk_mul_f32 v[92:93], v[92:93], v[92:93]
	v_pk_mul_f32 v[94:95], v[94:95], v[94:95]
	v_cvt_pk_bf16_f32 v80, v80, v81
	v_cvt_pk_bf16_f32 v81, v82, v83
	v_cvt_pk_bf16_f32 v82, v84, v85
	v_cvt_pk_bf16_f32 v83, v86, v87
	v_pk_mul_f32 v[72:73], v[72:73], v[72:73]
	v_pk_mul_f32 v[74:75], v[74:75], v[74:75]
	v_pk_mul_f32 v[76:77], v[76:77], v[76:77]
	v_pk_mul_f32 v[78:79], v[78:79], v[78:79]
	v_cvt_pk_bf16_f32 v64, v64, v65
	v_cvt_pk_bf16_f32 v65, v66, v67
	v_cvt_pk_bf16_f32 v66, v68, v69
	v_cvt_pk_bf16_f32 v67, v70, v71
	v_pk_mul_f32 v[56:57], v[56:57], v[56:57]
	v_pk_mul_f32 v[58:59], v[58:59], v[58:59]
	v_pk_mul_f32 v[60:61], v[60:61], v[60:61]
	v_pk_mul_f32 v[62:63], v[62:63], v[62:63]
	v_cvt_pk_bf16_f32 v51, v54, v55
	v_pk_mul_f32 v[40:41], v[40:41], v[40:41]
	v_pk_mul_f32 v[42:43], v[42:43], v[42:43]
	v_pk_mul_f32 v[44:45], v[44:45], v[44:45]
	v_pk_mul_f32 v[46:47], v[46:47], v[46:47]
	v_cvt_pk_bf16_f32 v32, v32, v33
	v_cvt_pk_bf16_f32 v33, v34, v35
	v_cvt_pk_bf16_f32 v34, v36, v37
	v_cvt_pk_bf16_f32 v35, v38, v39
	v_pk_mul_f32 v[24:25], v[24:25], v[24:25]
	v_pk_mul_f32 v[26:27], v[26:27], v[26:27]
	v_pk_mul_f32 v[28:29], v[28:29], v[28:29]
	v_pk_mul_f32 v[30:31], v[30:31], v[30:31]
	v_cvt_pk_bf16_f32 v16, v16, v17
	v_cvt_pk_bf16_f32 v17, v18, v19
	v_cvt_pk_bf16_f32 v18, v20, v21
	v_cvt_pk_bf16_f32 v19, v22, v23
	v_lshl_add_u64 v[4:5], s[4:5], 0, v[190:191]
	v_mad_u64_u32 v[0:1], s[4:5], v2, s18, v[190:191]
	ds_write2_b64 v128, v[112:113], v[114:115] offset1:2
	v_cvt_pk_bf16_f32 v112, v120, v121
	v_cvt_pk_bf16_f32 v113, v122, v123
	v_cvt_pk_bf16_f32 v114, v124, v125
	v_cvt_pk_bf16_f32 v115, v126, v127
	ds_write2_b64 v128, v[96:97], v[98:99] offset0:8 offset1:10
	v_cvt_pk_bf16_f32 v96, v104, v105
	v_cvt_pk_bf16_f32 v97, v106, v107
	v_cvt_pk_bf16_f32 v98, v108, v109
	v_cvt_pk_bf16_f32 v99, v110, v111
	ds_write2_b64 v128, v[80:81], v[82:83] offset0:16 offset1:18
	v_cvt_pk_bf16_f32 v80, v88, v89
	v_cvt_pk_bf16_f32 v81, v90, v91
	v_cvt_pk_bf16_f32 v82, v92, v93
	v_cvt_pk_bf16_f32 v83, v94, v95
	ds_write2_b64 v128, v[64:65], v[66:67] offset0:24 offset1:26
	v_cvt_pk_bf16_f32 v64, v72, v73
	v_cvt_pk_bf16_f32 v65, v74, v75
	v_cvt_pk_bf16_f32 v66, v76, v77
	v_cvt_pk_bf16_f32 v67, v78, v79
	ds_write2_b64 v52, v[48:49], v[50:51] offset0:64 offset1:66
	v_cvt_pk_bf16_f32 v48, v56, v57
	v_cvt_pk_bf16_f32 v49, v58, v59
	v_cvt_pk_bf16_f32 v50, v60, v61
	v_cvt_pk_bf16_f32 v51, v62, v63
	ds_write2_b64 v52, v[32:33], v[34:35] offset0:72 offset1:74
	v_cvt_pk_bf16_f32 v32, v40, v41
	v_cvt_pk_bf16_f32 v33, v42, v43
	v_cvt_pk_bf16_f32 v34, v44, v45
	v_cvt_pk_bf16_f32 v35, v46, v47
	ds_write2_b64 v52, v[16:17], v[18:19] offset0:80 offset1:82
	v_cvt_pk_bf16_f32 v16, v24, v25
	v_cvt_pk_bf16_f32 v17, v26, v27
	v_cvt_pk_bf16_f32 v18, v28, v29
	v_cvt_pk_bf16_f32 v19, v30, v31
	v_add_u32_e32 v1, s40, v2
	ds_write2_b64 v128, v[112:113], v[114:115] offset0:4 offset1:6
	ds_write2_b64 v128, v[96:97], v[98:99] offset0:12 offset1:14
	ds_write2_b64 v128, v[80:81], v[82:83] offset0:20 offset1:22
	ds_write2_b64 v128, v[64:65], v[66:67] offset0:28 offset1:30
	ds_write2_b64 v52, v[48:49], v[50:51] offset0:68 offset1:70
	ds_write2_b64 v52, v[32:33], v[34:35] offset0:76 offset1:78
	ds_write2_b64 v52, v[16:17], v[18:19] offset0:84 offset1:86
	s_waitcnt lgkmcnt(0)
	s_barrier
	v_mad_i64_i32 v[6:7], s[4:5], v1, s7, v[4:5]
	ds_read_b128 v[0:3], v0
	s_add_i32 s2, s2, 1
	s_waitcnt lgkmcnt(0)
	global_store_dwordx4 v[6:7], v[0:3], off
	s_nop 1
	v_add_u32_e32 v0, 0x100, v156
	v_ashrrev_i32_e32 v2, 5, v0
	v_mad_u64_u32 v[0:1], s[4:5], v2, s18, v[190:191]
	v_add_u32_e32 v1, s40, v2
	v_mad_i64_i32 v[6:7], s[4:5], v1, s7, v[4:5]
	ds_read_b128 v[0:3], v0
	s_waitcnt lgkmcnt(0)
	global_store_dwordx4 v[6:7], v[0:3], off
	s_nop 1
	v_add_u32_e32 v0, 0x200, v156
	v_ashrrev_i32_e32 v2, 5, v0
	v_mad_u64_u32 v[0:1], s[4:5], v2, s18, v[190:191]
	v_add_u32_e32 v1, s40, v2
	v_mad_i64_i32 v[6:7], s[4:5], v1, s7, v[4:5]
	ds_read_b128 v[0:3], v0
	s_waitcnt lgkmcnt(0)
	global_store_dwordx4 v[6:7], v[0:3], off
	s_nop 1
	v_add_u32_e32 v0, 0x300, v156
	v_ashrrev_i32_e32 v2, 5, v0
	v_mad_u64_u32 v[0:1], s[4:5], v2, s18, v[190:191]
	v_add_u32_e32 v1, s40, v2
	v_mad_i64_i32 v[6:7], s[4:5], v1, s7, v[4:5]
	ds_read_b128 v[0:3], v0
	s_waitcnt lgkmcnt(0)
	global_store_dwordx4 v[6:7], v[0:3], off
	s_nop 1
	v_add_u32_e32 v0, 0x400, v156
	v_ashrrev_i32_e32 v2, 5, v0
	v_mad_u64_u32 v[0:1], s[4:5], v2, s18, v[190:191]
	v_add_u32_e32 v1, s40, v2
	v_mad_i64_i32 v[6:7], s[4:5], v1, s7, v[4:5]
	ds_read_b128 v[0:3], v0
	s_waitcnt lgkmcnt(0)
	global_store_dwordx4 v[6:7], v[0:3], off
	s_nop 1
	v_add_u32_e32 v0, 0x500, v156
	v_ashrrev_i32_e32 v2, 5, v0
	v_mad_u64_u32 v[0:1], s[4:5], v2, s18, v[190:191]
	v_add_u32_e32 v1, s40, v2
	v_mad_i64_i32 v[6:7], s[4:5], v1, s7, v[4:5]
	ds_read_b128 v[0:3], v0
	s_waitcnt lgkmcnt(0)
	global_store_dwordx4 v[6:7], v[0:3], off
	s_nop 1
	v_add_u32_e32 v0, 0x600, v156
	v_ashrrev_i32_e32 v2, 5, v0
	v_mad_u64_u32 v[0:1], s[4:5], v2, s18, v[190:191]
	v_add_u32_e32 v1, s40, v2
	v_mad_i64_i32 v[6:7], s[4:5], v1, s7, v[4:5]
	ds_read_b128 v[0:3], v0
	s_waitcnt lgkmcnt(0)
	global_store_dwordx4 v[6:7], v[0:3], off
	s_nop 1
	v_add_u32_e32 v0, 0x700, v156
	v_ashrrev_i32_e32 v2, 5, v0
	v_mad_u64_u32 v[0:1], s[4:5], v2, s18, v[190:191]
	v_add_u32_e32 v1, s40, v2
	v_mad_i64_i32 v[6:7], s[4:5], v1, s7, v[4:5]
	ds_read_b128 v[0:3], v0
	s_waitcnt lgkmcnt(0)
	global_store_dwordx4 v[6:7], v[0:3], off
	s_nop 1
	v_add_u32_e32 v0, 0x800, v156
	v_ashrrev_i32_e32 v2, 5, v0
	v_mad_u64_u32 v[0:1], s[4:5], v2, s18, v[190:191]
	v_add_u32_e32 v1, s40, v2
	v_mad_i64_i32 v[6:7], s[4:5], v1, s7, v[4:5]
	ds_read_b128 v[0:3], v0
	s_waitcnt lgkmcnt(0)
	global_store_dwordx4 v[6:7], v[0:3], off
	s_nop 1
	v_add_u32_e32 v0, 0x900, v156
	v_ashrrev_i32_e32 v2, 5, v0
	v_mad_u64_u32 v[0:1], s[4:5], v2, s18, v[190:191]
	v_add_u32_e32 v1, s40, v2
	v_mad_i64_i32 v[6:7], s[4:5], v1, s7, v[4:5]
	ds_read_b128 v[0:3], v0
	s_waitcnt lgkmcnt(0)
	global_store_dwordx4 v[6:7], v[0:3], off
	s_nop 1
	v_add_u32_e32 v0, 0xa00, v156
	v_ashrrev_i32_e32 v2, 5, v0
	v_mad_u64_u32 v[0:1], s[4:5], v2, s18, v[190:191]
	v_add_u32_e32 v1, s40, v2
	v_mad_i64_i32 v[6:7], s[4:5], v1, s7, v[4:5]
	ds_read_b128 v[0:3], v0
	s_waitcnt lgkmcnt(0)
	global_store_dwordx4 v[6:7], v[0:3], off
	s_nop 1
	v_add_u32_e32 v0, 0xb00, v156
	v_ashrrev_i32_e32 v2, 5, v0
	v_mad_u64_u32 v[0:1], s[4:5], v2, s18, v[190:191]
	v_add_u32_e32 v1, s40, v2
	v_mad_i64_i32 v[6:7], s[4:5], v1, s7, v[4:5]
	ds_read_b128 v[0:3], v0
	s_waitcnt lgkmcnt(0)
	global_store_dwordx4 v[6:7], v[0:3], off
	s_nop 1
	v_add_u32_e32 v0, 0xc00, v156
	v_ashrrev_i32_e32 v2, 5, v0
	v_mad_u64_u32 v[0:1], s[4:5], v2, s18, v[190:191]
	v_add_u32_e32 v1, s40, v2
	v_mad_i64_i32 v[6:7], s[4:5], v1, s7, v[4:5]
	ds_read_b128 v[0:3], v0
	s_waitcnt lgkmcnt(0)
	global_store_dwordx4 v[6:7], v[0:3], off
	s_nop 1
	v_add_u32_e32 v0, 0xd00, v156
	v_ashrrev_i32_e32 v2, 5, v0
	v_mad_u64_u32 v[0:1], s[4:5], v2, s18, v[190:191]
	v_add_u32_e32 v1, s40, v2
	v_mad_i64_i32 v[6:7], s[4:5], v1, s7, v[4:5]
	ds_read_b128 v[0:3], v0
	s_waitcnt lgkmcnt(0)
	global_store_dwordx4 v[6:7], v[0:3], off
	s_nop 1
	v_add_u32_e32 v0, 0xe00, v156
	v_ashrrev_i32_e32 v2, 5, v0
	v_mad_u64_u32 v[0:1], s[4:5], v2, s18, v[190:191]
	v_add_u32_e32 v1, s40, v2
	v_mad_i64_i32 v[6:7], s[4:5], v1, s7, v[4:5]
	ds_read_b128 v[0:3], v0
	s_waitcnt lgkmcnt(0)
	global_store_dwordx4 v[6:7], v[0:3], off
	s_nop 1
	v_add_u32_e32 v0, 0xf00, v156
	v_ashrrev_i32_e32 v2, 5, v0
	v_mad_u64_u32 v[0:1], s[4:5], v2, s18, v[190:191]
	v_add_u32_e32 v1, s40, v2
	v_mad_i64_i32 v[4:5], s[4:5], v1, s7, v[4:5]
	ds_read_b128 v[0:3], v0
	s_mov_b64 s[4:5], 0
	s_waitcnt lgkmcnt(0)
	global_store_dwordx4 v[4:5], v[0:3], off
	s_barrier
	s_branch .LBB0_1060

.LBB0_1125:
	v_add_co_u32_e32 v182, vcc, 0x800, v152
	s_nop 1
	v_addc_co_u32_e32 v183, vcc, 0, v153, vcc
	v_add_co_u32_e32 v204, vcc, s25, v182
	s_nop 1
	v_addc_co_u32_e32 v205, vcc, 0, v183, vcc
	v_add_co_u32_e32 v206, vcc, s27, v182
	s_nop 1
	v_addc_co_u32_e32 v207, vcc, 0, v183, vcc
	v_add_co_u32_e32 v208, vcc, s12, v154
	s_nop 1
	v_addc_co_u32_e32 v209, vcc, 0, v155, vcc
	v_add_co_u32_e32 v210, vcc, s13, v154
	s_nop 1
	v_addc_co_u32_e32 v211, vcc, 0, v155, vcc
	v_add_co_u32_e32 v212, vcc, 0x1e82000, v154
	s_nop 1
	v_addc_co_u32_e32 v213, vcc, 0, v155, vcc
	v_add_co_u32_e32 v214, vcc, 0x1f04000, v154
	s_nop 1
	v_addc_co_u32_e32 v215, vcc, 0, v155, vcc
	v_and_b32_e32 v216, 3, v156
	v_bfe_u32 v217, v156, 4, 2
	v_xor_b32_e32 v218, v216, v217
	v_sub_u32_e32 v218, v218, v216
	v_lshlrev_b32_e32 v218, 4, v218
	v_ashrrev_i32_e32 v219, 31, v218
	v_lshl_add_u64 v[204:205], v[218:219], 0, v[204:205]
	v_lshl_add_u64 v[206:207], v[218:219], 0, v[206:207]
	v_lshl_add_u64 v[208:209], v[218:219], 0, v[208:209]
	v_lshl_add_u64 v[210:211], v[218:219], 0, v[210:211]
	v_lshl_add_u64 v[212:213], v[218:219], 0, v[212:213]
	v_lshl_add_u64 v[214:215], v[218:219], 0, v[214:215]
	v_mov_b32_e32 v216, 64
	v_mov_b32_e32 v217, 0
	v_lshl_add_u64 v[204:205], v[216:217], 1, v[204:205]
	v_lshl_add_u64 v[206:207], v[216:217], 1, v[206:207]
	v_lshl_add_u64 v[208:209], v[216:217], 1, v[208:209]
	v_lshl_add_u64 v[210:211], v[216:217], 1, v[210:211]
	v_lshl_add_u64 v[212:213], v[216:217], 1, v[212:213]
	v_lshl_add_u64 v[214:215], v[216:217], 1, v[214:215]
	v_lshrrev_b32_e32 v246, 6, v156
	v_lshlrev_b32_e32 v246, 10, v246
	s_nop 0
	v_readfirstlane_b32 s14, v246
	ds_read_b128 v[162:165], v157 offset:8192
	ds_read_b128 v[178:181], v161
	ds_read_b128 v[166:169], v157 offset:10240
	ds_read_b128 v[200:203], v161 offset:2048
	ds_read_b128 v[170:173], v157 offset:12288
	ds_read_b128 v[174:177], v157 offset:14336
	s_waitcnt lgkmcnt(4)
	v_mfma_f32_32x32x16_bf16 v[112:127], v[162:165], v[178:181], v[112:127]
	s_waitcnt lgkmcnt(3)
	v_mfma_f32_32x32x16_bf16 v[96:111], v[166:169], v[178:181], v[96:111]
	s_waitcnt lgkmcnt(1)
	v_mfma_f32_32x32x16_bf16 v[80:95], v[170:173], v[178:181], v[80:95]
	s_waitcnt lgkmcnt(0)
	v_mfma_f32_32x32x16_bf16 v[64:79], v[174:177], v[178:181], v[64:79]
	v_mfma_f32_32x32x16_bf16 v[48:63], v[162:165], v[200:203], v[48:63]
	v_mfma_f32_32x32x16_bf16 v[32:47], v[166:169], v[200:203], v[32:47]
	v_mfma_f32_32x32x16_bf16 v[16:31], v[170:173], v[200:203], v[16:31]
	v_mfma_f32_32x32x16_bf16 v[0:15], v[174:177], v[200:203], v[0:15]
	ds_read_b128 v[162:165], v159 offset:8192
	ds_read_b128 v[178:181], v158
	ds_read_b128 v[166:169], v159 offset:10240
	ds_read_b128 v[200:203], v158 offset:2048
	ds_read_b128 v[170:173], v159 offset:12288
	ds_read_b128 v[174:177], v159 offset:14336
	s_waitcnt vmcnt(5)
	ds_write_b128 v160, v[144:147] offset:24576
	s_waitcnt vmcnt(4)
	ds_write_b128 v160, v[148:151] offset:28672
	s_waitcnt vmcnt(3)
	ds_write_b128 v160, v[140:143] offset:32768
	s_waitcnt vmcnt(2)
	ds_write_b128 v160, v[136:139] offset:36864
	s_waitcnt vmcnt(1)
	ds_write_b128 v160, v[132:135] offset:40960
	s_waitcnt vmcnt(0)
	ds_write_b128 v160, v[128:131] offset:45056
	s_add_u32 m0, s14, 0xc000
	s_nop 0
	global_load_lds_dwordx4 v[204:205], off
	v_lshl_add_u64 v[204:205], v[216:217], 0, v[204:205]
	s_add_u32 m0, s14, 0xd000
	s_nop 0
	global_load_lds_dwordx4 v[206:207], off
	v_lshl_add_u64 v[206:207], v[216:217], 0, v[206:207]
	s_add_u32 m0, s14, 0xe000
	s_nop 0
	global_load_lds_dwordx4 v[208:209], off
	v_lshl_add_u64 v[208:209], v[216:217], 0, v[208:209]
	s_add_u32 m0, s14, 0xf000
	s_nop 0
	global_load_lds_dwordx4 v[210:211], off
	v_lshl_add_u64 v[210:211], v[216:217], 0, v[210:211]
	s_add_u32 m0, s14, 0x10000
	s_nop 0
	global_load_lds_dwordx4 v[212:213], off
	v_lshl_add_u64 v[212:213], v[216:217], 0, v[212:213]
	s_add_u32 m0, s14, 0x11000
	s_nop 0
	global_load_lds_dwordx4 v[214:215], off
	v_lshl_add_u64 v[214:215], v[216:217], 0, v[214:215]
	s_waitcnt lgkmcnt(10)
	v_mfma_f32_32x32x16_bf16 v[112:127], v[162:165], v[178:181], v[112:127]
	s_waitcnt lgkmcnt(9)
	v_mfma_f32_32x32x16_bf16 v[96:111], v[166:169], v[178:181], v[96:111]
	s_waitcnt lgkmcnt(7)
	v_mfma_f32_32x32x16_bf16 v[80:95], v[170:173], v[178:181], v[80:95]
	s_waitcnt lgkmcnt(6)
	v_mfma_f32_32x32x16_bf16 v[64:79], v[174:177], v[178:181], v[64:79]
	v_mfma_f32_32x32x16_bf16 v[48:63], v[162:165], v[200:203], v[48:63]
	v_mfma_f32_32x32x16_bf16 v[32:47], v[166:169], v[200:203], v[32:47]
	v_mfma_f32_32x32x16_bf16 v[16:31], v[170:173], v[200:203], v[16:31]
	v_mfma_f32_32x32x16_bf16 v[0:15], v[174:177], v[200:203], v[0:15]
	s_waitcnt lgkmcnt(0)
	s_barrier
	s_mov_b32 s4, 0
.Ldn_dma_loop:
	ds_read_b128 v[162:165], v157 offset:32768
	ds_read_b128 v[178:181], v161 offset:24576
	ds_read_b128 v[166:169], v157 offset:34816
	ds_read_b128 v[200:203], v161 offset:26624
	ds_read_b128 v[170:173], v157 offset:36864
	ds_read_b128 v[174:177], v157 offset:38912
	ds_read_b128 v[128:131], v159 offset:32768
	ds_read_b128 v[132:135], v158 offset:24576
	ds_read_b128 v[136:139], v159 offset:34816
	ds_read_b128 v[148:151], v158 offset:26624
	ds_read_b128 v[140:143], v159 offset:36864
	ds_read_b128 v[144:147], v159 offset:38912
	s_waitcnt lgkmcnt(10)
	v_mfma_f32_32x32x16_bf16 v[112:127], v[162:165], v[178:181], v[112:127]
	s_mov_b32 m0, s14
	s_nop 0
	global_load_lds_dwordx4 v[204:205], off
	v_lshl_add_u64 v[204:205], v[216:217], 0, v[204:205]
	s_waitcnt lgkmcnt(9)
	v_mfma_f32_32x32x16_bf16 v[96:111], v[166:169], v[178:181], v[96:111]
	s_add_u32 m0, s14, 0x1000
	s_nop 0
	global_load_lds_dwordx4 v[206:207], off
	v_lshl_add_u64 v[206:207], v[216:217], 0, v[206:207]
	s_waitcnt lgkmcnt(7)
	v_mfma_f32_32x32x16_bf16 v[80:95], v[170:173], v[178:181], v[80:95]
	s_add_u32 m0, s14, 0x2000
	s_nop 0
	global_load_lds_dwordx4 v[208:209], off
	v_lshl_add_u64 v[208:209], v[216:217], 0, v[208:209]
	s_waitcnt lgkmcnt(6)
	v_mfma_f32_32x32x16_bf16 v[64:79], v[174:177], v[178:181], v[64:79]
	s_add_u32 m0, s14, 0x3000
	s_nop 0
	global_load_lds_dwordx4 v[210:211], off
	v_lshl_add_u64 v[210:211], v[216:217], 0, v[210:211]
	v_mfma_f32_32x32x16_bf16 v[48:63], v[162:165], v[200:203], v[48:63]
	s_add_u32 m0, s14, 0x4000
	s_nop 0
	global_load_lds_dwordx4 v[212:213], off
	v_lshl_add_u64 v[212:213], v[216:217], 0, v[212:213]
	v_mfma_f32_32x32x16_bf16 v[32:47], v[166:169], v[200:203], v[32:47]
	s_add_u32 m0, s14, 0x5000
	s_nop 0
	global_load_lds_dwordx4 v[214:215], off
	v_lshl_add_u64 v[214:215], v[216:217], 0, v[214:215]
	v_mfma_f32_32x32x16_bf16 v[16:31], v[170:173], v[200:203], v[16:31]
	v_mfma_f32_32x32x16_bf16 v[0:15], v[174:177], v[200:203], v[0:15]
	s_waitcnt lgkmcnt(4)
	v_mfma_f32_32x32x16_bf16 v[112:127], v[128:131], v[132:135], v[112:127]
	s_waitcnt lgkmcnt(3)
	v_mfma_f32_32x32x16_bf16 v[96:111], v[136:139], v[132:135], v[96:111]
	s_waitcnt lgkmcnt(1)
	v_mfma_f32_32x32x16_bf16 v[80:95], v[140:143], v[132:135], v[80:95]
	s_waitcnt lgkmcnt(0)
	v_mfma_f32_32x32x16_bf16 v[64:79], v[144:147], v[132:135], v[64:79]
	v_mfma_f32_32x32x16_bf16 v[48:63], v[128:131], v[148:151], v[48:63]
	v_mfma_f32_32x32x16_bf16 v[32:47], v[136:139], v[148:151], v[32:47]
	v_mfma_f32_32x32x16_bf16 v[16:31], v[140:143], v[148:151], v[16:31]
	v_mfma_f32_32x32x16_bf16 v[0:15], v[144:147], v[148:151], v[0:15]
	s_waitcnt vmcnt(6)
	s_waitcnt lgkmcnt(0)
	s_barrier
	ds_read_b128 v[162:165], v157 offset:57344
	ds_read_b128 v[178:181], v161 offset:49152
	ds_read_b128 v[166:169], v157 offset:59392
	ds_read_b128 v[200:203], v161 offset:51200
	ds_read_b128 v[170:173], v157 offset:61440
	ds_read_b128 v[174:177], v157 offset:63488
	ds_read_b128 v[128:131], v159 offset:57344
	ds_read_b128 v[132:135], v158 offset:49152
	ds_read_b128 v[136:139], v159 offset:59392
	ds_read_b128 v[148:151], v158 offset:51200
	ds_read_b128 v[140:143], v159 offset:61440
	ds_read_b128 v[144:147], v159 offset:63488
	s_waitcnt lgkmcnt(10)
	v_mfma_f32_32x32x16_bf16 v[112:127], v[162:165], v[178:181], v[112:127]
	s_add_u32 m0, s14, 0x6000
	s_nop 0
	global_load_lds_dwordx4 v[204:205], off
	v_lshl_add_u64 v[204:205], v[216:217], 0, v[204:205]
	s_waitcnt lgkmcnt(9)
	v_mfma_f32_32x32x16_bf16 v[96:111], v[166:169], v[178:181], v[96:111]
	s_add_u32 m0, s14, 0x7000
	s_nop 0
	global_load_lds_dwordx4 v[206:207], off
	v_lshl_add_u64 v[206:207], v[216:217], 0, v[206:207]
	s_waitcnt lgkmcnt(7)
	v_mfma_f32_32x32x16_bf16 v[80:95], v[170:173], v[178:181], v[80:95]
	s_add_u32 m0, s14, 0x8000
	s_nop 0
	global_load_lds_dwordx4 v[208:209], off
	v_lshl_add_u64 v[208:209], v[216:217], 0, v[208:209]
	s_waitcnt lgkmcnt(6)
	v_mfma_f32_32x32x16_bf16 v[64:79], v[174:177], v[178:181], v[64:79]
	s_add_u32 m0, s14, 0x9000
	s_nop 0
	global_load_lds_dwordx4 v[210:211], off
	v_lshl_add_u64 v[210:211], v[216:217], 0, v[210:211]
	v_mfma_f32_32x32x16_bf16 v[48:63], v[162:165], v[200:203], v[48:63]
	s_add_u32 m0, s14, 0xa000
	s_nop 0
	global_load_lds_dwordx4 v[212:213], off
	v_lshl_add_u64 v[212:213], v[216:217], 0, v[212:213]
	v_mfma_f32_32x32x16_bf16 v[32:47], v[166:169], v[200:203], v[32:47]
	s_add_u32 m0, s14, 0xb000
	s_nop 0
	global_load_lds_dwordx4 v[214:215], off
	v_lshl_add_u64 v[214:215], v[216:217], 0, v[214:215]
	v_mfma_f32_32x32x16_bf16 v[16:31], v[170:173], v[200:203], v[16:31]
	v_mfma_f32_32x32x16_bf16 v[0:15], v[174:177], v[200:203], v[0:15]
	s_waitcnt lgkmcnt(4)
	v_mfma_f32_32x32x16_bf16 v[112:127], v[128:131], v[132:135], v[112:127]
	s_waitcnt lgkmcnt(3)
	v_mfma_f32_32x32x16_bf16 v[96:111], v[136:139], v[132:135], v[96:111]
	s_waitcnt lgkmcnt(1)
	v_mfma_f32_32x32x16_bf16 v[80:95], v[140:143], v[132:135], v[80:95]
	s_waitcnt lgkmcnt(0)
	v_mfma_f32_32x32x16_bf16 v[64:79], v[144:147], v[132:135], v[64:79]
	v_mfma_f32_32x32x16_bf16 v[48:63], v[128:131], v[148:151], v[48:63]
	v_mfma_f32_32x32x16_bf16 v[32:47], v[136:139], v[148:151], v[32:47]
	v_mfma_f32_32x32x16_bf16 v[16:31], v[140:143], v[148:151], v[16:31]
	v_mfma_f32_32x32x16_bf16 v[0:15], v[144:147], v[148:151], v[0:15]
	s_waitcnt vmcnt(6)
	s_waitcnt lgkmcnt(0)
	s_barrier
	ds_read_b128 v[162:165], v157 offset:8192
	ds_read_b128 v[178:181], v161
	ds_read_b128 v[166:169], v157 offset:10240
	ds_read_b128 v[200:203], v161 offset:2048
	ds_read_b128 v[170:173], v157 offset:12288
	ds_read_b128 v[174:177], v157 offset:14336
	ds_read_b128 v[128:131], v159 offset:8192
	ds_read_b128 v[132:135], v158
	ds_read_b128 v[136:139], v159 offset:10240
	ds_read_b128 v[148:151], v158 offset:2048
	ds_read_b128 v[140:143], v159 offset:12288
	ds_read_b128 v[144:147], v159 offset:14336
	s_waitcnt lgkmcnt(10)
	v_mfma_f32_32x32x16_bf16 v[112:127], v[162:165], v[178:181], v[112:127]
	s_add_u32 m0, s14, 0xc000
	s_nop 0
	global_load_lds_dwordx4 v[204:205], off
	v_lshl_add_u64 v[204:205], v[216:217], 0, v[204:205]
	s_waitcnt lgkmcnt(9)
	v_mfma_f32_32x32x16_bf16 v[96:111], v[166:169], v[178:181], v[96:111]
	s_add_u32 m0, s14, 0xd000
	s_nop 0
	global_load_lds_dwordx4 v[206:207], off
	v_lshl_add_u64 v[206:207], v[216:217], 0, v[206:207]
	s_waitcnt lgkmcnt(7)
	v_mfma_f32_32x32x16_bf16 v[80:95], v[170:173], v[178:181], v[80:95]
	s_add_u32 m0, s14, 0xe000
	s_nop 0
	global_load_lds_dwordx4 v[208:209], off
	v_lshl_add_u64 v[208:209], v[216:217], 0, v[208:209]
	s_waitcnt lgkmcnt(6)
	v_mfma_f32_32x32x16_bf16 v[64:79], v[174:177], v[178:181], v[64:79]
	s_add_u32 m0, s14, 0xf000
	s_nop 0
	global_load_lds_dwordx4 v[210:211], off
	v_lshl_add_u64 v[210:211], v[216:217], 0, v[210:211]
	v_mfma_f32_32x32x16_bf16 v[48:63], v[162:165], v[200:203], v[48:63]
	s_add_u32 m0, s14, 0x10000
	s_nop 0
	global_load_lds_dwordx4 v[212:213], off
	v_lshl_add_u64 v[212:213], v[216:217], 0, v[212:213]
	v_mfma_f32_32x32x16_bf16 v[32:47], v[166:169], v[200:203], v[32:47]
	s_add_u32 m0, s14, 0x11000
	s_nop 0
	global_load_lds_dwordx4 v[214:215], off
	v_lshl_add_u64 v[214:215], v[216:217], 0, v[214:215]
	v_mfma_f32_32x32x16_bf16 v[16:31], v[170:173], v[200:203], v[16:31]
	v_mfma_f32_32x32x16_bf16 v[0:15], v[174:177], v[200:203], v[0:15]
	s_waitcnt lgkmcnt(4)
	v_mfma_f32_32x32x16_bf16 v[112:127], v[128:131], v[132:135], v[112:127]
	s_waitcnt lgkmcnt(3)
	v_mfma_f32_32x32x16_bf16 v[96:111], v[136:139], v[132:135], v[96:111]
	s_waitcnt lgkmcnt(1)
	v_mfma_f32_32x32x16_bf16 v[80:95], v[140:143], v[132:135], v[80:95]
	s_waitcnt lgkmcnt(0)
	v_mfma_f32_32x32x16_bf16 v[64:79], v[144:147], v[132:135], v[64:79]
	v_mfma_f32_32x32x16_bf16 v[48:63], v[128:131], v[148:151], v[48:63]
	v_mfma_f32_32x32x16_bf16 v[32:47], v[136:139], v[148:151], v[32:47]
	v_mfma_f32_32x32x16_bf16 v[16:31], v[140:143], v[148:151], v[16:31]
	v_mfma_f32_32x32x16_bf16 v[0:15], v[144:147], v[148:151], v[0:15]
	s_waitcnt vmcnt(6)
	s_waitcnt lgkmcnt(0)
	s_barrier
	s_add_u32 s4, s4, 1
	s_cmp_lg_u32 s4, 41
	s_cbranch_scc1 .Ldn_dma_loop
	ds_read_b128 v[162:165], v157 offset:32768
	ds_read_b128 v[178:181], v161 offset:24576
	ds_read_b128 v[166:169], v157 offset:34816
	ds_read_b128 v[200:203], v161 offset:26624
	ds_read_b128 v[170:173], v157 offset:36864
	ds_read_b128 v[174:177], v157 offset:38912
	ds_read_b128 v[128:131], v159 offset:32768
	ds_read_b128 v[132:135], v158 offset:24576
	ds_read_b128 v[136:139], v159 offset:34816
	ds_read_b128 v[148:151], v158 offset:26624
	ds_read_b128 v[140:143], v159 offset:36864
	ds_read_b128 v[144:147], v159 offset:38912
	s_waitcnt lgkmcnt(10)
	v_mfma_f32_32x32x16_bf16 v[112:127], v[162:165], v[178:181], v[112:127]
	s_mov_b32 m0, s14
	s_nop 0
	global_load_lds_dwordx4 v[204:205], off
	v_lshl_add_u64 v[204:205], v[216:217], 0, v[204:205]
	s_waitcnt lgkmcnt(9)
	v_mfma_f32_32x32x16_bf16 v[96:111], v[166:169], v[178:181], v[96:111]
	s_add_u32 m0, s14, 0x1000
	s_nop 0
	global_load_lds_dwordx4 v[206:207], off
	v_lshl_add_u64 v[206:207], v[216:217], 0, v[206:207]
	s_waitcnt lgkmcnt(7)
	v_mfma_f32_32x32x16_bf16 v[80:95], v[170:173], v[178:181], v[80:95]
	s_add_u32 m0, s14, 0x2000
	s_nop 0
	global_load_lds_dwordx4 v[208:209], off
	v_lshl_add_u64 v[208:209], v[216:217], 0, v[208:209]
	s_waitcnt lgkmcnt(6)
	v_mfma_f32_32x32x16_bf16 v[64:79], v[174:177], v[178:181], v[64:79]
	s_add_u32 m0, s14, 0x3000
	s_nop 0
	global_load_lds_dwordx4 v[210:211], off
	v_lshl_add_u64 v[210:211], v[216:217], 0, v[210:211]
	v_mfma_f32_32x32x16_bf16 v[48:63], v[162:165], v[200:203], v[48:63]
	s_add_u32 m0, s14, 0x4000
	s_nop 0
	global_load_lds_dwordx4 v[212:213], off
	v_lshl_add_u64 v[212:213], v[216:217], 0, v[212:213]
	v_mfma_f32_32x32x16_bf16 v[32:47], v[166:169], v[200:203], v[32:47]
	s_add_u32 m0, s14, 0x5000
	s_nop 0
	global_load_lds_dwordx4 v[214:215], off
	v_lshl_add_u64 v[214:215], v[216:217], 0, v[214:215]
	v_mfma_f32_32x32x16_bf16 v[16:31], v[170:173], v[200:203], v[16:31]
	v_mfma_f32_32x32x16_bf16 v[0:15], v[174:177], v[200:203], v[0:15]
	s_waitcnt lgkmcnt(4)
	v_mfma_f32_32x32x16_bf16 v[112:127], v[128:131], v[132:135], v[112:127]
	s_waitcnt lgkmcnt(3)
	v_mfma_f32_32x32x16_bf16 v[96:111], v[136:139], v[132:135], v[96:111]
	s_waitcnt lgkmcnt(1)
	v_mfma_f32_32x32x16_bf16 v[80:95], v[140:143], v[132:135], v[80:95]
	s_waitcnt lgkmcnt(0)
	v_mfma_f32_32x32x16_bf16 v[64:79], v[144:147], v[132:135], v[64:79]
	v_mfma_f32_32x32x16_bf16 v[48:63], v[128:131], v[148:151], v[48:63]
	v_mfma_f32_32x32x16_bf16 v[32:47], v[136:139], v[148:151], v[32:47]
	v_mfma_f32_32x32x16_bf16 v[16:31], v[140:143], v[148:151], v[16:31]
	v_mfma_f32_32x32x16_bf16 v[0:15], v[144:147], v[148:151], v[0:15]
	s_waitcnt vmcnt(6)
	s_waitcnt lgkmcnt(0)
	s_barrier
	ds_read_b128 v[162:165], v157 offset:57344
	ds_read_b128 v[178:181], v161 offset:49152
	ds_read_b128 v[166:169], v157 offset:59392
	ds_read_b128 v[200:203], v161 offset:51200
	ds_read_b128 v[170:173], v157 offset:61440
	ds_read_b128 v[174:177], v157 offset:63488
	ds_read_b128 v[128:131], v159 offset:57344
	ds_read_b128 v[132:135], v158 offset:49152
	ds_read_b128 v[136:139], v159 offset:59392
	ds_read_b128 v[148:151], v158 offset:51200
	ds_read_b128 v[140:143], v159 offset:61440
	ds_read_b128 v[144:147], v159 offset:63488
	s_waitcnt lgkmcnt(10)
	v_mfma_f32_32x32x16_bf16 v[112:127], v[162:165], v[178:181], v[112:127]
	s_add_u32 m0, s14, 0x6000
	s_nop 0
	global_load_lds_dwordx4 v[204:205], off
	v_lshl_add_u64 v[204:205], v[216:217], 0, v[204:205]
	s_waitcnt lgkmcnt(9)
	v_mfma_f32_32x32x16_bf16 v[96:111], v[166:169], v[178:181], v[96:111]
	s_add_u32 m0, s14, 0x7000
	s_nop 0
	global_load_lds_dwordx4 v[206:207], off
	v_lshl_add_u64 v[206:207], v[216:217], 0, v[206:207]
	s_waitcnt lgkmcnt(7)
	v_mfma_f32_32x32x16_bf16 v[80:95], v[170:173], v[178:181], v[80:95]
	s_add_u32 m0, s14, 0x8000
	s_nop 0
	global_load_lds_dwordx4 v[208:209], off
	v_lshl_add_u64 v[208:209], v[216:217], 0, v[208:209]
	s_waitcnt lgkmcnt(6)
	v_mfma_f32_32x32x16_bf16 v[64:79], v[174:177], v[178:181], v[64:79]
	s_add_u32 m0, s14, 0x9000
	s_nop 0
	global_load_lds_dwordx4 v[210:211], off
	v_lshl_add_u64 v[210:211], v[216:217], 0, v[210:211]
	v_mfma_f32_32x32x16_bf16 v[48:63], v[162:165], v[200:203], v[48:63]
	s_add_u32 m0, s14, 0xa000
	s_nop 0
	global_load_lds_dwordx4 v[212:213], off
	v_lshl_add_u64 v[212:213], v[216:217], 0, v[212:213]
	v_mfma_f32_32x32x16_bf16 v[32:47], v[166:169], v[200:203], v[32:47]
	s_add_u32 m0, s14, 0xb000
	s_nop 0
	global_load_lds_dwordx4 v[214:215], off
	v_lshl_add_u64 v[214:215], v[216:217], 0, v[214:215]
	v_mfma_f32_32x32x16_bf16 v[16:31], v[170:173], v[200:203], v[16:31]
	v_mfma_f32_32x32x16_bf16 v[0:15], v[174:177], v[200:203], v[0:15]
	s_waitcnt lgkmcnt(4)
	v_mfma_f32_32x32x16_bf16 v[112:127], v[128:131], v[132:135], v[112:127]
	s_waitcnt lgkmcnt(3)
	v_mfma_f32_32x32x16_bf16 v[96:111], v[136:139], v[132:135], v[96:111]
	s_waitcnt lgkmcnt(1)
	v_mfma_f32_32x32x16_bf16 v[80:95], v[140:143], v[132:135], v[80:95]
	s_waitcnt lgkmcnt(0)
	v_mfma_f32_32x32x16_bf16 v[64:79], v[144:147], v[132:135], v[64:79]
	v_mfma_f32_32x32x16_bf16 v[48:63], v[128:131], v[148:151], v[48:63]
	v_mfma_f32_32x32x16_bf16 v[32:47], v[136:139], v[148:151], v[32:47]
	v_mfma_f32_32x32x16_bf16 v[16:31], v[140:143], v[148:151], v[16:31]
	v_mfma_f32_32x32x16_bf16 v[0:15], v[144:147], v[148:151], v[0:15]
	s_waitcnt vmcnt(6)
	s_waitcnt lgkmcnt(0)
	s_barrier
	ds_read_b128 v[162:165], v157 offset:8192
	ds_read_b128 v[178:181], v161
	ds_read_b128 v[166:169], v157 offset:10240
	ds_read_b128 v[200:203], v161 offset:2048
	ds_read_b128 v[170:173], v157 offset:12288
	ds_read_b128 v[174:177], v157 offset:14336
	ds_read_b128 v[128:131], v159 offset:8192
	ds_read_b128 v[132:135], v158
	ds_read_b128 v[136:139], v159 offset:10240
	ds_read_b128 v[148:151], v158 offset:2048
	ds_read_b128 v[140:143], v159 offset:12288
	ds_read_b128 v[144:147], v159 offset:14336
	s_waitcnt lgkmcnt(10)
	v_mfma_f32_32x32x16_bf16 v[112:127], v[162:165], v[178:181], v[112:127]
	s_waitcnt lgkmcnt(9)
	v_mfma_f32_32x32x16_bf16 v[96:111], v[166:169], v[178:181], v[96:111]
	s_waitcnt lgkmcnt(7)
	v_mfma_f32_32x32x16_bf16 v[80:95], v[170:173], v[178:181], v[80:95]
	s_waitcnt lgkmcnt(6)
	v_mfma_f32_32x32x16_bf16 v[64:79], v[174:177], v[178:181], v[64:79]
	v_mfma_f32_32x32x16_bf16 v[48:63], v[162:165], v[200:203], v[48:63]
	v_mfma_f32_32x32x16_bf16 v[32:47], v[166:169], v[200:203], v[32:47]
	v_mfma_f32_32x32x16_bf16 v[16:31], v[170:173], v[200:203], v[16:31]
	v_mfma_f32_32x32x16_bf16 v[0:15], v[174:177], v[200:203], v[0:15]
	s_waitcnt lgkmcnt(4)
	v_mfma_f32_32x32x16_bf16 v[112:127], v[128:131], v[132:135], v[112:127]
	s_waitcnt lgkmcnt(3)
	v_mfma_f32_32x32x16_bf16 v[96:111], v[136:139], v[132:135], v[96:111]
	s_waitcnt lgkmcnt(1)
	v_mfma_f32_32x32x16_bf16 v[80:95], v[140:143], v[132:135], v[80:95]
	s_waitcnt lgkmcnt(0)
	v_mfma_f32_32x32x16_bf16 v[64:79], v[144:147], v[132:135], v[64:79]
	v_mfma_f32_32x32x16_bf16 v[48:63], v[128:131], v[148:151], v[48:63]
	v_mfma_f32_32x32x16_bf16 v[32:47], v[136:139], v[148:151], v[32:47]
	v_mfma_f32_32x32x16_bf16 v[16:31], v[140:143], v[148:151], v[16:31]
	v_mfma_f32_32x32x16_bf16 v[0:15], v[144:147], v[148:151], v[0:15]
	s_waitcnt vmcnt(0)
	s_waitcnt lgkmcnt(0)
	s_barrier
	ds_read_b128 v[162:165], v157 offset:32768
	ds_read_b128 v[178:181], v161 offset:24576
	ds_read_b128 v[166:169], v157 offset:34816
	ds_read_b128 v[200:203], v161 offset:26624
	ds_read_b128 v[170:173], v157 offset:36864
	ds_read_b128 v[174:177], v157 offset:38912
	ds_read_b128 v[128:131], v159 offset:32768
	ds_read_b128 v[132:135], v158 offset:24576
	ds_read_b128 v[136:139], v159 offset:34816
	ds_read_b128 v[148:151], v158 offset:26624
	ds_read_b128 v[140:143], v159 offset:36864
	ds_read_b128 v[144:147], v159 offset:38912
	s_waitcnt lgkmcnt(10)
	v_mfma_f32_32x32x16_bf16 v[112:127], v[162:165], v[178:181], v[112:127]
	s_waitcnt lgkmcnt(9)
	v_mfma_f32_32x32x16_bf16 v[96:111], v[166:169], v[178:181], v[96:111]
	s_waitcnt lgkmcnt(7)
	v_mfma_f32_32x32x16_bf16 v[80:95], v[170:173], v[178:181], v[80:95]
	s_waitcnt lgkmcnt(6)
	v_mfma_f32_32x32x16_bf16 v[64:79], v[174:177], v[178:181], v[64:79]
	v_mfma_f32_32x32x16_bf16 v[48:63], v[162:165], v[200:203], v[48:63]
	v_mfma_f32_32x32x16_bf16 v[32:47], v[166:169], v[200:203], v[32:47]
	v_mfma_f32_32x32x16_bf16 v[16:31], v[170:173], v[200:203], v[16:31]
	v_mfma_f32_32x32x16_bf16 v[0:15], v[174:177], v[200:203], v[0:15]
	s_mov_b32 s14, 0x1f04000
	s_mov_b32 s5, 0
	s_waitcnt lgkmcnt(0)
	s_barrier
	v_mfma_f32_32x32x16_bf16 v[112:127], v[128:131], v[132:135], v[112:127]
	v_mfma_f32_32x32x16_bf16 v[96:111], v[136:139], v[132:135], v[96:111]
	v_mfma_f32_32x32x16_bf16 v[80:95], v[140:143], v[132:135], v[80:95]
	v_mfma_f32_32x32x16_bf16 v[64:79], v[144:147], v[132:135], v[64:79]
	v_mfma_f32_32x32x16_bf16 v[48:63], v[128:131], v[148:151], v[48:63]
	v_ashrrev_i32_e32 v128, 1, v156
	v_and_b32_e32 v128, 0xffffffc0, v128
	v_add_u32_e32 v128, s40, v128
	v_and_or_b32 v134, v156, 31, v128
	v_cmp_lt_i32_e32 vcc, s57, v134
	v_mfma_f32_32x32x16_bf16 v[32:47], v[136:139], v[148:151], v[32:47]
	v_mfma_f32_32x32x16_bf16 v[16:31], v[140:143], v[148:151], v[16:31]
	v_mfma_f32_32x32x16_bf16 v[0:15], v[144:147], v[148:151], v[0:15]
	s_and_saveexec_b64 s[4:5], vcc
	s_xor_b64 s[4:5], exec, s[4:5]
	v_add_u32_e32 v190, 0xffffc000, v134
	v_mov_b64_e32 v[128:129], v[190:191]
	s_or_saveexec_b64 s[4:5], s[4:5]
	v_mov_b32_e32 v132, 0
	v_mov_b64_e32 v[130:131], 0
	s_xor_b64 exec, exec, s[4:5]
	v_add_u32_e32 v128, s21, v134
	v_ashrrev_i32_e32 v129, 12, v128
	v_add_u32_e32 v132, 1, v129
	v_ashrrev_i32_e32 v129, 31, v128
	v_mov_b64_e32 v[130:131], 0x400000
	s_or_b64 exec, exec, s[4:5]
	v_lshlrev_b32_e32 v131, 1, v156
	v_lshrrev_b32_e32 v133, 3, v156
	s_lshl_b32 s4, s23, 8
	v_and_b32_e32 v131, 0x80, v131
	v_and_b32_e32 v133, 4, v133
	v_or3_b32 v136, v133, v131, s4
	v_readlane_b32 s4, v255, 18
	v_readlane_b32 s5, v255, 19
	v_readlane_b32 s40, v252, 4
	v_add_u32_e32 v131, s2, v132
	v_mov_b64_e32 v[132:133], s[4:5]
	v_lshlrev_b32_e32 v190, 2, v130
	v_readlane_b32 s52, v252, 16
	v_readlane_b32 s53, v252, 17
	v_mad_i64_i32 v[132:133], s[4:5], v131, s88, v[132:133]
	s_nop 0
	v_lshl_add_u64 v[130:131], s[52:53], 0, v[190:191]
	v_lshlrev_b64 v[128:129], 12, v[128:129]
	v_ashrrev_i32_e32 v137, 31, v136
	v_lshl_add_u64 v[130:131], v[130:131], 0, v[128:129]
	v_lshlrev_b64 v[128:129], 2, v[136:137]
	v_lshl_add_u64 v[130:131], v[130:131], 0, v[128:129]
	v_lshl_add_u64 v[132:133], v[132:133], 0, v[128:129]
	global_load_dwordx4 v[136:139], v[130:131], off
	global_load_dwordx4 v[140:143], v[132:133], off
	v_readlane_b32 s41, v252, 5
	v_readlane_b32 s42, v252, 6
	v_readlane_b32 s43, v252, 7
	v_readlane_b32 s44, v252, 8
	v_readlane_b32 s45, v252, 9
	v_readlane_b32 s46, v252, 10
	v_readlane_b32 s47, v252, 11
	v_readlane_b32 s48, v252, 12
	v_readlane_b32 s49, v252, 13
	v_readlane_b32 s50, v252, 14
	v_readlane_b32 s51, v252, 15
	v_readlane_b32 s54, v252, 18
	v_readlane_b32 s55, v252, 19
	s_waitcnt vmcnt(0)
	v_pk_fma_f32 v[112:113], v[112:113], v[140:141], v[136:137]
	v_pk_fma_f32 v[114:115], v[114:115], v[142:143], v[138:139]
	global_store_dwordx4 v[130:131], v[112:115], off
	global_load_dwordx4 v[112:115], v[130:131], off offset:32
	s_nop 0
	global_load_dwordx4 v[136:139], v[132:133], off offset:32
	s_waitcnt vmcnt(0)
	v_pk_fma_f32 v[112:113], v[116:117], v[136:137], v[112:113]
	v_pk_fma_f32 v[114:115], v[118:119], v[138:139], v[114:115]
	global_store_dwordx4 v[130:131], v[112:115], off offset:32
	global_load_dwordx4 v[112:115], v[130:131], off offset:64
	s_nop 0
	global_load_dwordx4 v[116:119], v[132:133], off offset:64
	s_waitcnt vmcnt(0)
	v_pk_fma_f32 v[112:113], v[120:121], v[116:117], v[112:113]
	v_pk_fma_f32 v[114:115], v[122:123], v[118:119], v[114:115]
	global_store_dwordx4 v[130:131], v[112:115], off offset:64
	global_load_dwordx4 v[112:115], v[130:131], off offset:96
	s_nop 0
	global_load_dwordx4 v[116:119], v[132:133], off offset:96
	s_waitcnt vmcnt(0)
	v_pk_fma_f32 v[112:113], v[124:125], v[116:117], v[112:113]
	v_pk_fma_f32 v[114:115], v[126:127], v[118:119], v[114:115]
	global_store_dwordx4 v[130:131], v[112:115], off offset:96
	global_load_dwordx4 v[112:115], v[130:131], off offset:128
	s_nop 0
	global_load_dwordx4 v[116:119], v[132:133], off offset:128
	s_waitcnt vmcnt(0)
	v_pk_fma_f32 v[96:97], v[96:97], v[116:117], v[112:113]
	v_pk_fma_f32 v[98:99], v[98:99], v[118:119], v[114:115]
	global_store_dwordx4 v[130:131], v[96:99], off offset:128
	global_load_dwordx4 v[96:99], v[130:131], off offset:160
	s_nop 0
	global_load_dwordx4 v[112:115], v[132:133], off offset:160
	s_waitcnt vmcnt(0)
	v_pk_fma_f32 v[96:97], v[100:101], v[112:113], v[96:97]
	v_pk_fma_f32 v[98:99], v[102:103], v[114:115], v[98:99]
	global_store_dwordx4 v[130:131], v[96:99], off offset:160
	global_load_dwordx4 v[96:99], v[130:131], off offset:192
	s_nop 0
	global_load_dwordx4 v[100:103], v[132:133], off offset:192
	s_waitcnt vmcnt(0)
	v_pk_fma_f32 v[96:97], v[104:105], v[100:101], v[96:97]
	v_pk_fma_f32 v[98:99], v[106:107], v[102:103], v[98:99]
	global_store_dwordx4 v[130:131], v[96:99], off offset:192
	global_load_dwordx4 v[96:99], v[130:131], off offset:224
	s_nop 0
	global_load_dwordx4 v[100:103], v[132:133], off offset:224
	s_waitcnt vmcnt(0)
	v_pk_fma_f32 v[96:97], v[108:109], v[100:101], v[96:97]
	v_pk_fma_f32 v[98:99], v[110:111], v[102:103], v[98:99]
	global_store_dwordx4 v[130:131], v[96:99], off offset:224
	global_load_dwordx4 v[96:99], v[130:131], off offset:256
	s_nop 0
	global_load_dwordx4 v[100:103], v[132:133], off offset:256
	s_waitcnt vmcnt(0)
	v_pk_fma_f32 v[80:81], v[80:81], v[100:101], v[96:97]
	v_pk_fma_f32 v[82:83], v[82:83], v[102:103], v[98:99]
	global_store_dwordx4 v[130:131], v[80:83], off offset:256
	global_load_dwordx4 v[80:83], v[130:131], off offset:288
	s_nop 0
	global_load_dwordx4 v[96:99], v[132:133], off offset:288
	s_waitcnt vmcnt(0)
	v_pk_fma_f32 v[80:81], v[84:85], v[96:97], v[80:81]
	v_pk_fma_f32 v[82:83], v[86:87], v[98:99], v[82:83]
	global_store_dwordx4 v[130:131], v[80:83], off offset:288
	global_load_dwordx4 v[80:83], v[130:131], off offset:320
	s_nop 0
	global_load_dwordx4 v[84:87], v[132:133], off offset:320
	s_waitcnt vmcnt(0)
	v_pk_fma_f32 v[80:81], v[88:89], v[84:85], v[80:81]
	v_pk_fma_f32 v[82:83], v[90:91], v[86:87], v[82:83]
	global_store_dwordx4 v[130:131], v[80:83], off offset:320
	global_load_dwordx4 v[80:83], v[130:131], off offset:352
	s_nop 0
	global_load_dwordx4 v[84:87], v[132:133], off offset:352
	s_waitcnt vmcnt(0)
	v_pk_fma_f32 v[80:81], v[92:93], v[84:85], v[80:81]
	v_pk_fma_f32 v[82:83], v[94:95], v[86:87], v[82:83]
	global_store_dwordx4 v[130:131], v[80:83], off offset:352
	global_load_dwordx4 v[80:83], v[130:131], off offset:384
	s_nop 0
	global_load_dwordx4 v[84:87], v[132:133], off offset:384
	s_waitcnt vmcnt(0)
	v_pk_fma_f32 v[64:65], v[64:65], v[84:85], v[80:81]
	v_pk_fma_f32 v[66:67], v[66:67], v[86:87], v[82:83]
	global_store_dwordx4 v[130:131], v[64:67], off offset:384
	global_load_dwordx4 v[64:67], v[130:131], off offset:416
	s_nop 0
	global_load_dwordx4 v[80:83], v[132:133], off offset:416
	s_waitcnt vmcnt(0)
	v_pk_fma_f32 v[64:65], v[68:69], v[80:81], v[64:65]
	v_pk_fma_f32 v[66:67], v[70:71], v[82:83], v[66:67]
	global_store_dwordx4 v[130:131], v[64:67], off offset:416
	global_load_dwordx4 v[64:67], v[130:131], off offset:448
	s_nop 0
	global_load_dwordx4 v[68:71], v[132:133], off offset:448
	s_waitcnt vmcnt(0)
	v_pk_fma_f32 v[64:65], v[72:73], v[68:69], v[64:65]
	v_pk_fma_f32 v[66:67], v[74:75], v[70:71], v[66:67]
	global_store_dwordx4 v[130:131], v[64:67], off offset:448
	global_load_dwordx4 v[64:67], v[130:131], off offset:480
	s_nop 0
	global_load_dwordx4 v[68:71], v[132:133], off offset:480
	s_waitcnt vmcnt(0)
	v_pk_fma_f32 v[64:65], v[76:77], v[68:69], v[64:65]
	v_or_b32_e32 v68, 32, v134
	v_pk_fma_f32 v[66:67], v[78:79], v[70:71], v[66:67]
	v_cmp_lt_i32_e32 vcc, s57, v68
	global_store_dwordx4 v[130:131], v[64:67], off offset:480
	s_and_saveexec_b64 s[4:5], vcc
	s_xor_b64 s[4:5], exec, s[4:5]
	v_add_u32_e32 v190, 0xffffc020, v134
	v_mov_b64_e32 v[64:65], v[190:191]
	s_or_saveexec_b64 s[4:5], s[4:5]
	v_mov_b32_e32 v69, 0
	v_mov_b64_e32 v[66:67], 0
	s_xor_b64 exec, exec, s[4:5]
	s_cbranch_execz .LBB0_1118
	v_add_u32_e32 v64, s21, v68
	v_ashrrev_i32_e32 v65, 12, v64
	v_add_u32_e32 v69, 1, v65
	v_ashrrev_i32_e32 v65, 31, v64
	v_mov_b64_e32 v[66:67], 0x400000
	s_branch .LBB0_1118
